# back edge of seven GEMM K loops rotated in front of the loop-closing barrier (barrier becomes the loop head; exit path keeps its own copy); on v085
# baseline (speedup 1.0000x reference)
.LBB0_177:
	s_ashr_i32 s45, s44, 31
	v_cmp_lt_i64_e32 vcc, s[46:47], v[144:145]
	s_lshl_b64 s[46:47], s[44:45], 19
	s_add_u32 s46, s68, s46
	s_addc_u32 s47, s69, s47
	s_and_b64 s[48:49], vcc, exec
	s_cselect_b32 s11, s47, s51
	s_cselect_b32 s13, s46, s50
	s_ashr_i32 s43, s42, 31
	s_lshl_b64 s[48:49], s[42:43], 19
	s_add_u32 s48, s26, s48
	s_addc_u32 s49, s27, s49
	s_and_b64 s[54:55], vcc, exec
	s_cselect_b32 s17, s49, s53
	s_cselect_b32 s43, s48, s52
	s_add_u32 s50, s50, 0x40080
	s_addc_u32 s51, s51, 0
	s_add_u32 s45, s52, 0x100
	s_addc_u32 s91, s53, 0
	s_mov_b32 s92, -2
	s_waitcnt lgkmcnt(0)
	s_branch .LBB0_178
.Lrot_178:
	s_barrier
.LBB0_178:
	ds_read_b128 v[148:151], v159
	ds_read_b128 v[152:155], v159 offset:1024
	ds_read_b128 v[164:167], v159 offset:2048
	ds_read_b128 v[168:171], v159 offset:3072
	s_add_u32 s52, s50, 0xfffc0080
	s_addc_u32 s53, s51, -1
	s_cmp_eq_u32 s92, 12
	s_cselect_b32 s55, s11, s53
	s_cselect_b32 s54, s13, s52
	s_cselect_b32 s53, s17, s91
	s_cselect_b32 s52, s43, s45
	v_lshl_add_u64 v[156:157], s[50:51], 0, v[140:141]
	s_add_i32 m0, s58, 0xc000
	ds_read_b128 v[172:175], v160
	ds_read_b128 v[176:179], v160 offset:1024
	ds_read_b128 v[180:183], v160 offset:2048
	ds_read_b128 v[184:187], v160 offset:3072
	ds_read_b128 v[188:191], v160 offset:4096
	ds_read_b128 v[196:199], v160 offset:5120
	ds_read_b128 v[200:203], v160 offset:6144
	ds_read_b128 v[204:207], v160 offset:7168
	global_load_lds_dwordx4 v[156:157], off
	v_lshl_add_u64 v[156:157], s[50:51], 0, v[142:143]
	s_add_i32 m0, s58, 0xe000
	s_nop 0
	global_load_lds_dwordx4 v[156:157], off
	s_waitcnt lgkmcnt(8)
	s_barrier
	s_waitcnt lgkmcnt(0)
	s_waitcnt lgkmcnt(0)
	s_cmp_eq_u32 s92, -2
	s_cbranch_scc1 .Lz1_0_first
	v_mfma_f32_16x16x32_bf16 v[124:127], v[148:151], v[172:175], v[124:127]
	v_mfma_f32_16x16x32_bf16 v[120:123], v[164:167], v[172:175], v[120:123]
	v_mfma_f32_16x16x32_bf16 v[108:111], v[148:151], v[180:183], v[108:111]
	v_mfma_f32_16x16x32_bf16 v[104:107], v[164:167], v[180:183], v[104:107]
	v_mfma_f32_16x16x32_bf16 v[92:95], v[148:151], v[188:191], v[92:95]
	v_mfma_f32_16x16x32_bf16 v[88:91], v[164:167], v[188:191], v[88:91]
	v_mfma_f32_16x16x32_bf16 v[76:79], v[148:151], v[200:203], v[76:79]
	v_mfma_f32_16x16x32_bf16 v[72:75], v[164:167], v[200:203], v[72:75]
	v_mfma_f32_16x16x32_bf16 v[124:127], v[152:155], v[176:179], v[124:127]
	v_mfma_f32_16x16x32_bf16 v[120:123], v[168:171], v[176:179], v[120:123]
	v_mfma_f32_16x16x32_bf16 v[108:111], v[152:155], v[184:187], v[108:111]
	v_mfma_f32_16x16x32_bf16 v[104:107], v[168:171], v[184:187], v[104:107]
	v_mfma_f32_16x16x32_bf16 v[92:95], v[152:155], v[196:199], v[92:95]
	v_mfma_f32_16x16x32_bf16 v[88:91], v[168:171], v[196:199], v[88:91]
	v_mfma_f32_16x16x32_bf16 v[76:79], v[152:155], v[204:207], v[76:79]
	v_mfma_f32_16x16x32_bf16 v[72:75], v[168:171], v[204:207], v[72:75]

.Lz1_3_join:
	s_add_i32 s93, 0, 0x18000
	v_add_u32_e32 v136, s93, v158
	s_barrier
	ds_read_b128 v[148:151], v136
	ds_read_b128 v[152:155], v136 offset:1024
	ds_read_b128 v[164:167], v136 offset:2048
	ds_read_b128 v[168:171], v136 offset:3072
	s_add_u32 s54, s54, 0x40000
	s_addc_u32 s55, s55, 0
	s_mov_b32 m0, s60
	v_lshl_add_u64 v[208:209], s[54:55], 0, v[128:129]
	ds_read_b128 v[172:175], v160 offset:32768
	ds_read_b128 v[176:179], v160 offset:33792
	ds_read_b128 v[180:183], v160 offset:34816
	ds_read_b128 v[184:187], v160 offset:35840
	ds_read_b128 v[188:191], v160 offset:36864
	ds_read_b128 v[196:199], v160 offset:37888
	ds_read_b128 v[200:203], v160 offset:38912
	ds_read_b128 v[204:207], v160 offset:39936
	global_load_lds_dwordx4 v[208:209], off
	v_lshl_add_u64 v[208:209], s[54:55], 0, v[132:133]
	s_mov_b32 m0, s61
	s_nop 0
	global_load_lds_dwordx4 v[208:209], off
	s_waitcnt lgkmcnt(8)
	s_barrier
	s_waitcnt lgkmcnt(0)
	s_waitcnt lgkmcnt(0)
	v_mfma_f32_16x16x32_bf16 v[124:127], v[148:151], v[172:175], v[124:127]
	v_mfma_f32_16x16x32_bf16 v[120:123], v[164:167], v[172:175], v[120:123]
	v_mfma_f32_16x16x32_bf16 v[108:111], v[148:151], v[180:183], v[108:111]
	v_mfma_f32_16x16x32_bf16 v[104:107], v[164:167], v[180:183], v[104:107]
	v_mfma_f32_16x16x32_bf16 v[92:95], v[148:151], v[188:191], v[92:95]
	v_mfma_f32_16x16x32_bf16 v[88:91], v[164:167], v[188:191], v[88:91]
	v_mfma_f32_16x16x32_bf16 v[76:79], v[148:151], v[200:203], v[76:79]
	v_mfma_f32_16x16x32_bf16 v[72:75], v[164:167], v[200:203], v[72:75]
	v_mfma_f32_16x16x32_bf16 v[124:127], v[152:155], v[176:179], v[124:127]
	v_mfma_f32_16x16x32_bf16 v[120:123], v[168:171], v[176:179], v[120:123]
	v_mfma_f32_16x16x32_bf16 v[108:111], v[152:155], v[184:187], v[108:111]
	v_mfma_f32_16x16x32_bf16 v[104:107], v[168:171], v[184:187], v[104:107]
	v_mfma_f32_16x16x32_bf16 v[92:95], v[152:155], v[196:199], v[92:95]
	v_mfma_f32_16x16x32_bf16 v[88:91], v[168:171], v[196:199], v[88:91]
	v_mfma_f32_16x16x32_bf16 v[76:79], v[152:155], v[204:207], v[76:79]
	v_mfma_f32_16x16x32_bf16 v[72:75], v[168:171], v[204:207], v[72:75]
	s_barrier
	s_add_i32 s54, 0, 0x1c000
	s_add_i32 s55, s93, s57
	v_add_u32_e32 v136, s54, v158
	v_lshl_add_u64 v[156:157], v[156:157], 0, s[0:1]
	s_mov_b32 m0, s55
	ds_read_b128 v[208:211], v136
	ds_read_b128 v[212:215], v136 offset:1024
	ds_read_b128 v[216:219], v136 offset:2048
	ds_read_b128 v[220:223], v136 offset:3072
	global_load_lds_dwordx4 v[156:157], off
	v_lshl_add_u64 v[156:157], v[224:225], 0, s[0:1]
	s_add_i32 m0, s55, 0x2000
	s_nop 0
	global_load_lds_dwordx4 v[156:157], off
	s_barrier
	s_waitcnt lgkmcnt(0)
	s_waitcnt lgkmcnt(0)
	v_mfma_f32_16x16x32_bf16 v[116:119], v[208:211], v[172:175], v[116:119]
	v_mfma_f32_16x16x32_bf16 v[112:115], v[216:219], v[172:175], v[112:115]
	v_mfma_f32_16x16x32_bf16 v[100:103], v[208:211], v[180:183], v[100:103]
	v_mfma_f32_16x16x32_bf16 v[96:99], v[216:219], v[180:183], v[96:99]
	v_mfma_f32_16x16x32_bf16 v[84:87], v[208:211], v[188:191], v[84:87]
	v_mfma_f32_16x16x32_bf16 v[80:83], v[216:219], v[188:191], v[80:83]
	v_mfma_f32_16x16x32_bf16 v[68:71], v[208:211], v[200:203], v[68:71]
	v_mfma_f32_16x16x32_bf16 v[64:67], v[216:219], v[200:203], v[64:67]
	v_mfma_f32_16x16x32_bf16 v[116:119], v[212:215], v[176:179], v[116:119]
	v_mfma_f32_16x16x32_bf16 v[112:115], v[220:223], v[176:179], v[112:115]
	v_mfma_f32_16x16x32_bf16 v[100:103], v[212:215], v[184:187], v[100:103]
	v_mfma_f32_16x16x32_bf16 v[96:99], v[220:223], v[184:187], v[96:99]
	v_mfma_f32_16x16x32_bf16 v[84:87], v[212:215], v[196:199], v[84:87]
	v_mfma_f32_16x16x32_bf16 v[80:83], v[220:223], v[196:199], v[80:83]
	v_mfma_f32_16x16x32_bf16 v[68:71], v[212:215], v[204:207], v[68:71]
	v_mfma_f32_16x16x32_bf16 v[64:67], v[220:223], v[204:207], v[64:67]
	s_mov_b32 m0, s65
	v_lshl_add_u64 v[156:157], v[226:227], 0, s[0:1]
	s_waitcnt vmcnt(10)
	s_barrier
	ds_read_b128 v[172:175], v160 offset:49152
	ds_read_b128 v[176:179], v160 offset:50176
	ds_read_b128 v[180:183], v160 offset:51200
	ds_read_b128 v[184:187], v160 offset:52224
	ds_read_b128 v[188:191], v160 offset:53248
	ds_read_b128 v[196:199], v160 offset:54272
	ds_read_b128 v[200:203], v160 offset:55296
	ds_read_b128 v[204:207], v160 offset:56320
	global_load_lds_dwordx4 v[156:157], off
	v_lshl_add_u64 v[156:157], v[228:229], 0, s[0:1]
	s_mov_b32 m0, s66
	s_nop 0
	global_load_lds_dwordx4 v[156:157], off
	s_barrier
	s_waitcnt lgkmcnt(0)
	s_waitcnt lgkmcnt(0)
	v_mfma_f32_16x16x32_bf16 v[60:63], v[148:151], v[172:175], v[60:63]
	v_mfma_f32_16x16x32_bf16 v[56:59], v[164:167], v[172:175], v[56:59]
	v_mfma_f32_16x16x32_bf16 v[44:47], v[148:151], v[180:183], v[44:47]
	v_mfma_f32_16x16x32_bf16 v[40:43], v[164:167], v[180:183], v[40:43]
	v_mfma_f32_16x16x32_bf16 v[28:31], v[148:151], v[188:191], v[28:31]
	v_mfma_f32_16x16x32_bf16 v[24:27], v[164:167], v[188:191], v[24:27]
	v_mfma_f32_16x16x32_bf16 v[12:15], v[148:151], v[200:203], v[12:15]
	v_mfma_f32_16x16x32_bf16 v[8:11], v[164:167], v[200:203], v[8:11]
	v_mfma_f32_16x16x32_bf16 v[60:63], v[152:155], v[176:179], v[60:63]
	v_mfma_f32_16x16x32_bf16 v[56:59], v[168:171], v[176:179], v[56:59]
	v_mfma_f32_16x16x32_bf16 v[44:47], v[152:155], v[184:187], v[44:47]
	v_mfma_f32_16x16x32_bf16 v[40:43], v[168:171], v[184:187], v[40:43]
	v_mfma_f32_16x16x32_bf16 v[28:31], v[152:155], v[196:199], v[28:31]
	v_mfma_f32_16x16x32_bf16 v[24:27], v[168:171], v[196:199], v[24:27]
	v_mfma_f32_16x16x32_bf16 v[12:15], v[152:155], v[204:207], v[12:15]
	v_mfma_f32_16x16x32_bf16 v[8:11], v[168:171], v[204:207], v[8:11]
	s_barrier
	s_add_u32 s52, s52, 0x10080
	s_addc_u32 s53, s53, 0
	s_add_i32 s54, s54, s57
	v_lshl_add_u64 v[148:149], s[52:53], 0, v[130:131]
	s_mov_b32 m0, s54
	s_nop 0
	global_load_lds_dwordx4 v[148:149], off
	v_lshl_add_u64 v[148:149], s[52:53], 0, v[134:135]
	s_add_i32 m0, s54, 0x2000
	s_nop 0
	global_load_lds_dwordx4 v[148:149], off
	s_waitcnt vmcnt(6)
	s_barrier
	v_mfma_f32_16x16x32_bf16 v[52:55], v[208:211], v[172:175], v[52:55]
	v_mfma_f32_16x16x32_bf16 v[48:51], v[216:219], v[172:175], v[48:51]
	v_mfma_f32_16x16x32_bf16 v[36:39], v[208:211], v[180:183], v[36:39]
	v_mfma_f32_16x16x32_bf16 v[32:35], v[216:219], v[180:183], v[32:35]
	v_mfma_f32_16x16x32_bf16 v[20:23], v[208:211], v[188:191], v[20:23]
	v_mfma_f32_16x16x32_bf16 v[16:19], v[216:219], v[188:191], v[16:19]
	v_mfma_f32_16x16x32_bf16 v[4:7], v[208:211], v[200:203], v[4:7]
	v_mfma_f32_16x16x32_bf16 v[0:3], v[216:219], v[200:203], v[0:3]
	v_mfma_f32_16x16x32_bf16 v[52:55], v[212:215], v[176:179], v[52:55]
	v_mfma_f32_16x16x32_bf16 v[48:51], v[220:223], v[176:179], v[48:51]
	v_mfma_f32_16x16x32_bf16 v[36:39], v[212:215], v[184:187], v[36:39]
	v_mfma_f32_16x16x32_bf16 v[32:35], v[220:223], v[184:187], v[32:35]
	v_mfma_f32_16x16x32_bf16 v[20:23], v[212:215], v[196:199], v[20:23]
	v_mfma_f32_16x16x32_bf16 v[16:19], v[220:223], v[196:199], v[16:19]
	v_mfma_f32_16x16x32_bf16 v[4:7], v[212:215], v[204:207], v[4:7]
	v_mfma_f32_16x16x32_bf16 v[0:3], v[220:223], v[204:207], v[0:3]
	s_add_i32 s92, s92, 2
	s_add_u32 s50, s50, 0x100
	s_addc_u32 s51, s51, 0
	s_add_u32 s45, s45, 0x100
	s_addc_u32 s91, s91, 0
	s_cmp_gt_u32 s92, 13
	s_cbranch_scc0 .Lrot_178
	s_barrier
	s_branch .Lz1_skip

.LBB0_341:
	s_ashr_i32 s9, s8, 31
	v_cmp_lt_i64_e64 s[48:49], s[10:11], 64
	s_lshl_b64 s[10:11], s[8:9], 19
	s_add_u32 s10, s82, s10
	s_addc_u32 s11, s83, s11
	s_and_b64 s[12:13], s[48:49], exec
	s_cselect_b32 s9, s11, s45
	s_cselect_b32 s63, s10, s44
	s_ashr_i32 s7, s6, 31
	s_lshl_b64 s[12:13], s[6:7], 19
	s_add_u32 s12, s80, s12
	s_addc_u32 s13, s81, s13
	s_and_b64 s[48:49], s[48:49], exec
	s_cselect_b32 s7, s13, s47
	s_cselect_b32 s64, s12, s46
	s_add_u32 s44, s44, 0x40080
	s_addc_u32 s45, s45, 0
	s_add_u32 s65, s46, 0x100
	v_mov_b32_e32 v0, 0
	s_addc_u32 s66, s47, 0
	s_mov_b32 s67, -2
	v_mov_b64_e32 v[0:1], 0
	v_mov_b64_e32 v[2:3], 0
	v_mov_b64_e32 v[4:5], 0
	v_mov_b64_e32 v[6:7], 0
	v_mov_b64_e32 v[8:9], 0
	v_mov_b64_e32 v[10:11], 0
	v_mov_b64_e32 v[12:13], 0
	v_mov_b64_e32 v[14:15], 0
	v_mov_b64_e32 v[16:17], 0
	v_mov_b64_e32 v[18:19], 0
	v_mov_b64_e32 v[20:21], 0
	v_mov_b64_e32 v[22:23], 0
	v_mov_b64_e32 v[24:25], 0
	v_mov_b64_e32 v[26:27], 0
	v_mov_b64_e32 v[28:29], 0
	v_mov_b64_e32 v[30:31], 0
	v_mov_b64_e32 v[32:33], 0
	v_mov_b64_e32 v[34:35], 0
	v_mov_b64_e32 v[36:37], 0
	v_mov_b64_e32 v[38:39], 0
	v_mov_b64_e32 v[40:41], 0
	v_mov_b64_e32 v[42:43], 0
	v_mov_b64_e32 v[44:45], 0
	v_mov_b64_e32 v[46:47], 0
	v_mov_b64_e32 v[48:49], 0
	v_mov_b64_e32 v[50:51], 0
	v_mov_b64_e32 v[52:53], 0
	v_mov_b64_e32 v[54:55], 0
	v_mov_b64_e32 v[56:57], 0
	v_mov_b64_e32 v[58:59], 0
	v_mov_b64_e32 v[60:61], 0
	v_mov_b64_e32 v[62:63], 0
	v_mov_b64_e32 v[64:65], 0
	v_mov_b64_e32 v[66:67], 0
	v_mov_b64_e32 v[68:69], 0
	v_mov_b64_e32 v[70:71], 0
	v_mov_b64_e32 v[72:73], 0
	v_mov_b64_e32 v[74:75], 0
	v_mov_b64_e32 v[76:77], 0
	v_mov_b64_e32 v[78:79], 0
	v_mov_b64_e32 v[80:81], 0
	v_mov_b64_e32 v[82:83], 0
	v_mov_b64_e32 v[84:85], 0
	v_mov_b64_e32 v[86:87], 0
	v_mov_b64_e32 v[88:89], 0
	v_mov_b64_e32 v[90:91], 0
	v_mov_b64_e32 v[92:93], 0
	v_mov_b64_e32 v[94:95], 0
	v_mov_b64_e32 v[96:97], 0
	v_mov_b64_e32 v[98:99], 0
	v_mov_b64_e32 v[100:101], 0
	v_mov_b64_e32 v[102:103], 0
	v_mov_b64_e32 v[104:105], 0
	v_mov_b64_e32 v[106:107], 0
	v_mov_b64_e32 v[108:109], 0
	v_mov_b64_e32 v[110:111], 0
	v_mov_b64_e32 v[112:113], 0
	v_mov_b64_e32 v[114:115], 0
	v_mov_b64_e32 v[116:117], 0
	v_mov_b64_e32 v[118:119], 0
	v_mov_b64_e32 v[120:121], 0
	v_mov_b64_e32 v[122:123], 0
	v_mov_b64_e32 v[124:125], 0
	v_mov_b64_e32 v[126:127], 0
	s_branch .LBB0_342

.LBB0_342:
	ds_read_b128 v[146:149], v143
	ds_read_b128 v[150:153], v143 offset:1024
	ds_read_b128 v[154:157], v143 offset:2048
	ds_read_b128 v[158:161], v143 offset:3072
	s_add_u32 s46, s44, 0xfffc0080
	s_addc_u32 s47, s45, -1
	s_cmp_eq_u32 s67, 12
	s_cselect_b32 s49, s9, s47
	s_cselect_b32 s48, s63, s46
	s_cselect_b32 s47, s7, s66
	s_cselect_b32 s46, s64, s65
	v_lshl_add_u64 v[190:191], s[44:45], 0, v[136:137]
	s_add_i32 m0, s43, 0xc000
	ds_read_b128 v[162:165], v144
	ds_read_b128 v[166:169], v144 offset:1024
	ds_read_b128 v[170:173], v144 offset:2048
	ds_read_b128 v[174:177], v144 offset:3072
	ds_read_b128 v[178:181], v144 offset:4096
	ds_read_b128 v[182:185], v144 offset:5120
	ds_read_b128 v[186:189], v144 offset:6144
	ds_read_b128 v[196:199], v144 offset:7168
	global_load_lds_dwordx4 v[190:191], off
	v_lshl_add_u64 v[190:191], s[44:45], 0, v[138:139]
	s_add_i32 m0, s43, 0xe000
	s_nop 0
	global_load_lds_dwordx4 v[190:191], off
	s_waitcnt lgkmcnt(8)
	s_barrier
	s_waitcnt lgkmcnt(0)
	s_waitcnt lgkmcnt(0)
	v_mfma_f32_16x16x32_bf16 v[124:127], v[146:149], v[162:165], v[124:127]
	v_mfma_f32_16x16x32_bf16 v[120:123], v[154:157], v[162:165], v[120:123]
	v_mfma_f32_16x16x32_bf16 v[108:111], v[146:149], v[170:173], v[108:111]
	v_mfma_f32_16x16x32_bf16 v[104:107], v[154:157], v[170:173], v[104:107]
	v_mfma_f32_16x16x32_bf16 v[92:95], v[146:149], v[178:181], v[92:95]
	v_mfma_f32_16x16x32_bf16 v[88:91], v[154:157], v[178:181], v[88:91]
	v_mfma_f32_16x16x32_bf16 v[76:79], v[146:149], v[186:189], v[76:79]
	v_mfma_f32_16x16x32_bf16 v[72:75], v[154:157], v[186:189], v[72:75]
	v_mfma_f32_16x16x32_bf16 v[124:127], v[150:153], v[166:169], v[124:127]
	v_mfma_f32_16x16x32_bf16 v[120:123], v[158:161], v[166:169], v[120:123]
	v_mfma_f32_16x16x32_bf16 v[108:111], v[150:153], v[174:177], v[108:111]
	v_mfma_f32_16x16x32_bf16 v[104:107], v[158:161], v[174:177], v[104:107]
	v_mfma_f32_16x16x32_bf16 v[92:95], v[150:153], v[182:185], v[92:95]
	v_mfma_f32_16x16x32_bf16 v[88:91], v[158:161], v[182:185], v[88:91]
	v_mfma_f32_16x16x32_bf16 v[76:79], v[150:153], v[196:199], v[76:79]
	v_mfma_f32_16x16x32_bf16 v[72:75], v[158:161], v[196:199], v[72:75]
	s_barrier
	s_add_i32 s84, s60, s50
	v_lshl_add_u64 v[190:191], s[46:47], 0, v[132:133]
	s_mov_b32 m0, s84
	ds_read_b128 v[200:203], v145
	ds_read_b128 v[204:207], v145 offset:1024
	ds_read_b128 v[208:211], v145 offset:2048
	ds_read_b128 v[212:215], v145 offset:3072
	global_load_lds_dwordx4 v[190:191], off
	v_lshl_add_u64 v[216:217], s[46:47], 0, v[128:129]
	s_add_i32 m0, s84, 0x2000
	s_nop 0
	global_load_lds_dwordx4 v[216:217], off
	s_barrier
	s_waitcnt lgkmcnt(0)
	s_waitcnt lgkmcnt(0)
	v_mfma_f32_16x16x32_bf16 v[116:119], v[200:203], v[162:165], v[116:119]
	v_mfma_f32_16x16x32_bf16 v[112:115], v[208:211], v[162:165], v[112:115]
	v_mfma_f32_16x16x32_bf16 v[100:103], v[200:203], v[170:173], v[100:103]
	v_mfma_f32_16x16x32_bf16 v[96:99], v[208:211], v[170:173], v[96:99]
	v_mfma_f32_16x16x32_bf16 v[84:87], v[200:203], v[178:181], v[84:87]
	v_mfma_f32_16x16x32_bf16 v[80:83], v[208:211], v[178:181], v[80:83]
	v_mfma_f32_16x16x32_bf16 v[68:71], v[200:203], v[186:189], v[68:71]
	v_mfma_f32_16x16x32_bf16 v[64:67], v[208:211], v[186:189], v[64:67]
	v_mfma_f32_16x16x32_bf16 v[116:119], v[204:207], v[166:169], v[116:119]
	v_mfma_f32_16x16x32_bf16 v[112:115], v[212:215], v[166:169], v[112:115]
	v_mfma_f32_16x16x32_bf16 v[100:103], v[204:207], v[174:177], v[100:103]
	v_mfma_f32_16x16x32_bf16 v[96:99], v[212:215], v[174:177], v[96:99]
	v_mfma_f32_16x16x32_bf16 v[84:87], v[204:207], v[182:185], v[84:87]
	v_mfma_f32_16x16x32_bf16 v[80:83], v[212:215], v[182:185], v[80:83]
	v_mfma_f32_16x16x32_bf16 v[68:71], v[204:207], v[196:199], v[68:71]
	v_mfma_f32_16x16x32_bf16 v[64:67], v[212:215], v[196:199], v[64:67]
	s_mov_b32 m0, s43
	v_lshl_add_u64 v[218:219], s[48:49], 0, v[134:135]
	s_barrier
	ds_read_b128 v[162:165], v144 offset:16384
	ds_read_b128 v[166:169], v144 offset:17408
	ds_read_b128 v[170:173], v144 offset:18432
	ds_read_b128 v[174:177], v144 offset:19456
	ds_read_b128 v[178:181], v144 offset:20480
	ds_read_b128 v[182:185], v144 offset:21504
	ds_read_b128 v[186:189], v144 offset:22528
	ds_read_b128 v[196:199], v144 offset:23552
	global_load_lds_dwordx4 v[218:219], off
	v_lshl_add_u64 v[220:221], s[48:49], 0, v[130:131]
	s_mov_b32 m0, s52
	s_nop 0
	global_load_lds_dwordx4 v[220:221], off
	s_barrier
	s_waitcnt lgkmcnt(0)
	s_waitcnt lgkmcnt(0)
	v_mfma_f32_16x16x32_bf16 v[60:63], v[146:149], v[162:165], v[60:63]
	v_mfma_f32_16x16x32_bf16 v[56:59], v[154:157], v[162:165], v[56:59]
	v_mfma_f32_16x16x32_bf16 v[44:47], v[146:149], v[170:173], v[44:47]
	v_mfma_f32_16x16x32_bf16 v[40:43], v[154:157], v[170:173], v[40:43]
	v_mfma_f32_16x16x32_bf16 v[28:31], v[146:149], v[178:181], v[28:31]
	v_mfma_f32_16x16x32_bf16 v[24:27], v[154:157], v[178:181], v[24:27]
	v_mfma_f32_16x16x32_bf16 v[12:15], v[146:149], v[186:189], v[12:15]
	v_mfma_f32_16x16x32_bf16 v[8:11], v[154:157], v[186:189], v[8:11]
	v_mfma_f32_16x16x32_bf16 v[60:63], v[150:153], v[166:169], v[60:63]
	v_mfma_f32_16x16x32_bf16 v[56:59], v[158:161], v[166:169], v[56:59]
	v_mfma_f32_16x16x32_bf16 v[44:47], v[150:153], v[174:177], v[44:47]
	v_mfma_f32_16x16x32_bf16 v[40:43], v[158:161], v[174:177], v[40:43]
	v_mfma_f32_16x16x32_bf16 v[28:31], v[150:153], v[182:185], v[28:31]
	v_mfma_f32_16x16x32_bf16 v[24:27], v[158:161], v[182:185], v[24:27]
	v_mfma_f32_16x16x32_bf16 v[12:15], v[150:153], v[196:199], v[12:15]
	v_mfma_f32_16x16x32_bf16 v[8:11], v[158:161], v[196:199], v[8:11]
	s_barrier
	s_add_u32 s84, s46, 0x10000
	s_addc_u32 s85, s47, 0
	s_add_i32 s89, s61, s50
	v_lshl_add_u64 v[146:147], s[84:85], 0, v[132:133]
	s_mov_b32 m0, s89
	s_nop 0
	global_load_lds_dwordx4 v[146:147], off
	v_lshl_add_u64 v[146:147], s[84:85], 0, v[128:129]
	s_add_i32 m0, s89, 0x2000
	s_nop 0
	global_load_lds_dwordx4 v[146:147], off
	s_waitcnt vmcnt(6)
	s_barrier
	v_mfma_f32_16x16x32_bf16 v[52:55], v[200:203], v[162:165], v[52:55]
	v_mfma_f32_16x16x32_bf16 v[48:51], v[208:211], v[162:165], v[48:51]
	v_mfma_f32_16x16x32_bf16 v[36:39], v[200:203], v[170:173], v[36:39]
	v_mfma_f32_16x16x32_bf16 v[32:35], v[208:211], v[170:173], v[32:35]
	v_mfma_f32_16x16x32_bf16 v[20:23], v[200:203], v[178:181], v[20:23]
	v_mfma_f32_16x16x32_bf16 v[16:19], v[208:211], v[178:181], v[16:19]
	v_mfma_f32_16x16x32_bf16 v[4:7], v[200:203], v[186:189], v[4:7]
	v_mfma_f32_16x16x32_bf16 v[0:3], v[208:211], v[186:189], v[0:3]
	v_mfma_f32_16x16x32_bf16 v[52:55], v[204:207], v[166:169], v[52:55]
	v_mfma_f32_16x16x32_bf16 v[48:51], v[212:215], v[166:169], v[48:51]
	v_mfma_f32_16x16x32_bf16 v[36:39], v[204:207], v[174:177], v[36:39]
	v_mfma_f32_16x16x32_bf16 v[32:35], v[212:215], v[174:177], v[32:35]
	v_mfma_f32_16x16x32_bf16 v[20:23], v[204:207], v[182:185], v[20:23]
	v_mfma_f32_16x16x32_bf16 v[16:19], v[212:215], v[182:185], v[16:19]
	v_mfma_f32_16x16x32_bf16 v[4:7], v[204:207], v[196:199], v[4:7]
	v_mfma_f32_16x16x32_bf16 v[0:3], v[212:215], v[196:199], v[0:3]
	s_add_i32 s84, 0, 0x18000
	v_add_u32_e32 v158, s84, v141
	s_barrier
	ds_read_b128 v[146:149], v158
	ds_read_b128 v[150:153], v158 offset:1024
	ds_read_b128 v[154:157], v158 offset:2048
	ds_read_b128 v[158:161], v158 offset:3072
	s_add_u32 s48, s48, 0x40000
	s_addc_u32 s49, s49, 0
	s_mov_b32 m0, s53
	v_lshl_add_u64 v[200:201], s[48:49], 0, v[134:135]
	ds_read_b128 v[162:165], v144 offset:32768
	ds_read_b128 v[166:169], v144 offset:33792
	ds_read_b128 v[170:173], v144 offset:34816
	ds_read_b128 v[174:177], v144 offset:35840
	ds_read_b128 v[178:181], v144 offset:36864
	ds_read_b128 v[182:185], v144 offset:37888
	ds_read_b128 v[186:189], v144 offset:38912
	ds_read_b128 v[196:199], v144 offset:39936
	global_load_lds_dwordx4 v[200:201], off
	v_lshl_add_u64 v[200:201], s[48:49], 0, v[130:131]
	s_mov_b32 m0, s54
	s_nop 0
	global_load_lds_dwordx4 v[200:201], off
	s_waitcnt lgkmcnt(8)
	s_barrier
	s_waitcnt lgkmcnt(0)
	s_waitcnt lgkmcnt(0)
	v_mfma_f32_16x16x32_bf16 v[124:127], v[146:149], v[162:165], v[124:127]
	v_mfma_f32_16x16x32_bf16 v[120:123], v[154:157], v[162:165], v[120:123]
	v_mfma_f32_16x16x32_bf16 v[108:111], v[146:149], v[170:173], v[108:111]
	v_mfma_f32_16x16x32_bf16 v[104:107], v[154:157], v[170:173], v[104:107]
	v_mfma_f32_16x16x32_bf16 v[92:95], v[146:149], v[178:181], v[92:95]
	v_mfma_f32_16x16x32_bf16 v[88:91], v[154:157], v[178:181], v[88:91]
	v_mfma_f32_16x16x32_bf16 v[76:79], v[146:149], v[186:189], v[76:79]
	v_mfma_f32_16x16x32_bf16 v[72:75], v[154:157], v[186:189], v[72:75]
	v_mfma_f32_16x16x32_bf16 v[124:127], v[150:153], v[166:169], v[124:127]
	v_mfma_f32_16x16x32_bf16 v[120:123], v[158:161], v[166:169], v[120:123]
	v_mfma_f32_16x16x32_bf16 v[108:111], v[150:153], v[174:177], v[108:111]
	v_mfma_f32_16x16x32_bf16 v[104:107], v[158:161], v[174:177], v[104:107]
	v_mfma_f32_16x16x32_bf16 v[92:95], v[150:153], v[182:185], v[92:95]
	v_mfma_f32_16x16x32_bf16 v[88:91], v[158:161], v[182:185], v[88:91]
	v_mfma_f32_16x16x32_bf16 v[76:79], v[150:153], v[196:199], v[76:79]
	v_mfma_f32_16x16x32_bf16 v[72:75], v[158:161], v[196:199], v[72:75]
	s_barrier
	s_add_i32 s48, 0, 0x1c000
	s_add_i32 s49, s84, s50
	v_add_u32_e32 v195, s48, v141
	v_lshl_add_u64 v[190:191], v[190:191], 0, s[0:1]
	s_mov_b32 m0, s49
	ds_read_b128 v[200:203], v195
	ds_read_b128 v[204:207], v195 offset:1024
	ds_read_b128 v[208:211], v195 offset:2048
	ds_read_b128 v[212:215], v195 offset:3072
	global_load_lds_dwordx4 v[190:191], off
	v_lshl_add_u64 v[190:191], v[216:217], 0, s[0:1]
	s_add_i32 m0, s49, 0x2000
	s_nop 0
	global_load_lds_dwordx4 v[190:191], off
	s_barrier
	s_waitcnt lgkmcnt(0)
	s_waitcnt lgkmcnt(0)
	v_mfma_f32_16x16x32_bf16 v[116:119], v[200:203], v[162:165], v[116:119]
	v_mfma_f32_16x16x32_bf16 v[112:115], v[208:211], v[162:165], v[112:115]
	v_mfma_f32_16x16x32_bf16 v[100:103], v[200:203], v[170:173], v[100:103]
	v_mfma_f32_16x16x32_bf16 v[96:99], v[208:211], v[170:173], v[96:99]
	v_mfma_f32_16x16x32_bf16 v[84:87], v[200:203], v[178:181], v[84:87]
	v_mfma_f32_16x16x32_bf16 v[80:83], v[208:211], v[178:181], v[80:83]
	v_mfma_f32_16x16x32_bf16 v[68:71], v[200:203], v[186:189], v[68:71]
	v_mfma_f32_16x16x32_bf16 v[64:67], v[208:211], v[186:189], v[64:67]
	v_mfma_f32_16x16x32_bf16 v[116:119], v[204:207], v[166:169], v[116:119]
	v_mfma_f32_16x16x32_bf16 v[112:115], v[212:215], v[166:169], v[112:115]
	v_mfma_f32_16x16x32_bf16 v[100:103], v[204:207], v[174:177], v[100:103]
	v_mfma_f32_16x16x32_bf16 v[96:99], v[212:215], v[174:177], v[96:99]
	v_mfma_f32_16x16x32_bf16 v[84:87], v[204:207], v[182:185], v[84:87]
	v_mfma_f32_16x16x32_bf16 v[80:83], v[212:215], v[182:185], v[80:83]
	v_mfma_f32_16x16x32_bf16 v[68:71], v[204:207], v[196:199], v[68:71]
	v_mfma_f32_16x16x32_bf16 v[64:67], v[212:215], v[196:199], v[64:67]
	s_mov_b32 m0, s57
	v_lshl_add_u64 v[190:191], v[218:219], 0, s[0:1]
	s_barrier
	ds_read_b128 v[162:165], v144 offset:49152
	ds_read_b128 v[166:169], v144 offset:50176
	ds_read_b128 v[170:173], v144 offset:51200
	ds_read_b128 v[174:177], v144 offset:52224
	ds_read_b128 v[178:181], v144 offset:53248
	ds_read_b128 v[182:185], v144 offset:54272
	ds_read_b128 v[186:189], v144 offset:55296
	ds_read_b128 v[196:199], v144 offset:56320
	global_load_lds_dwordx4 v[190:191], off
	v_lshl_add_u64 v[190:191], v[220:221], 0, s[0:1]
	s_mov_b32 m0, s58
	s_nop 0
	global_load_lds_dwordx4 v[190:191], off
	s_barrier
	s_waitcnt lgkmcnt(0)
	s_waitcnt lgkmcnt(0)
	v_mfma_f32_16x16x32_bf16 v[60:63], v[146:149], v[162:165], v[60:63]
	v_mfma_f32_16x16x32_bf16 v[56:59], v[154:157], v[162:165], v[56:59]
	v_mfma_f32_16x16x32_bf16 v[44:47], v[146:149], v[170:173], v[44:47]
	v_mfma_f32_16x16x32_bf16 v[40:43], v[154:157], v[170:173], v[40:43]
	v_mfma_f32_16x16x32_bf16 v[28:31], v[146:149], v[178:181], v[28:31]
	v_mfma_f32_16x16x32_bf16 v[24:27], v[154:157], v[178:181], v[24:27]
	v_mfma_f32_16x16x32_bf16 v[12:15], v[146:149], v[186:189], v[12:15]
	v_mfma_f32_16x16x32_bf16 v[8:11], v[154:157], v[186:189], v[8:11]
	v_mfma_f32_16x16x32_bf16 v[60:63], v[150:153], v[166:169], v[60:63]
	v_mfma_f32_16x16x32_bf16 v[56:59], v[158:161], v[166:169], v[56:59]
	v_mfma_f32_16x16x32_bf16 v[44:47], v[150:153], v[174:177], v[44:47]
	v_mfma_f32_16x16x32_bf16 v[40:43], v[158:161], v[174:177], v[40:43]
	v_mfma_f32_16x16x32_bf16 v[28:31], v[150:153], v[182:185], v[28:31]
	v_mfma_f32_16x16x32_bf16 v[24:27], v[158:161], v[182:185], v[24:27]
	v_mfma_f32_16x16x32_bf16 v[12:15], v[150:153], v[196:199], v[12:15]
	v_mfma_f32_16x16x32_bf16 v[8:11], v[158:161], v[196:199], v[8:11]
	s_barrier
	s_add_u32 s46, s46, 0x10080
	s_addc_u32 s47, s47, 0
	s_add_i32 s48, s48, s50
	v_lshl_add_u64 v[146:147], s[46:47], 0, v[132:133]
	s_mov_b32 m0, s48
	s_nop 0
	global_load_lds_dwordx4 v[146:147], off
	v_lshl_add_u64 v[146:147], s[46:47], 0, v[128:129]
	s_add_i32 m0, s48, 0x2000
	s_nop 0
	global_load_lds_dwordx4 v[146:147], off
	s_waitcnt vmcnt(6)
	s_barrier
	v_mfma_f32_16x16x32_bf16 v[52:55], v[200:203], v[162:165], v[52:55]
	v_mfma_f32_16x16x32_bf16 v[48:51], v[208:211], v[162:165], v[48:51]
	v_mfma_f32_16x16x32_bf16 v[36:39], v[200:203], v[170:173], v[36:39]
	v_mfma_f32_16x16x32_bf16 v[32:35], v[208:211], v[170:173], v[32:35]
	v_mfma_f32_16x16x32_bf16 v[20:23], v[200:203], v[178:181], v[20:23]
	v_mfma_f32_16x16x32_bf16 v[16:19], v[208:211], v[178:181], v[16:19]
	v_mfma_f32_16x16x32_bf16 v[4:7], v[200:203], v[186:189], v[4:7]
	v_mfma_f32_16x16x32_bf16 v[0:3], v[208:211], v[186:189], v[0:3]
	v_mfma_f32_16x16x32_bf16 v[52:55], v[204:207], v[166:169], v[52:55]
	v_mfma_f32_16x16x32_bf16 v[48:51], v[212:215], v[166:169], v[48:51]
	v_mfma_f32_16x16x32_bf16 v[36:39], v[204:207], v[174:177], v[36:39]
	v_mfma_f32_16x16x32_bf16 v[32:35], v[212:215], v[174:177], v[32:35]
	v_mfma_f32_16x16x32_bf16 v[20:23], v[204:207], v[182:185], v[20:23]
	v_mfma_f32_16x16x32_bf16 v[16:19], v[212:215], v[182:185], v[16:19]
	v_mfma_f32_16x16x32_bf16 v[4:7], v[204:207], v[196:199], v[4:7]
	v_mfma_f32_16x16x32_bf16 v[0:3], v[212:215], v[196:199], v[0:3]
	s_add_i32 s67, s67, 2
	s_add_u32 s44, s44, 0x100
	s_addc_u32 s45, s45, 0
	s_add_u32 s65, s65, 0x100
	s_addc_u32 s66, s66, 0
	s_cmp_gt_u32 s67, 13
	s_cbranch_scc0 .Lrot_342
	s_barrier
	v_cvt_pk_bf16_f32 v124, v124, v125
	v_cvt_pk_bf16_f32 v120, v120, v121
	v_cvt_pk_bf16_f32 v121, v122, v123
	v_cvt_pk_bf16_f32 v122, v116, v117
	v_cvt_pk_bf16_f32 v112, v112, v113
	v_cvt_pk_bf16_f32 v125, v126, v127
	v_cvt_pk_bf16_f32 v118, v118, v119
	v_cvt_pk_bf16_f32 v113, v114, v115
	v_cndmask_b32_e64 v114, v124, v122, s[2:3]
	v_mov_b32_e32 v123, 0
	v_cndmask_b32_e64 v115, v120, v112, s[2:3]
	v_mov_b32_e32 v126, 0
	v_lshl_add_u32 v148, s42, 8, v140
	v_mov_b32_dpp v123, v114 row_ror:8 row_mask:0xf bank_mask:0xf
	v_cndmask_b32_e64 v114, v125, v118, s[2:3]
	v_mov_b32_e32 v119, 0
	v_mov_b32_dpp v126, v115 row_ror:8 row_mask:0xf bank_mask:0xf
	v_mov_b32_e32 v127, 0
	v_mov_b32_dpp v119, v114 row_ror:8 row_mask:0xf bank_mask:0xf
	v_cndmask_b32_e64 v114, v121, v113, s[2:3]
	v_cndmask_b32_e64 v116, v126, v120, s[2:3]
	v_cndmask_b32_e64 v120, v112, v126, s[2:3]
	v_add_u32_e32 v112, -8, v148
	v_mov_b32_dpp v127, v114 row_ror:8 row_mask:0xf bank_mask:0xf
	v_cndmask_b32_e64 v112, v112, v148, s[2:3]
	v_lshl_or_b32 v146, s62, 8, v142
	v_cndmask_b32_e64 v117, v127, v121, s[2:3]
	v_cndmask_b32_e64 v121, v113, v127, s[2:3]
	v_ashrrev_i32_e32 v113, 31, v112
	v_ashrrev_i32_e32 v147, 31, v146
	v_lshlrev_b64 v[112:113], 11, v[112:113]
	v_cndmask_b32_e64 v115, v119, v125, s[2:3]
	v_cndmask_b32_e64 v114, v123, v124, s[2:3]
	v_cndmask_b32_e64 v119, v118, v119, s[2:3]
	v_cndmask_b32_e64 v118, v122, v123, s[2:3]
	v_lshl_add_u64 v[122:123], s[40:41], 0, v[112:113]
	v_lshlrev_b64 v[112:113], 1, v[146:147]
	v_lshl_add_u64 v[122:123], v[122:123], 0, v[112:113]
	global_store_dwordx4 v[122:123], v[114:117], off
	v_cvt_pk_bf16_f32 v108, v108, v109
	v_cvt_pk_bf16_f32 v100, v100, v101
	v_add_u32_e32 v116, 8, v148
	v_cndmask_b32_e64 v114, v148, v116, s[2:3]
	v_ashrrev_i32_e32 v115, 31, v114
	v_lshlrev_b64 v[114:115], 11, v[114:115]
	v_lshl_add_u64 v[114:115], s[40:41], 0, v[114:115]
	v_cvt_pk_bf16_f32 v109, v110, v111
	v_cvt_pk_bf16_f32 v104, v104, v105
	v_cvt_pk_bf16_f32 v105, v106, v107
	v_cvt_pk_bf16_f32 v101, v102, v103
	v_cvt_pk_bf16_f32 v102, v96, v97
	v_cndmask_b32_e64 v96, v108, v100, s[2:3]
	v_mov_b32_e32 v106, 0
	v_lshl_add_u64 v[114:115], v[114:115], 0, v[112:113]
	v_cvt_pk_bf16_f32 v103, v98, v99
	v_mov_b32_dpp v106, v96 row_ror:8 row_mask:0xf bank_mask:0xf
	v_cndmask_b32_e64 v96, v109, v101, s[2:3]
	v_mov_b32_e32 v107, 0
	v_cndmask_b32_e64 v97, v104, v102, s[2:3]
	v_mov_b32_e32 v110, 0
	global_store_dwordx4 v[114:115], v[118:121], off
	v_or_b32_e32 v114, 16, v148
	v_mov_b32_dpp v107, v96 row_ror:8 row_mask:0xf bank_mask:0xf
	v_cndmask_b32_e64 v96, v105, v103, s[2:3]
	v_mov_b32_dpp v110, v97 row_ror:8 row_mask:0xf bank_mask:0xf
	v_mov_b32_e32 v111, 0
	v_cndmask_b32_e64 v98, v110, v104, s[2:3]
	v_cndmask_b32_e64 v104, v116, v114, s[2:3]
	v_mov_b32_dpp v111, v96 row_ror:8 row_mask:0xf bank_mask:0xf
	v_cndmask_b32_e64 v99, v111, v105, s[2:3]
	v_ashrrev_i32_e32 v105, 31, v104
	v_lshlrev_b64 v[104:105], 11, v[104:105]
	v_lshl_add_u64 v[104:105], s[40:41], 0, v[104:105]
	v_cndmask_b32_e64 v97, v107, v109, s[2:3]
	v_cndmask_b32_e64 v96, v106, v108, s[2:3]
	v_lshl_add_u64 v[104:105], v[104:105], 0, v[112:113]
	global_store_dwordx4 v[104:105], v[96:99], off
	v_cvt_pk_bf16_f32 v92, v92, v93
	v_cvt_pk_bf16_f32 v84, v84, v85
	v_add_u32_e32 v98, 24, v148
	v_cndmask_b32_e64 v96, v114, v98, s[2:3]
	v_ashrrev_i32_e32 v97, 31, v96
	v_lshlrev_b64 v[96:97], 11, v[96:97]
	v_lshl_add_u64 v[96:97], s[40:41], 0, v[96:97]
	v_cvt_pk_bf16_f32 v93, v94, v95
	v_cvt_pk_bf16_f32 v88, v88, v89
	v_cvt_pk_bf16_f32 v89, v90, v91
	v_cvt_pk_bf16_f32 v85, v86, v87
	v_cvt_pk_bf16_f32 v86, v80, v81
	v_cndmask_b32_e64 v80, v92, v84, s[2:3]
	v_mov_b32_e32 v90, 0
	v_cndmask_b32_e64 v103, v103, v111, s[2:3]
	v_cndmask_b32_e64 v102, v102, v110, s[2:3]
	v_cndmask_b32_e64 v101, v101, v107, s[2:3]
	v_cndmask_b32_e64 v100, v100, v106, s[2:3]
	v_lshl_add_u64 v[96:97], v[96:97], 0, v[112:113]
	v_cvt_pk_bf16_f32 v87, v82, v83
	v_mov_b32_dpp v90, v80 row_ror:8 row_mask:0xf bank_mask:0xf
	v_cndmask_b32_e64 v80, v93, v85, s[2:3]
	v_mov_b32_e32 v91, 0
	v_cndmask_b32_e64 v81, v88, v86, s[2:3]
	v_mov_b32_e32 v94, 0
	global_store_dwordx4 v[96:97], v[100:103], off
	v_or_b32_e32 v96, 32, v148
	v_mov_b32_dpp v91, v80 row_ror:8 row_mask:0xf bank_mask:0xf
	v_cndmask_b32_e64 v80, v89, v87, s[2:3]
	v_mov_b32_dpp v94, v81 row_ror:8 row_mask:0xf bank_mask:0xf
	v_mov_b32_e32 v95, 0
	v_cndmask_b32_e64 v82, v94, v88, s[2:3]
	v_cndmask_b32_e64 v88, v98, v96, s[2:3]
	v_mov_b32_dpp v95, v80 row_ror:8 row_mask:0xf bank_mask:0xf
	v_cndmask_b32_e64 v83, v95, v89, s[2:3]
	v_ashrrev_i32_e32 v89, 31, v88
	v_lshlrev_b64 v[88:89], 11, v[88:89]
	v_lshl_add_u64 v[88:89], s[40:41], 0, v[88:89]
	v_cndmask_b32_e64 v81, v91, v93, s[2:3]
	v_cndmask_b32_e64 v80, v90, v92, s[2:3]
	v_lshl_add_u64 v[88:89], v[88:89], 0, v[112:113]
	global_store_dwordx4 v[88:89], v[80:83], off
	v_cvt_pk_bf16_f32 v76, v76, v77
	v_cvt_pk_bf16_f32 v68, v68, v69
	v_add_u32_e32 v82, 40, v148
	v_cndmask_b32_e64 v80, v96, v82, s[2:3]
	v_ashrrev_i32_e32 v81, 31, v80
	v_lshlrev_b64 v[80:81], 11, v[80:81]
	v_lshl_add_u64 v[80:81], s[40:41], 0, v[80:81]
	v_cvt_pk_bf16_f32 v77, v78, v79
	v_cvt_pk_bf16_f32 v72, v72, v73
	v_cvt_pk_bf16_f32 v73, v74, v75
	v_cvt_pk_bf16_f32 v69, v70, v71
	v_cvt_pk_bf16_f32 v70, v64, v65
	v_cndmask_b32_e64 v64, v76, v68, s[2:3]
	v_mov_b32_e32 v74, 0
	v_cndmask_b32_e64 v87, v87, v95, s[2:3]
	v_cndmask_b32_e64 v86, v86, v94, s[2:3]
	v_cndmask_b32_e64 v85, v85, v91, s[2:3]
	v_cndmask_b32_e64 v84, v84, v90, s[2:3]
	v_lshl_add_u64 v[80:81], v[80:81], 0, v[112:113]
	v_cvt_pk_bf16_f32 v71, v66, v67
	v_mov_b32_dpp v74, v64 row_ror:8 row_mask:0xf bank_mask:0xf
	v_cndmask_b32_e64 v64, v77, v69, s[2:3]
	v_mov_b32_e32 v75, 0
	v_cndmask_b32_e64 v65, v72, v70, s[2:3]
	v_mov_b32_e32 v78, 0
	global_store_dwordx4 v[80:81], v[84:87], off
	v_or_b32_e32 v80, 48, v148
	v_mov_b32_dpp v75, v64 row_ror:8 row_mask:0xf bank_mask:0xf
	v_cndmask_b32_e64 v64, v73, v71, s[2:3]
	v_mov_b32_dpp v78, v65 row_ror:8 row_mask:0xf bank_mask:0xf
	v_mov_b32_e32 v79, 0
	v_cndmask_b32_e64 v66, v78, v72, s[2:3]
	v_cndmask_b32_e64 v72, v82, v80, s[2:3]
	v_mov_b32_dpp v79, v64 row_ror:8 row_mask:0xf bank_mask:0xf
	v_cndmask_b32_e64 v67, v79, v73, s[2:3]
	v_ashrrev_i32_e32 v73, 31, v72
	v_lshlrev_b64 v[72:73], 11, v[72:73]
	v_lshl_add_u64 v[72:73], s[40:41], 0, v[72:73]
	v_cndmask_b32_e64 v65, v75, v77, s[2:3]
	v_cndmask_b32_e64 v64, v74, v76, s[2:3]
	v_lshl_add_u64 v[72:73], v[72:73], 0, v[112:113]
	global_store_dwordx4 v[72:73], v[64:67], off
	v_cvt_pk_bf16_f32 v60, v60, v61
	v_cvt_pk_bf16_f32 v56, v56, v57
	v_add_u32_e32 v64, 56, v148
	v_cndmask_b32_e64 v64, v80, v64, s[2:3]
	v_ashrrev_i32_e32 v65, 31, v64
	v_lshlrev_b64 v[64:65], 11, v[64:65]
	v_cvt_pk_bf16_f32 v52, v52, v53
	v_cvt_pk_bf16_f32 v53, v54, v55
	v_cvt_pk_bf16_f32 v54, v48, v49
	v_lshl_add_u64 v[64:65], s[40:41], 0, v[64:65]
	v_cvt_pk_bf16_f32 v61, v62, v63
	v_cvt_pk_bf16_f32 v57, v58, v59
	v_cndmask_b32_e64 v48, v60, v52, s[2:3]
	v_mov_b32_e32 v58, 0
	v_cndmask_b32_e64 v49, v56, v54, s[2:3]
	v_mov_b32_e32 v62, 0
	v_cndmask_b32_e64 v71, v71, v79, s[2:3]
	v_cndmask_b32_e64 v70, v70, v78, s[2:3]
	v_cndmask_b32_e64 v69, v69, v75, s[2:3]
	v_cndmask_b32_e64 v68, v68, v74, s[2:3]
	v_lshl_add_u64 v[64:65], v[64:65], 0, v[112:113]
	v_cvt_pk_bf16_f32 v55, v50, v51
	v_mov_b32_dpp v58, v48 row_ror:8 row_mask:0xf bank_mask:0xf
	v_cndmask_b32_e64 v48, v61, v53, s[2:3]
	v_mov_b32_e32 v59, 0
	v_mov_b32_dpp v62, v49 row_ror:8 row_mask:0xf bank_mask:0xf
	global_store_dwordx4 v[64:65], v[68:71], off
	v_add_u32_e32 v64, 0x80, v148
	v_mov_b32_dpp v59, v48 row_ror:8 row_mask:0xf bank_mask:0xf
	v_cndmask_b32_e64 v48, v57, v55, s[2:3]
	v_mov_b32_e32 v63, 0
	v_cndmask_b32_e64 v50, v62, v56, s[2:3]
	v_add_u32_e32 v56, 0x78, v148
	v_mov_b32_dpp v63, v48 row_ror:8 row_mask:0xf bank_mask:0xf
	v_cndmask_b32_e64 v56, v56, v64, s[2:3]
	v_cndmask_b32_e64 v51, v63, v57, s[2:3]
	v_ashrrev_i32_e32 v57, 31, v56
	v_lshlrev_b64 v[56:57], 11, v[56:57]
	v_lshl_add_u64 v[56:57], s[40:41], 0, v[56:57]
	v_cndmask_b32_e64 v49, v59, v61, s[2:3]
	v_cndmask_b32_e64 v48, v58, v60, s[2:3]
	v_lshl_add_u64 v[56:57], v[56:57], 0, v[112:113]
	global_store_dwordx4 v[56:57], v[48:51], off
	v_cvt_pk_bf16_f32 v44, v44, v45
	v_cvt_pk_bf16_f32 v36, v36, v37
	v_add_u32_e32 v50, 0x88, v148
	v_cndmask_b32_e64 v48, v64, v50, s[2:3]
	v_ashrrev_i32_e32 v49, 31, v48
	v_lshlrev_b64 v[48:49], 11, v[48:49]
	v_lshl_add_u64 v[48:49], s[40:41], 0, v[48:49]
	v_cvt_pk_bf16_f32 v45, v46, v47
	v_cvt_pk_bf16_f32 v40, v40, v41
	v_cvt_pk_bf16_f32 v41, v42, v43
	v_cvt_pk_bf16_f32 v37, v38, v39
	v_cvt_pk_bf16_f32 v38, v32, v33
	v_cndmask_b32_e64 v32, v44, v36, s[2:3]
	v_mov_b32_e32 v42, 0
	v_cndmask_b32_e64 v55, v55, v63, s[2:3]
	v_cndmask_b32_e64 v54, v54, v62, s[2:3]
	v_cndmask_b32_e64 v53, v53, v59, s[2:3]
	v_cndmask_b32_e64 v52, v52, v58, s[2:3]
	v_lshl_add_u64 v[48:49], v[48:49], 0, v[112:113]
	v_cvt_pk_bf16_f32 v39, v34, v35
	v_mov_b32_dpp v42, v32 row_ror:8 row_mask:0xf bank_mask:0xf
	v_cndmask_b32_e64 v32, v45, v37, s[2:3]
	v_mov_b32_e32 v43, 0
	v_cndmask_b32_e64 v33, v40, v38, s[2:3]
	v_mov_b32_e32 v46, 0
	global_store_dwordx4 v[48:49], v[52:55], off
	v_add_u32_e32 v48, 0x90, v148
	v_mov_b32_dpp v43, v32 row_ror:8 row_mask:0xf bank_mask:0xf
	v_cndmask_b32_e64 v32, v41, v39, s[2:3]
	v_mov_b32_dpp v46, v33 row_ror:8 row_mask:0xf bank_mask:0xf
	v_mov_b32_e32 v47, 0
	v_cndmask_b32_e64 v34, v46, v40, s[2:3]
	v_cndmask_b32_e64 v40, v50, v48, s[2:3]
	v_mov_b32_dpp v47, v32 row_ror:8 row_mask:0xf bank_mask:0xf
	v_cndmask_b32_e64 v35, v47, v41, s[2:3]
	v_ashrrev_i32_e32 v41, 31, v40
	v_lshlrev_b64 v[40:41], 11, v[40:41]
	v_lshl_add_u64 v[40:41], s[40:41], 0, v[40:41]
	v_cndmask_b32_e64 v33, v43, v45, s[2:3]
	v_cndmask_b32_e64 v32, v42, v44, s[2:3]
	v_lshl_add_u64 v[40:41], v[40:41], 0, v[112:113]
	global_store_dwordx4 v[40:41], v[32:35], off
	v_cvt_pk_bf16_f32 v28, v28, v29
	v_cvt_pk_bf16_f32 v20, v20, v21
	v_add_u32_e32 v34, 0x98, v148
	v_cndmask_b32_e64 v32, v48, v34, s[2:3]
	v_ashrrev_i32_e32 v33, 31, v32
	v_lshlrev_b64 v[32:33], 11, v[32:33]
	v_lshl_add_u64 v[32:33], s[40:41], 0, v[32:33]
	v_cvt_pk_bf16_f32 v29, v30, v31
	v_cvt_pk_bf16_f32 v24, v24, v25
	v_cvt_pk_bf16_f32 v25, v26, v27
	v_cvt_pk_bf16_f32 v21, v22, v23
	v_cvt_pk_bf16_f32 v22, v16, v17
	v_cndmask_b32_e64 v16, v28, v20, s[2:3]
	v_mov_b32_e32 v26, 0
	v_cndmask_b32_e64 v39, v39, v47, s[2:3]
	v_cndmask_b32_e64 v38, v38, v46, s[2:3]
	v_cndmask_b32_e64 v37, v37, v43, s[2:3]
	v_cndmask_b32_e64 v36, v36, v42, s[2:3]
	v_lshl_add_u64 v[32:33], v[32:33], 0, v[112:113]
	v_cvt_pk_bf16_f32 v23, v18, v19
	v_mov_b32_dpp v26, v16 row_ror:8 row_mask:0xf bank_mask:0xf
	v_cndmask_b32_e64 v16, v29, v21, s[2:3]
	v_mov_b32_e32 v27, 0
	v_cndmask_b32_e64 v17, v24, v22, s[2:3]
	v_mov_b32_e32 v30, 0
	global_store_dwordx4 v[32:33], v[36:39], off
	v_add_u32_e32 v32, 0xa0, v148
	v_mov_b32_dpp v27, v16 row_ror:8 row_mask:0xf bank_mask:0xf
	v_cndmask_b32_e64 v16, v25, v23, s[2:3]
	v_mov_b32_dpp v30, v17 row_ror:8 row_mask:0xf bank_mask:0xf
	v_mov_b32_e32 v31, 0
	v_cndmask_b32_e64 v18, v30, v24, s[2:3]
	v_cndmask_b32_e64 v24, v34, v32, s[2:3]
	v_mov_b32_dpp v31, v16 row_ror:8 row_mask:0xf bank_mask:0xf
	v_cndmask_b32_e64 v19, v31, v25, s[2:3]
	v_ashrrev_i32_e32 v25, 31, v24
	v_lshlrev_b64 v[24:25], 11, v[24:25]
	v_lshl_add_u64 v[24:25], s[40:41], 0, v[24:25]
	v_cndmask_b32_e64 v17, v27, v29, s[2:3]
	v_cndmask_b32_e64 v16, v26, v28, s[2:3]
	v_lshl_add_u64 v[24:25], v[24:25], 0, v[112:113]
	global_store_dwordx4 v[24:25], v[16:19], off
	v_cndmask_b32_e64 v23, v23, v31, s[2:3]
	v_cndmask_b32_e64 v22, v22, v30, s[2:3]
	v_add_u32_e32 v18, 0xa8, v148
	v_cndmask_b32_e64 v16, v32, v18, s[2:3]
	v_ashrrev_i32_e32 v17, 31, v16
	v_lshlrev_b64 v[16:17], 11, v[16:17]
	v_lshl_add_u64 v[16:17], s[40:41], 0, v[16:17]
	v_cndmask_b32_e64 v21, v21, v27, s[2:3]
	v_cndmask_b32_e64 v20, v20, v26, s[2:3]
	v_lshl_add_u64 v[16:17], v[16:17], 0, v[112:113]
	global_store_dwordx4 v[16:17], v[20:23], off
	v_add_u32_e32 v16, 0xb0, v148
	v_cvt_pk_bf16_f32 v12, v12, v13
	v_cvt_pk_bf16_f32 v8, v8, v9
	v_cvt_pk_bf16_f32 v9, v10, v11
	v_cvt_pk_bf16_f32 v10, v4, v5
	v_cvt_pk_bf16_f32 v13, v14, v15
	v_cvt_pk_bf16_f32 v6, v6, v7
	v_cvt_pk_bf16_f32 v7, v0, v1
	v_cndmask_b32_e64 v0, v12, v10, s[2:3]
	v_mov_b32_e32 v14, 0
	v_cndmask_b32_e64 v4, v18, v16, s[2:3]
	v_cvt_pk_bf16_f32 v11, v2, v3
	v_mov_b32_dpp v14, v0 row_ror:8 row_mask:0xf bank_mask:0xf
	v_cndmask_b32_e64 v0, v13, v6, s[2:3]
	v_mov_b32_e32 v15, 0
	v_ashrrev_i32_e32 v5, 31, v4
	v_cndmask_b32_e64 v1, v8, v7, s[2:3]
	v_mov_b32_dpp v15, v0 row_ror:8 row_mask:0xf bank_mask:0xf
	v_cndmask_b32_e64 v0, v9, v11, s[2:3]
	v_mov_b32_e32 v17, 0
	v_mov_b32_e32 v19, 0
	v_lshlrev_b64 v[4:5], 11, v[4:5]
	v_mov_b32_dpp v17, v1 row_ror:8 row_mask:0xf bank_mask:0xf
	v_mov_b32_dpp v19, v0 row_ror:8 row_mask:0xf bank_mask:0xf
	v_lshl_add_u64 v[4:5], s[40:41], 0, v[4:5]
	v_cndmask_b32_e64 v3, v19, v9, s[2:3]
	v_cndmask_b32_e64 v2, v17, v8, s[2:3]
	v_cndmask_b32_e64 v1, v15, v13, s[2:3]
	v_cndmask_b32_e64 v0, v14, v12, s[2:3]
	v_lshl_add_u64 v[4:5], v[4:5], 0, v[112:113]
	global_store_dwordx4 v[4:5], v[0:3], off
	s_and_b64 vcc, exec, s[4:5]
	s_mov_b32 s62, s6
	v_add_u32_e32 v0, 0xb8, v148
	v_cndmask_b32_e64 v0, v16, v0, s[2:3]
	v_ashrrev_i32_e32 v1, 31, v0
	v_lshlrev_b64 v[0:1], 11, v[0:1]
	v_lshl_add_u64 v[0:1], s[40:41], 0, v[0:1]
	v_lshl_add_u64 v[4:5], v[0:1], 0, v[112:113]
	v_cndmask_b32_e64 v3, v11, v19, s[2:3]
	v_cndmask_b32_e64 v2, v7, v17, s[2:3]
	v_cndmask_b32_e64 v1, v6, v15, s[2:3]
	v_cndmask_b32_e64 v0, v10, v14, s[2:3]
	s_mov_b32 s42, s8
	s_mov_b64 s[46:47], s[12:13]
	s_mov_b64 s[44:45], s[10:11]
	global_store_dwordx4 v[4:5], v[0:3], off
	s_cbranch_vccz .LBB0_335
	s_waitcnt vmcnt(0)
	s_cmpk_gt_u32 s17, 0xff
	s_cbranch_scc1 .LBB0_346
	s_barrier

.LBB0_739:
	s_ashr_i32 s57, s56, 31
	v_cmp_lt_i64_e32 vcc, s[58:59], v[208:209]
	s_lshl_b64 s[58:59], s[56:57], 19
	s_add_u32 s58, s68, s58
	s_addc_u32 s59, s69, s59
	s_and_b64 s[60:61], vcc, exec
	s_cselect_b32 s9, s59, s11
	s_cselect_b32 s13, s58, s10
	s_ashr_i32 s55, s54, 31
	s_lshl_b64 s[60:61], s[54:55], 19
	s_add_u32 s60, s76, s60
	s_addc_u32 s61, s77, s61
	s_and_b64 s[64:65], vcc, exec
	s_cselect_b32 s17, s61, s63
	s_cselect_b32 s44, s60, s62
	s_add_u32 s10, s10, 0x40080
	s_addc_u32 s11, s11, 0
	s_add_u32 s55, s62, 0x100
	v_mov_b32_e32 v0, 0
	s_addc_u32 s57, s63, 0
	s_mov_b32 s92, -2
	s_waitcnt lgkmcnt(0)
	v_mov_b64_e32 v[0:1], 0
	v_mov_b64_e32 v[2:3], 0
	v_mov_b64_e32 v[4:5], 0
	v_mov_b64_e32 v[6:7], 0
	v_mov_b64_e32 v[8:9], 0
	v_mov_b64_e32 v[10:11], 0
	v_mov_b64_e32 v[12:13], 0
	v_mov_b64_e32 v[14:15], 0
	v_mov_b64_e32 v[16:17], 0
	v_mov_b64_e32 v[18:19], 0
	v_mov_b64_e32 v[20:21], 0
	v_mov_b64_e32 v[22:23], 0
	v_mov_b64_e32 v[24:25], 0
	v_mov_b64_e32 v[26:27], 0
	v_mov_b64_e32 v[28:29], 0
	v_mov_b64_e32 v[30:31], 0
	v_mov_b64_e32 v[32:33], 0
	v_mov_b64_e32 v[34:35], 0
	v_mov_b64_e32 v[36:37], 0
	v_mov_b64_e32 v[38:39], 0
	v_mov_b64_e32 v[40:41], 0
	v_mov_b64_e32 v[42:43], 0
	v_mov_b64_e32 v[44:45], 0
	v_mov_b64_e32 v[46:47], 0
	v_mov_b64_e32 v[48:49], 0
	v_mov_b64_e32 v[50:51], 0
	v_mov_b64_e32 v[52:53], 0
	v_mov_b64_e32 v[54:55], 0
	v_mov_b64_e32 v[56:57], 0
	v_mov_b64_e32 v[58:59], 0
	v_mov_b64_e32 v[60:61], 0
	v_mov_b64_e32 v[62:63], 0
	v_mov_b64_e32 v[72:73], 0
	v_mov_b64_e32 v[74:75], 0
	v_mov_b64_e32 v[76:77], 0
	v_mov_b64_e32 v[78:79], 0
	v_mov_b64_e32 v[80:81], 0
	v_mov_b64_e32 v[82:83], 0
	v_mov_b64_e32 v[88:89], 0
	v_mov_b64_e32 v[90:91], 0
	v_mov_b64_e32 v[96:97], 0
	v_mov_b64_e32 v[98:99], 0
	v_mov_b64_e32 v[100:101], 0
	v_mov_b64_e32 v[102:103], 0
	v_mov_b64_e32 v[104:105], 0
	v_mov_b64_e32 v[106:107], 0
	v_mov_b64_e32 v[108:109], 0
	v_mov_b64_e32 v[110:111], 0
	v_mov_b64_e32 v[112:113], 0
	v_mov_b64_e32 v[114:115], 0
	v_mov_b64_e32 v[116:117], 0
	v_mov_b64_e32 v[118:119], 0
	v_mov_b64_e32 v[120:121], 0
	v_mov_b64_e32 v[122:123], 0
	v_mov_b64_e32 v[124:125], 0
	v_mov_b64_e32 v[126:127], 0
	v_mov_b64_e32 v[128:129], 0
	v_mov_b64_e32 v[130:131], 0
	v_mov_b64_e32 v[132:133], 0
	v_mov_b64_e32 v[134:135], 0
	v_mov_b64_e32 v[136:137], 0
	v_mov_b64_e32 v[138:139], 0
	v_mov_b64_e32 v[140:141], 0
	v_mov_b64_e32 v[142:143], 0
	s_branch .LBB0_740

.LBB0_740:
	ds_read_b128 v[64:67], v221
	ds_read_b128 v[68:71], v221 offset:1024
	ds_read_b128 v[84:87], v221 offset:2048
	ds_read_b128 v[92:95], v221 offset:3072
	s_add_u32 s28, s10, 0xfffc0080
	s_addc_u32 s29, s11, -1
	s_cmp_eq_u32 s92, 12
	s_cselect_b32 s65, s9, s29
	s_cselect_b32 s64, s13, s28
	s_cselect_b32 s63, s17, s57
	s_cselect_b32 s62, s44, s55
	v_lshl_add_u64 v[176:177], s[10:11], 0, v[204:205]
	s_add_i32 m0, s78, 0xc000
	ds_read_b128 v[144:147], v222
	ds_read_b128 v[148:151], v222 offset:1024
	ds_read_b128 v[152:155], v222 offset:2048
	ds_read_b128 v[156:159], v222 offset:3072
	ds_read_b128 v[160:163], v222 offset:4096
	ds_read_b128 v[164:167], v222 offset:5120
	ds_read_b128 v[168:171], v222 offset:6144
	ds_read_b128 v[172:175], v222 offset:7168
	global_load_lds_dwordx4 v[176:177], off
	v_lshl_add_u64 v[176:177], s[10:11], 0, v[206:207]
	s_add_i32 m0, s78, 0xe000
	s_nop 0
	global_load_lds_dwordx4 v[176:177], off
	s_waitcnt lgkmcnt(8)
	s_barrier
	s_waitcnt lgkmcnt(0)
	s_waitcnt lgkmcnt(0)
	v_mfma_f32_16x16x32_bf16 v[140:143], v[64:67], v[144:147], v[140:143]
	v_mfma_f32_16x16x32_bf16 v[136:139], v[84:87], v[144:147], v[136:139]
	v_mfma_f32_16x16x32_bf16 v[124:127], v[64:67], v[152:155], v[124:127]
	v_mfma_f32_16x16x32_bf16 v[120:123], v[84:87], v[152:155], v[120:123]
	v_mfma_f32_16x16x32_bf16 v[108:111], v[64:67], v[160:163], v[108:111]
	v_mfma_f32_16x16x32_bf16 v[104:107], v[84:87], v[160:163], v[104:107]
	v_mfma_f32_16x16x32_bf16 v[88:91], v[64:67], v[168:171], v[88:91]
	v_mfma_f32_16x16x32_bf16 v[80:83], v[84:87], v[168:171], v[80:83]
	v_mfma_f32_16x16x32_bf16 v[140:143], v[68:71], v[148:151], v[140:143]
	v_mfma_f32_16x16x32_bf16 v[136:139], v[92:95], v[148:151], v[136:139]
	v_mfma_f32_16x16x32_bf16 v[124:127], v[68:71], v[156:159], v[124:127]
	v_mfma_f32_16x16x32_bf16 v[120:123], v[92:95], v[156:159], v[120:123]
	v_mfma_f32_16x16x32_bf16 v[108:111], v[68:71], v[164:167], v[108:111]
	v_mfma_f32_16x16x32_bf16 v[104:107], v[92:95], v[164:167], v[104:107]
	v_mfma_f32_16x16x32_bf16 v[88:91], v[68:71], v[172:175], v[88:91]
	v_mfma_f32_16x16x32_bf16 v[80:83], v[92:95], v[172:175], v[80:83]
	s_barrier
	s_add_i32 s28, s89, s67
	v_lshl_add_u64 v[212:213], s[62:63], 0, v[198:199]
	s_mov_b32 m0, s28
	ds_read_b128 v[176:179], v223
	ds_read_b128 v[180:183], v223 offset:1024
	ds_read_b128 v[184:187], v223 offset:2048
	ds_read_b128 v[188:191], v223 offset:3072
	global_load_lds_dwordx4 v[212:213], off
	v_lshl_add_u64 v[214:215], s[62:63], 0, v[202:203]
	s_add_i32 m0, s28, 0x2000
	s_nop 0
	global_load_lds_dwordx4 v[214:215], off
	s_barrier
	s_waitcnt lgkmcnt(0)
	s_waitcnt lgkmcnt(0)
	v_mfma_f32_16x16x32_bf16 v[132:135], v[176:179], v[144:147], v[132:135]
	v_mfma_f32_16x16x32_bf16 v[128:131], v[184:187], v[144:147], v[128:131]
	v_mfma_f32_16x16x32_bf16 v[116:119], v[176:179], v[152:155], v[116:119]
	v_mfma_f32_16x16x32_bf16 v[112:115], v[184:187], v[152:155], v[112:115]
	v_mfma_f32_16x16x32_bf16 v[100:103], v[176:179], v[160:163], v[100:103]
	v_mfma_f32_16x16x32_bf16 v[96:99], v[184:187], v[160:163], v[96:99]
	v_mfma_f32_16x16x32_bf16 v[76:79], v[176:179], v[168:171], v[76:79]
	v_mfma_f32_16x16x32_bf16 v[72:75], v[184:187], v[168:171], v[72:75]
	v_mfma_f32_16x16x32_bf16 v[132:135], v[180:183], v[148:151], v[132:135]
	v_mfma_f32_16x16x32_bf16 v[128:131], v[188:191], v[148:151], v[128:131]
	v_mfma_f32_16x16x32_bf16 v[116:119], v[180:183], v[156:159], v[116:119]
	v_mfma_f32_16x16x32_bf16 v[112:115], v[188:191], v[156:159], v[112:115]
	v_mfma_f32_16x16x32_bf16 v[100:103], v[180:183], v[164:167], v[100:103]
	v_mfma_f32_16x16x32_bf16 v[96:99], v[188:191], v[164:167], v[96:99]
	v_mfma_f32_16x16x32_bf16 v[76:79], v[180:183], v[172:175], v[76:79]
	v_mfma_f32_16x16x32_bf16 v[72:75], v[188:191], v[172:175], v[72:75]
	s_mov_b32 m0, s78
	v_lshl_add_u64 v[216:217], s[64:65], 0, v[196:197]
	s_barrier
	ds_read_b128 v[144:147], v222 offset:16384
	ds_read_b128 v[148:151], v222 offset:17408
	ds_read_b128 v[152:155], v222 offset:18432
	ds_read_b128 v[156:159], v222 offset:19456
	ds_read_b128 v[160:163], v222 offset:20480
	ds_read_b128 v[164:167], v222 offset:21504
	ds_read_b128 v[168:171], v222 offset:22528
	ds_read_b128 v[172:175], v222 offset:23552
	global_load_lds_dwordx4 v[216:217], off
	v_lshl_add_u64 v[226:227], s[64:65], 0, v[200:201]
	s_mov_b32 m0, s79
	s_nop 0
	global_load_lds_dwordx4 v[226:227], off
	s_barrier
	s_waitcnt lgkmcnt(0)
	s_waitcnt lgkmcnt(0)
	v_mfma_f32_16x16x32_bf16 v[60:63], v[64:67], v[144:147], v[60:63]
	v_mfma_f32_16x16x32_bf16 v[56:59], v[84:87], v[144:147], v[56:59]
	v_mfma_f32_16x16x32_bf16 v[44:47], v[64:67], v[152:155], v[44:47]
	v_mfma_f32_16x16x32_bf16 v[40:43], v[84:87], v[152:155], v[40:43]
	v_mfma_f32_16x16x32_bf16 v[28:31], v[64:67], v[160:163], v[28:31]
	v_mfma_f32_16x16x32_bf16 v[24:27], v[84:87], v[160:163], v[24:27]
	v_mfma_f32_16x16x32_bf16 v[12:15], v[64:67], v[168:171], v[12:15]
	v_mfma_f32_16x16x32_bf16 v[8:11], v[84:87], v[168:171], v[8:11]
	v_mfma_f32_16x16x32_bf16 v[60:63], v[68:71], v[148:151], v[60:63]
	v_mfma_f32_16x16x32_bf16 v[56:59], v[92:95], v[148:151], v[56:59]
	v_mfma_f32_16x16x32_bf16 v[44:47], v[68:71], v[156:159], v[44:47]
	v_mfma_f32_16x16x32_bf16 v[40:43], v[92:95], v[156:159], v[40:43]
	v_mfma_f32_16x16x32_bf16 v[28:31], v[68:71], v[164:167], v[28:31]
	v_mfma_f32_16x16x32_bf16 v[24:27], v[92:95], v[164:167], v[24:27]
	v_mfma_f32_16x16x32_bf16 v[12:15], v[68:71], v[172:175], v[12:15]
	v_mfma_f32_16x16x32_bf16 v[8:11], v[92:95], v[172:175], v[8:11]
	s_barrier
	s_add_u32 s94, s62, 0x10000
	s_addc_u32 s95, s63, 0
	s_add_i32 s28, s90, s67
	v_lshl_add_u64 v[64:65], s[94:95], 0, v[198:199]
	s_mov_b32 m0, s28
	s_nop 0
	global_load_lds_dwordx4 v[64:65], off
	v_lshl_add_u64 v[64:65], s[94:95], 0, v[202:203]
	s_add_i32 m0, s28, 0x2000
	s_nop 0
	global_load_lds_dwordx4 v[64:65], off
	s_waitcnt vmcnt(6)
	s_barrier
	v_mfma_f32_16x16x32_bf16 v[52:55], v[176:179], v[144:147], v[52:55]
	v_mfma_f32_16x16x32_bf16 v[48:51], v[184:187], v[144:147], v[48:51]
	v_mfma_f32_16x16x32_bf16 v[36:39], v[176:179], v[152:155], v[36:39]
	v_mfma_f32_16x16x32_bf16 v[32:35], v[184:187], v[152:155], v[32:35]
	v_mfma_f32_16x16x32_bf16 v[20:23], v[176:179], v[160:163], v[20:23]
	v_mfma_f32_16x16x32_bf16 v[16:19], v[184:187], v[160:163], v[16:19]
	v_mfma_f32_16x16x32_bf16 v[4:7], v[176:179], v[168:171], v[4:7]
	v_mfma_f32_16x16x32_bf16 v[0:3], v[184:187], v[168:171], v[0:3]
	v_mfma_f32_16x16x32_bf16 v[52:55], v[180:183], v[148:151], v[52:55]
	v_mfma_f32_16x16x32_bf16 v[48:51], v[188:191], v[148:151], v[48:51]
	v_mfma_f32_16x16x32_bf16 v[36:39], v[180:183], v[156:159], v[36:39]
	v_mfma_f32_16x16x32_bf16 v[32:35], v[188:191], v[156:159], v[32:35]
	v_mfma_f32_16x16x32_bf16 v[20:23], v[180:183], v[164:167], v[20:23]
	v_mfma_f32_16x16x32_bf16 v[16:19], v[188:191], v[164:167], v[16:19]
	v_mfma_f32_16x16x32_bf16 v[4:7], v[180:183], v[172:175], v[4:7]
	v_mfma_f32_16x16x32_bf16 v[0:3], v[188:191], v[172:175], v[0:3]
	s_add_i32 s28, 0, 0x18000
	v_add_u32_e32 v92, s28, v218
	s_barrier
	ds_read_b128 v[64:67], v92
	ds_read_b128 v[68:71], v92 offset:1024
	ds_read_b128 v[84:87], v92 offset:2048
	ds_read_b128 v[92:95], v92 offset:3072
	s_add_u32 s64, s64, 0x40000
	s_addc_u32 s65, s65, 0
	s_mov_b32 m0, s80
	v_lshl_add_u64 v[176:177], s[64:65], 0, v[196:197]
	ds_read_b128 v[144:147], v222 offset:32768
	ds_read_b128 v[148:151], v222 offset:33792
	ds_read_b128 v[152:155], v222 offset:34816
	ds_read_b128 v[156:159], v222 offset:35840
	ds_read_b128 v[160:163], v222 offset:36864
	ds_read_b128 v[164:167], v222 offset:37888
	ds_read_b128 v[168:171], v222 offset:38912
	ds_read_b128 v[172:175], v222 offset:39936
	global_load_lds_dwordx4 v[176:177], off
	v_lshl_add_u64 v[176:177], s[64:65], 0, v[200:201]
	s_mov_b32 m0, s81
	s_nop 0
	global_load_lds_dwordx4 v[176:177], off
	s_waitcnt lgkmcnt(8)
	s_barrier
	s_waitcnt lgkmcnt(0)
	s_waitcnt lgkmcnt(0)
	v_mfma_f32_16x16x32_bf16 v[140:143], v[64:67], v[144:147], v[140:143]
	v_mfma_f32_16x16x32_bf16 v[136:139], v[84:87], v[144:147], v[136:139]
	v_mfma_f32_16x16x32_bf16 v[124:127], v[64:67], v[152:155], v[124:127]
	v_mfma_f32_16x16x32_bf16 v[120:123], v[84:87], v[152:155], v[120:123]
	v_mfma_f32_16x16x32_bf16 v[108:111], v[64:67], v[160:163], v[108:111]
	v_mfma_f32_16x16x32_bf16 v[104:107], v[84:87], v[160:163], v[104:107]
	v_mfma_f32_16x16x32_bf16 v[88:91], v[64:67], v[168:171], v[88:91]
	v_mfma_f32_16x16x32_bf16 v[80:83], v[84:87], v[168:171], v[80:83]
	v_mfma_f32_16x16x32_bf16 v[140:143], v[68:71], v[148:151], v[140:143]
	v_mfma_f32_16x16x32_bf16 v[136:139], v[92:95], v[148:151], v[136:139]
	v_mfma_f32_16x16x32_bf16 v[124:127], v[68:71], v[156:159], v[124:127]
	v_mfma_f32_16x16x32_bf16 v[120:123], v[92:95], v[156:159], v[120:123]
	v_mfma_f32_16x16x32_bf16 v[108:111], v[68:71], v[164:167], v[108:111]
	v_mfma_f32_16x16x32_bf16 v[104:107], v[92:95], v[164:167], v[104:107]
	v_mfma_f32_16x16x32_bf16 v[88:91], v[68:71], v[172:175], v[88:91]
	v_mfma_f32_16x16x32_bf16 v[80:83], v[92:95], v[172:175], v[80:83]
	s_barrier
	s_add_i32 s29, 0, 0x1c000
	s_add_i32 s28, s28, s67
	v_add_u32_e32 v188, s29, v218
	v_lshl_add_u64 v[212:213], v[212:213], 0, s[52:53]
	s_mov_b32 m0, s28
	ds_read_b128 v[176:179], v188
	ds_read_b128 v[180:183], v188 offset:1024
	ds_read_b128 v[184:187], v188 offset:2048
	ds_read_b128 v[188:191], v188 offset:3072
	global_load_lds_dwordx4 v[212:213], off
	v_lshl_add_u64 v[212:213], v[214:215], 0, s[52:53]
	s_add_i32 m0, s28, 0x2000
	s_nop 0
	global_load_lds_dwordx4 v[212:213], off
	s_barrier
	s_waitcnt lgkmcnt(0)
	s_waitcnt lgkmcnt(0)
	v_mfma_f32_16x16x32_bf16 v[132:135], v[176:179], v[144:147], v[132:135]
	v_mfma_f32_16x16x32_bf16 v[128:131], v[184:187], v[144:147], v[128:131]
	v_mfma_f32_16x16x32_bf16 v[116:119], v[176:179], v[152:155], v[116:119]
	v_mfma_f32_16x16x32_bf16 v[112:115], v[184:187], v[152:155], v[112:115]
	v_mfma_f32_16x16x32_bf16 v[100:103], v[176:179], v[160:163], v[100:103]
	v_mfma_f32_16x16x32_bf16 v[96:99], v[184:187], v[160:163], v[96:99]
	v_mfma_f32_16x16x32_bf16 v[76:79], v[176:179], v[168:171], v[76:79]
	v_mfma_f32_16x16x32_bf16 v[72:75], v[184:187], v[168:171], v[72:75]
	v_mfma_f32_16x16x32_bf16 v[132:135], v[180:183], v[148:151], v[132:135]
	v_mfma_f32_16x16x32_bf16 v[128:131], v[188:191], v[148:151], v[128:131]
	v_mfma_f32_16x16x32_bf16 v[116:119], v[180:183], v[156:159], v[116:119]
	v_mfma_f32_16x16x32_bf16 v[112:115], v[188:191], v[156:159], v[112:115]
	v_mfma_f32_16x16x32_bf16 v[100:103], v[180:183], v[164:167], v[100:103]
	v_mfma_f32_16x16x32_bf16 v[96:99], v[188:191], v[164:167], v[96:99]
	v_mfma_f32_16x16x32_bf16 v[76:79], v[180:183], v[172:175], v[76:79]
	v_mfma_f32_16x16x32_bf16 v[72:75], v[188:191], v[172:175], v[72:75]
	s_mov_b32 m0, s85
	v_lshl_add_u64 v[212:213], v[216:217], 0, s[52:53]
	s_barrier
	ds_read_b128 v[144:147], v222 offset:49152
	ds_read_b128 v[148:151], v222 offset:50176
	ds_read_b128 v[152:155], v222 offset:51200
	ds_read_b128 v[156:159], v222 offset:52224
	ds_read_b128 v[160:163], v222 offset:53248
	ds_read_b128 v[164:167], v222 offset:54272
	ds_read_b128 v[168:171], v222 offset:55296
	ds_read_b128 v[172:175], v222 offset:56320
	global_load_lds_dwordx4 v[212:213], off
	v_lshl_add_u64 v[212:213], v[226:227], 0, s[52:53]
	s_mov_b32 m0, s87
	s_nop 0
	global_load_lds_dwordx4 v[212:213], off
	s_barrier
	s_waitcnt lgkmcnt(0)
	s_waitcnt lgkmcnt(0)
	v_mfma_f32_16x16x32_bf16 v[60:63], v[64:67], v[144:147], v[60:63]
	v_mfma_f32_16x16x32_bf16 v[56:59], v[84:87], v[144:147], v[56:59]
	v_mfma_f32_16x16x32_bf16 v[44:47], v[64:67], v[152:155], v[44:47]
	v_mfma_f32_16x16x32_bf16 v[40:43], v[84:87], v[152:155], v[40:43]
	v_mfma_f32_16x16x32_bf16 v[28:31], v[64:67], v[160:163], v[28:31]
	v_mfma_f32_16x16x32_bf16 v[24:27], v[84:87], v[160:163], v[24:27]
	v_mfma_f32_16x16x32_bf16 v[12:15], v[64:67], v[168:171], v[12:15]
	v_mfma_f32_16x16x32_bf16 v[8:11], v[84:87], v[168:171], v[8:11]
	v_mfma_f32_16x16x32_bf16 v[60:63], v[68:71], v[148:151], v[60:63]
	v_mfma_f32_16x16x32_bf16 v[56:59], v[92:95], v[148:151], v[56:59]
	v_mfma_f32_16x16x32_bf16 v[44:47], v[68:71], v[156:159], v[44:47]
	v_mfma_f32_16x16x32_bf16 v[40:43], v[92:95], v[156:159], v[40:43]
	v_mfma_f32_16x16x32_bf16 v[28:31], v[68:71], v[164:167], v[28:31]
	v_mfma_f32_16x16x32_bf16 v[24:27], v[92:95], v[164:167], v[24:27]
	v_mfma_f32_16x16x32_bf16 v[12:15], v[68:71], v[172:175], v[12:15]
	v_mfma_f32_16x16x32_bf16 v[8:11], v[92:95], v[172:175], v[8:11]
	s_barrier
	s_add_u32 s62, s62, 0x10080
	s_addc_u32 s63, s63, 0
	s_add_i32 s28, s29, s67
	v_lshl_add_u64 v[64:65], s[62:63], 0, v[198:199]
	s_mov_b32 m0, s28
	s_nop 0
	global_load_lds_dwordx4 v[64:65], off
	v_lshl_add_u64 v[64:65], s[62:63], 0, v[202:203]
	s_add_i32 m0, s28, 0x2000
	s_nop 0
	global_load_lds_dwordx4 v[64:65], off
	s_waitcnt vmcnt(6)
	s_barrier
	v_mfma_f32_16x16x32_bf16 v[52:55], v[176:179], v[144:147], v[52:55]
	v_mfma_f32_16x16x32_bf16 v[48:51], v[184:187], v[144:147], v[48:51]
	v_mfma_f32_16x16x32_bf16 v[36:39], v[176:179], v[152:155], v[36:39]
	v_mfma_f32_16x16x32_bf16 v[32:35], v[184:187], v[152:155], v[32:35]
	v_mfma_f32_16x16x32_bf16 v[20:23], v[176:179], v[160:163], v[20:23]
	v_mfma_f32_16x16x32_bf16 v[16:19], v[184:187], v[160:163], v[16:19]
	v_mfma_f32_16x16x32_bf16 v[4:7], v[176:179], v[168:171], v[4:7]
	v_mfma_f32_16x16x32_bf16 v[0:3], v[184:187], v[168:171], v[0:3]
	v_mfma_f32_16x16x32_bf16 v[52:55], v[180:183], v[148:151], v[52:55]
	v_mfma_f32_16x16x32_bf16 v[48:51], v[188:191], v[148:151], v[48:51]
	v_mfma_f32_16x16x32_bf16 v[36:39], v[180:183], v[156:159], v[36:39]
	v_mfma_f32_16x16x32_bf16 v[32:35], v[188:191], v[156:159], v[32:35]
	v_mfma_f32_16x16x32_bf16 v[20:23], v[180:183], v[164:167], v[20:23]
	v_mfma_f32_16x16x32_bf16 v[16:19], v[188:191], v[164:167], v[16:19]
	v_mfma_f32_16x16x32_bf16 v[4:7], v[180:183], v[172:175], v[4:7]
	v_mfma_f32_16x16x32_bf16 v[0:3], v[188:191], v[172:175], v[0:3]
	s_add_i32 s92, s92, 2
	s_add_u32 s10, s10, 0x100
	s_addc_u32 s11, s11, 0
	s_add_u32 s55, s55, 0x100
	s_addc_u32 s57, s57, 0
	s_cmp_gt_u32 s92, 13
	s_cbranch_scc0 .Lrot_740
	s_barrier
	v_lshl_add_u32 v212, s8, 8, v195
	v_lshl_or_b32 v214, s12, 8, v219
	v_ashrrev_i32_e32 v213, 31, v212
	v_ashrrev_i32_e32 v215, 31, v214
	s_mov_b64 s[8:9], -1
	s_and_b64 vcc, exec, s[48:49]
	s_cbranch_vccz .LBB0_743
	v_lshlrev_b64 v[64:65], 12, v[212:213]
	v_lshl_add_u64 v[64:65], s[36:37], 0, v[64:65]
	v_lshl_add_u64 v[64:65], v[214:215], 2, v[64:65]
	global_load_dwordx4 v[160:163], v[64:65], off offset:16
	global_load_dwordx4 v[164:167], v[64:65], off
	global_load_dwordx4 v[168:171], v[64:65], off offset:144
	global_load_dwordx4 v[172:175], v[64:65], off offset:128
	s_mov_b64 s[8:9], 0

.LBB0_903:
	s_ashr_i32 s45, s44, 31
	v_cmp_lt_i64_e32 vcc, s[0:1], v[142:143]
	s_lshl_b64 s[0:1], s[44:45], 19
	s_add_u32 s46, s42, s0
	s_addc_u32 s47, s43, s1
	s_and_b64 s[0:1], vcc, exec
	s_cselect_b32 s7, s47, s53
	s_cselect_b32 s45, s46, s52
	s_ashr_i32 s37, s36, 31
	s_lshl_b64 s[0:1], s[36:37], 19
	s_add_u32 s48, s74, s0
	s_addc_u32 s49, s75, s1
	s_and_b64 s[0:1], vcc, exec
	s_cselect_b32 s37, s49, s51
	s_cselect_b32 s67, s48, s50
	s_add_u32 s0, s52, 0x40080
	s_addc_u32 s1, s53, 0
	s_add_u32 s76, s50, 0x100
	v_mov_b32_e32 v0, 0
	s_addc_u32 s77, s51, 0
	s_mov_b32 s78, -2
	v_mov_b64_e32 v[0:1], 0
	v_mov_b64_e32 v[2:3], 0
	v_mov_b64_e32 v[4:5], 0
	v_mov_b64_e32 v[6:7], 0
	v_mov_b64_e32 v[8:9], 0
	v_mov_b64_e32 v[10:11], 0
	v_mov_b64_e32 v[12:13], 0
	v_mov_b64_e32 v[14:15], 0
	v_mov_b64_e32 v[16:17], 0
	v_mov_b64_e32 v[18:19], 0
	v_mov_b64_e32 v[20:21], 0
	v_mov_b64_e32 v[22:23], 0
	v_mov_b64_e32 v[24:25], 0
	v_mov_b64_e32 v[26:27], 0
	v_mov_b64_e32 v[28:29], 0
	v_mov_b64_e32 v[30:31], 0
	v_mov_b64_e32 v[32:33], 0
	v_mov_b64_e32 v[34:35], 0
	v_mov_b64_e32 v[36:37], 0
	v_mov_b64_e32 v[38:39], 0
	v_mov_b64_e32 v[40:41], 0
	v_mov_b64_e32 v[42:43], 0
	v_mov_b64_e32 v[44:45], 0
	v_mov_b64_e32 v[46:47], 0
	v_mov_b64_e32 v[48:49], 0
	v_mov_b64_e32 v[50:51], 0
	v_mov_b64_e32 v[52:53], 0
	v_mov_b64_e32 v[54:55], 0
	v_mov_b64_e32 v[56:57], 0
	v_mov_b64_e32 v[58:59], 0
	v_mov_b64_e32 v[60:61], 0
	v_mov_b64_e32 v[62:63], 0
	v_mov_b64_e32 v[64:65], 0
	v_mov_b64_e32 v[66:67], 0
	v_mov_b64_e32 v[68:69], 0
	v_mov_b64_e32 v[70:71], 0
	v_mov_b64_e32 v[72:73], 0
	v_mov_b64_e32 v[74:75], 0
	v_mov_b64_e32 v[76:77], 0
	v_mov_b64_e32 v[78:79], 0
	v_mov_b64_e32 v[80:81], 0
	v_mov_b64_e32 v[82:83], 0
	v_mov_b64_e32 v[84:85], 0
	v_mov_b64_e32 v[86:87], 0
	v_mov_b64_e32 v[88:89], 0
	v_mov_b64_e32 v[90:91], 0
	v_mov_b64_e32 v[92:93], 0
	v_mov_b64_e32 v[94:95], 0
	v_mov_b64_e32 v[96:97], 0
	v_mov_b64_e32 v[98:99], 0
	v_mov_b64_e32 v[100:101], 0
	v_mov_b64_e32 v[102:103], 0
	v_mov_b64_e32 v[104:105], 0
	v_mov_b64_e32 v[106:107], 0
	v_mov_b64_e32 v[108:109], 0
	v_mov_b64_e32 v[110:111], 0
	v_mov_b64_e32 v[112:113], 0
	v_mov_b64_e32 v[114:115], 0
	v_mov_b64_e32 v[116:117], 0
	v_mov_b64_e32 v[118:119], 0
	v_mov_b64_e32 v[120:121], 0
	v_mov_b64_e32 v[122:123], 0
	v_mov_b64_e32 v[124:125], 0
	v_mov_b64_e32 v[126:127], 0
	s_branch .LBB0_904

.LBB0_904:
	ds_read_b128 v[146:149], v169
	ds_read_b128 v[150:153], v169 offset:1024
	ds_read_b128 v[154:157], v169 offset:2048
	ds_read_b128 v[174:177], v169 offset:3072
	s_add_u32 s28, s0, 0xfffc0080
	s_addc_u32 s29, s1, -1
	s_cmp_eq_u32 s78, 12
	s_cselect_b32 s53, s7, s29
	s_cselect_b32 s52, s45, s28
	s_cselect_b32 s51, s37, s77
	s_cselect_b32 s50, s67, s76
	v_lshl_add_u64 v[158:159], s[0:1], 0, v[138:139]
	s_add_i32 m0, s54, 0xc000
	ds_read_b128 v[178:181], v171
	ds_read_b128 v[182:185], v171 offset:1024
	ds_read_b128 v[186:189], v171 offset:2048
	ds_read_b128 v[196:199], v171 offset:3072
	ds_read_b128 v[200:203], v171 offset:4096
	ds_read_b128 v[204:207], v171 offset:5120
	ds_read_b128 v[208:211], v171 offset:6144
	ds_read_b128 v[212:215], v171 offset:7168
	global_load_lds_dwordx4 v[158:159], off
	v_lshl_add_u64 v[158:159], s[0:1], 0, v[140:141]
	s_add_i32 m0, s54, 0xe000
	s_nop 0
	global_load_lds_dwordx4 v[158:159], off
	s_waitcnt lgkmcnt(8)
	s_barrier
	s_waitcnt lgkmcnt(0)
	s_waitcnt lgkmcnt(0)
	v_mfma_f32_16x16x32_bf16 v[124:127], v[146:149], v[178:181], v[124:127]
	v_mfma_f32_16x16x32_bf16 v[120:123], v[154:157], v[178:181], v[120:123]
	v_mfma_f32_16x16x32_bf16 v[108:111], v[146:149], v[186:189], v[108:111]
	v_mfma_f32_16x16x32_bf16 v[104:107], v[154:157], v[186:189], v[104:107]
	v_mfma_f32_16x16x32_bf16 v[92:95], v[146:149], v[200:203], v[92:95]
	v_mfma_f32_16x16x32_bf16 v[88:91], v[154:157], v[200:203], v[88:91]
	v_mfma_f32_16x16x32_bf16 v[76:79], v[146:149], v[208:211], v[76:79]
	v_mfma_f32_16x16x32_bf16 v[72:75], v[154:157], v[208:211], v[72:75]
	v_mfma_f32_16x16x32_bf16 v[124:127], v[150:153], v[182:185], v[124:127]
	v_mfma_f32_16x16x32_bf16 v[120:123], v[174:177], v[182:185], v[120:123]
	v_mfma_f32_16x16x32_bf16 v[108:111], v[150:153], v[196:199], v[108:111]
	v_mfma_f32_16x16x32_bf16 v[104:107], v[174:177], v[196:199], v[104:107]
	v_mfma_f32_16x16x32_bf16 v[92:95], v[150:153], v[204:207], v[92:95]
	v_mfma_f32_16x16x32_bf16 v[88:91], v[174:177], v[204:207], v[88:91]
	v_mfma_f32_16x16x32_bf16 v[76:79], v[150:153], v[212:215], v[76:79]
	v_mfma_f32_16x16x32_bf16 v[72:75], v[174:177], v[212:215], v[72:75]
	s_barrier
	s_add_i32 s28, s63, s13
	v_lshl_add_u64 v[158:159], s[50:51], 0, v[132:133]
	s_mov_b32 m0, s28
	ds_read_b128 v[216:219], v172
	ds_read_b128 v[220:223], v172 offset:1024
	ds_read_b128 v[224:227], v172 offset:2048
	ds_read_b128 v[228:231], v172 offset:3072
	global_load_lds_dwordx4 v[158:159], off
	v_lshl_add_u64 v[164:165], s[50:51], 0, v[128:129]
	s_add_i32 m0, s28, 0x2000
	s_nop 0
	global_load_lds_dwordx4 v[164:165], off
	s_barrier
	s_waitcnt lgkmcnt(0)
	s_waitcnt lgkmcnt(0)
	v_mfma_f32_16x16x32_bf16 v[116:119], v[216:219], v[178:181], v[116:119]
	v_mfma_f32_16x16x32_bf16 v[112:115], v[224:227], v[178:181], v[112:115]
	v_mfma_f32_16x16x32_bf16 v[100:103], v[216:219], v[186:189], v[100:103]
	v_mfma_f32_16x16x32_bf16 v[96:99], v[224:227], v[186:189], v[96:99]
	v_mfma_f32_16x16x32_bf16 v[84:87], v[216:219], v[200:203], v[84:87]
	v_mfma_f32_16x16x32_bf16 v[80:83], v[224:227], v[200:203], v[80:83]
	v_mfma_f32_16x16x32_bf16 v[68:71], v[216:219], v[208:211], v[68:71]
	v_mfma_f32_16x16x32_bf16 v[64:67], v[224:227], v[208:211], v[64:67]
	v_mfma_f32_16x16x32_bf16 v[116:119], v[220:223], v[182:185], v[116:119]
	v_mfma_f32_16x16x32_bf16 v[112:115], v[228:231], v[182:185], v[112:115]
	v_mfma_f32_16x16x32_bf16 v[100:103], v[220:223], v[196:199], v[100:103]
	v_mfma_f32_16x16x32_bf16 v[96:99], v[228:231], v[196:199], v[96:99]
	v_mfma_f32_16x16x32_bf16 v[84:87], v[220:223], v[204:207], v[84:87]
	v_mfma_f32_16x16x32_bf16 v[80:83], v[228:231], v[204:207], v[80:83]
	v_mfma_f32_16x16x32_bf16 v[68:71], v[220:223], v[212:215], v[68:71]
	v_mfma_f32_16x16x32_bf16 v[64:67], v[228:231], v[212:215], v[64:67]
	s_mov_b32 m0, s54
	v_lshl_add_u64 v[190:191], s[52:53], 0, v[134:135]
	s_barrier
	ds_read_b128 v[178:181], v171 offset:16384
	ds_read_b128 v[182:185], v171 offset:17408
	ds_read_b128 v[186:189], v171 offset:18432
	ds_read_b128 v[196:199], v171 offset:19456
	ds_read_b128 v[200:203], v171 offset:20480
	ds_read_b128 v[204:207], v171 offset:21504
	ds_read_b128 v[208:211], v171 offset:22528
	ds_read_b128 v[212:215], v171 offset:23552
	global_load_lds_dwordx4 v[190:191], off
	v_lshl_add_u64 v[232:233], s[52:53], 0, v[130:131]
	s_mov_b32 m0, s55
	s_nop 0
	global_load_lds_dwordx4 v[232:233], off
	s_barrier
	s_waitcnt lgkmcnt(0)
	s_waitcnt lgkmcnt(0)
	v_mfma_f32_16x16x32_bf16 v[60:63], v[146:149], v[178:181], v[60:63]
	v_mfma_f32_16x16x32_bf16 v[56:59], v[154:157], v[178:181], v[56:59]
	v_mfma_f32_16x16x32_bf16 v[44:47], v[146:149], v[186:189], v[44:47]
	v_mfma_f32_16x16x32_bf16 v[40:43], v[154:157], v[186:189], v[40:43]
	v_mfma_f32_16x16x32_bf16 v[28:31], v[146:149], v[200:203], v[28:31]
	v_mfma_f32_16x16x32_bf16 v[24:27], v[154:157], v[200:203], v[24:27]
	v_mfma_f32_16x16x32_bf16 v[12:15], v[146:149], v[208:211], v[12:15]
	v_mfma_f32_16x16x32_bf16 v[8:11], v[154:157], v[208:211], v[8:11]
	v_mfma_f32_16x16x32_bf16 v[60:63], v[150:153], v[182:185], v[60:63]
	v_mfma_f32_16x16x32_bf16 v[56:59], v[174:177], v[182:185], v[56:59]
	v_mfma_f32_16x16x32_bf16 v[44:47], v[150:153], v[196:199], v[44:47]
	v_mfma_f32_16x16x32_bf16 v[40:43], v[174:177], v[196:199], v[40:43]
	v_mfma_f32_16x16x32_bf16 v[28:31], v[150:153], v[204:207], v[28:31]
	v_mfma_f32_16x16x32_bf16 v[24:27], v[174:177], v[204:207], v[24:27]
	v_mfma_f32_16x16x32_bf16 v[12:15], v[150:153], v[212:215], v[12:15]
	v_mfma_f32_16x16x32_bf16 v[8:11], v[174:177], v[212:215], v[8:11]
	s_barrier
	s_add_u32 s80, s50, 0x10000
	s_addc_u32 s81, s51, 0
	s_add_i32 s28, s64, s13
	v_lshl_add_u64 v[146:147], s[80:81], 0, v[132:133]
	s_mov_b32 m0, s28
	s_nop 0
	global_load_lds_dwordx4 v[146:147], off
	v_lshl_add_u64 v[146:147], s[80:81], 0, v[128:129]
	s_add_i32 m0, s28, 0x2000
	s_nop 0
	global_load_lds_dwordx4 v[146:147], off
	s_waitcnt vmcnt(6)
	s_barrier
	v_mfma_f32_16x16x32_bf16 v[52:55], v[216:219], v[178:181], v[52:55]
	v_mfma_f32_16x16x32_bf16 v[48:51], v[224:227], v[178:181], v[48:51]
	v_mfma_f32_16x16x32_bf16 v[36:39], v[216:219], v[186:189], v[36:39]
	v_mfma_f32_16x16x32_bf16 v[32:35], v[224:227], v[186:189], v[32:35]
	v_mfma_f32_16x16x32_bf16 v[20:23], v[216:219], v[200:203], v[20:23]
	v_mfma_f32_16x16x32_bf16 v[16:19], v[224:227], v[200:203], v[16:19]
	v_mfma_f32_16x16x32_bf16 v[4:7], v[216:219], v[208:211], v[4:7]
	v_mfma_f32_16x16x32_bf16 v[0:3], v[224:227], v[208:211], v[0:3]
	v_mfma_f32_16x16x32_bf16 v[52:55], v[220:223], v[182:185], v[52:55]
	v_mfma_f32_16x16x32_bf16 v[48:51], v[228:231], v[182:185], v[48:51]
	v_mfma_f32_16x16x32_bf16 v[36:39], v[220:223], v[196:199], v[36:39]
	v_mfma_f32_16x16x32_bf16 v[32:35], v[228:231], v[196:199], v[32:35]
	v_mfma_f32_16x16x32_bf16 v[20:23], v[220:223], v[204:207], v[20:23]
	v_mfma_f32_16x16x32_bf16 v[16:19], v[228:231], v[204:207], v[16:19]
	v_mfma_f32_16x16x32_bf16 v[4:7], v[220:223], v[212:215], v[4:7]
	v_mfma_f32_16x16x32_bf16 v[0:3], v[228:231], v[212:215], v[0:3]
	s_add_i32 s28, 0, 0x18000
	v_add_u32_e32 v160, s28, v163
	s_barrier
	ds_read_b128 v[146:149], v160
	ds_read_b128 v[150:153], v160 offset:1024
	ds_read_b128 v[154:157], v160 offset:2048
	ds_read_b128 v[174:177], v160 offset:3072
	s_add_u32 s52, s52, 0x40000
	s_addc_u32 s53, s53, 0
	s_mov_b32 m0, s56
	v_lshl_add_u64 v[216:217], s[52:53], 0, v[134:135]
	ds_read_b128 v[178:181], v171 offset:32768
	ds_read_b128 v[182:185], v171 offset:33792
	ds_read_b128 v[186:189], v171 offset:34816
	ds_read_b128 v[196:199], v171 offset:35840
	ds_read_b128 v[200:203], v171 offset:36864
	ds_read_b128 v[204:207], v171 offset:37888
	ds_read_b128 v[208:211], v171 offset:38912
	ds_read_b128 v[212:215], v171 offset:39936
	global_load_lds_dwordx4 v[216:217], off
	v_lshl_add_u64 v[216:217], s[52:53], 0, v[130:131]
	s_mov_b32 m0, s57
	s_nop 0
	global_load_lds_dwordx4 v[216:217], off
	s_waitcnt lgkmcnt(8)
	s_barrier
	s_waitcnt lgkmcnt(0)
	s_waitcnt lgkmcnt(0)
	v_mfma_f32_16x16x32_bf16 v[124:127], v[146:149], v[178:181], v[124:127]
	v_mfma_f32_16x16x32_bf16 v[120:123], v[154:157], v[178:181], v[120:123]
	v_mfma_f32_16x16x32_bf16 v[108:111], v[146:149], v[186:189], v[108:111]
	v_mfma_f32_16x16x32_bf16 v[104:107], v[154:157], v[186:189], v[104:107]
	v_mfma_f32_16x16x32_bf16 v[92:95], v[146:149], v[200:203], v[92:95]
	v_mfma_f32_16x16x32_bf16 v[88:91], v[154:157], v[200:203], v[88:91]
	v_mfma_f32_16x16x32_bf16 v[76:79], v[146:149], v[208:211], v[76:79]
	v_mfma_f32_16x16x32_bf16 v[72:75], v[154:157], v[208:211], v[72:75]
	v_mfma_f32_16x16x32_bf16 v[124:127], v[150:153], v[182:185], v[124:127]
	v_mfma_f32_16x16x32_bf16 v[120:123], v[174:177], v[182:185], v[120:123]
	v_mfma_f32_16x16x32_bf16 v[108:111], v[150:153], v[196:199], v[108:111]
	v_mfma_f32_16x16x32_bf16 v[104:107], v[174:177], v[196:199], v[104:107]
	v_mfma_f32_16x16x32_bf16 v[92:95], v[150:153], v[204:207], v[92:95]
	v_mfma_f32_16x16x32_bf16 v[88:91], v[174:177], v[204:207], v[88:91]
	v_mfma_f32_16x16x32_bf16 v[76:79], v[150:153], v[212:215], v[76:79]
	v_mfma_f32_16x16x32_bf16 v[72:75], v[174:177], v[212:215], v[72:75]
	s_barrier
	s_add_i32 s29, 0, 0x1c000
	s_add_i32 s28, s28, s13
	v_add_u32_e32 v160, s29, v163
	v_lshl_add_u64 v[158:159], v[158:159], 0, s[8:9]
	s_mov_b32 m0, s28
	ds_read_b128 v[216:219], v160
	ds_read_b128 v[220:223], v160 offset:1024
	ds_read_b128 v[224:227], v160 offset:2048
	ds_read_b128 v[228:231], v160 offset:3072
	global_load_lds_dwordx4 v[158:159], off
	v_lshl_add_u64 v[158:159], v[164:165], 0, s[8:9]
	s_add_i32 m0, s28, 0x2000
	s_nop 0
	global_load_lds_dwordx4 v[158:159], off
	s_barrier
	s_waitcnt lgkmcnt(0)
	s_waitcnt lgkmcnt(0)
	v_mfma_f32_16x16x32_bf16 v[116:119], v[216:219], v[178:181], v[116:119]
	v_mfma_f32_16x16x32_bf16 v[112:115], v[224:227], v[178:181], v[112:115]
	v_mfma_f32_16x16x32_bf16 v[100:103], v[216:219], v[186:189], v[100:103]
	v_mfma_f32_16x16x32_bf16 v[96:99], v[224:227], v[186:189], v[96:99]
	v_mfma_f32_16x16x32_bf16 v[84:87], v[216:219], v[200:203], v[84:87]
	v_mfma_f32_16x16x32_bf16 v[80:83], v[224:227], v[200:203], v[80:83]
	v_mfma_f32_16x16x32_bf16 v[68:71], v[216:219], v[208:211], v[68:71]
	v_mfma_f32_16x16x32_bf16 v[64:67], v[224:227], v[208:211], v[64:67]
	v_mfma_f32_16x16x32_bf16 v[116:119], v[220:223], v[182:185], v[116:119]
	v_mfma_f32_16x16x32_bf16 v[112:115], v[228:231], v[182:185], v[112:115]
	v_mfma_f32_16x16x32_bf16 v[100:103], v[220:223], v[196:199], v[100:103]
	v_mfma_f32_16x16x32_bf16 v[96:99], v[228:231], v[196:199], v[96:99]
	v_mfma_f32_16x16x32_bf16 v[84:87], v[220:223], v[204:207], v[84:87]
	v_mfma_f32_16x16x32_bf16 v[80:83], v[228:231], v[204:207], v[80:83]
	v_mfma_f32_16x16x32_bf16 v[68:71], v[220:223], v[212:215], v[68:71]
	v_mfma_f32_16x16x32_bf16 v[64:67], v[228:231], v[212:215], v[64:67]
	s_mov_b32 m0, s60
	v_lshl_add_u64 v[158:159], v[190:191], 0, s[8:9]
	s_barrier
	ds_read_b128 v[178:181], v171 offset:49152
	ds_read_b128 v[182:185], v171 offset:50176
	ds_read_b128 v[186:189], v171 offset:51200
	ds_read_b128 v[196:199], v171 offset:52224
	ds_read_b128 v[200:203], v171 offset:53248
	ds_read_b128 v[204:207], v171 offset:54272
	ds_read_b128 v[208:211], v171 offset:55296
	ds_read_b128 v[212:215], v171 offset:56320
	global_load_lds_dwordx4 v[158:159], off
	v_lshl_add_u64 v[158:159], v[232:233], 0, s[8:9]
	s_mov_b32 m0, s61
	s_nop 0
	global_load_lds_dwordx4 v[158:159], off
	s_barrier
	s_waitcnt lgkmcnt(0)
	s_waitcnt lgkmcnt(0)
	v_mfma_f32_16x16x32_bf16 v[60:63], v[146:149], v[178:181], v[60:63]
	v_mfma_f32_16x16x32_bf16 v[56:59], v[154:157], v[178:181], v[56:59]
	v_mfma_f32_16x16x32_bf16 v[44:47], v[146:149], v[186:189], v[44:47]
	v_mfma_f32_16x16x32_bf16 v[40:43], v[154:157], v[186:189], v[40:43]
	v_mfma_f32_16x16x32_bf16 v[28:31], v[146:149], v[200:203], v[28:31]
	v_mfma_f32_16x16x32_bf16 v[24:27], v[154:157], v[200:203], v[24:27]
	v_mfma_f32_16x16x32_bf16 v[12:15], v[146:149], v[208:211], v[12:15]
	v_mfma_f32_16x16x32_bf16 v[8:11], v[154:157], v[208:211], v[8:11]
	v_mfma_f32_16x16x32_bf16 v[60:63], v[150:153], v[182:185], v[60:63]
	v_mfma_f32_16x16x32_bf16 v[56:59], v[174:177], v[182:185], v[56:59]
	v_mfma_f32_16x16x32_bf16 v[44:47], v[150:153], v[196:199], v[44:47]
	v_mfma_f32_16x16x32_bf16 v[40:43], v[174:177], v[196:199], v[40:43]
	v_mfma_f32_16x16x32_bf16 v[28:31], v[150:153], v[204:207], v[28:31]
	v_mfma_f32_16x16x32_bf16 v[24:27], v[174:177], v[204:207], v[24:27]
	v_mfma_f32_16x16x32_bf16 v[12:15], v[150:153], v[212:215], v[12:15]
	v_mfma_f32_16x16x32_bf16 v[8:11], v[174:177], v[212:215], v[8:11]
	s_barrier
	s_add_u32 s50, s50, 0x10080
	s_addc_u32 s51, s51, 0
	s_add_i32 s28, s29, s13
	v_lshl_add_u64 v[146:147], s[50:51], 0, v[132:133]
	s_mov_b32 m0, s28
	s_nop 0
	global_load_lds_dwordx4 v[146:147], off
	v_lshl_add_u64 v[146:147], s[50:51], 0, v[128:129]
	s_add_i32 m0, s28, 0x2000
	s_nop 0
	global_load_lds_dwordx4 v[146:147], off
	s_waitcnt vmcnt(6)
	s_barrier
	v_mfma_f32_16x16x32_bf16 v[52:55], v[216:219], v[178:181], v[52:55]
	v_mfma_f32_16x16x32_bf16 v[48:51], v[224:227], v[178:181], v[48:51]
	v_mfma_f32_16x16x32_bf16 v[36:39], v[216:219], v[186:189], v[36:39]
	v_mfma_f32_16x16x32_bf16 v[32:35], v[224:227], v[186:189], v[32:35]
	v_mfma_f32_16x16x32_bf16 v[20:23], v[216:219], v[200:203], v[20:23]
	v_mfma_f32_16x16x32_bf16 v[16:19], v[224:227], v[200:203], v[16:19]
	v_mfma_f32_16x16x32_bf16 v[4:7], v[216:219], v[208:211], v[4:7]
	v_mfma_f32_16x16x32_bf16 v[0:3], v[224:227], v[208:211], v[0:3]
	v_mfma_f32_16x16x32_bf16 v[52:55], v[220:223], v[182:185], v[52:55]
	v_mfma_f32_16x16x32_bf16 v[48:51], v[228:231], v[182:185], v[48:51]
	v_mfma_f32_16x16x32_bf16 v[36:39], v[220:223], v[196:199], v[36:39]
	v_mfma_f32_16x16x32_bf16 v[32:35], v[228:231], v[196:199], v[32:35]
	v_mfma_f32_16x16x32_bf16 v[20:23], v[220:223], v[204:207], v[20:23]
	v_mfma_f32_16x16x32_bf16 v[16:19], v[228:231], v[204:207], v[16:19]
	v_mfma_f32_16x16x32_bf16 v[4:7], v[220:223], v[212:215], v[4:7]
	v_mfma_f32_16x16x32_bf16 v[0:3], v[228:231], v[212:215], v[0:3]
	s_add_i32 s78, s78, 2
	s_add_u32 s0, s0, 0x100
	s_addc_u32 s1, s1, 0
	s_add_u32 s76, s76, 0x100
	s_addc_u32 s77, s77, 0
	s_cmp_gt_u32 s78, 13
	s_cbranch_scc0 .Lrot_904
	s_barrier
	v_lshl_add_u32 v146, s6, 8, v161
	v_or_b32_e32 v164, 16, v146
	v_ashrrev_i32_e32 v165, 31, v164
	v_lshlrev_b64 v[148:149], 6, v[164:165]
	v_or_b32_e32 v158, 32, v146
	v_lshl_add_u64 v[148:149], v[136:137], 0, v[148:149]
	v_ashrrev_i32_e32 v159, 31, v158
	v_or_b32_e32 v156, 48, v146
	global_load_dwordx4 v[174:177], v[148:149], off
	v_lshlrev_b64 v[148:149], 6, v[158:159]
	v_ashrrev_i32_e32 v157, 31, v156
	v_add_u32_e32 v154, 0x80, v146
	v_lshl_add_u64 v[148:149], v[136:137], 0, v[148:149]
	v_lshlrev_b64 v[150:151], 6, v[156:157]
	v_ashrrev_i32_e32 v155, 31, v154
	v_lshl_add_u64 v[150:151], v[136:137], 0, v[150:151]
	global_load_dwordx4 v[178:181], v[148:149], off
	global_load_dwordx4 v[182:185], v[150:151], off
	v_lshlrev_b64 v[148:149], 6, v[154:155]
	v_lshl_add_u64 v[148:149], v[136:137], 0, v[148:149]
	global_load_dwordx4 v[186:189], v[148:149], off
	v_ashrrev_i32_e32 v147, 31, v146
	v_lshlrev_b64 v[148:149], 6, v[146:147]
	v_add_u32_e32 v152, 0x90, v146
	v_lshl_add_u64 v[148:149], v[136:137], 0, v[148:149]
	v_ashrrev_i32_e32 v153, 31, v152
	global_load_dwordx4 v[196:199], v[148:149], off
	v_lshlrev_b64 v[148:149], 6, v[152:153]
	v_lshl_add_u64 v[148:149], v[136:137], 0, v[148:149]
	global_load_dwordx4 v[200:203], v[148:149], off
	v_add_u32_e32 v148, 0xa0, v146
	v_ashrrev_i32_e32 v149, 31, v148
	v_lshlrev_b64 v[150:151], 6, v[148:149]
	v_lshl_add_u64 v[150:151], v[136:137], 0, v[150:151]
	global_load_dwordx4 v[204:207], v[150:151], off
	v_add_u32_e32 v150, 0xb0, v146
	v_ashrrev_i32_e32 v151, 31, v150
	v_lshlrev_b64 v[208:209], 6, v[150:151]
	v_lshl_add_u64 v[208:209], v[136:137], 0, v[208:209]
	global_load_dwordx4 v[208:211], v[208:209], off
	v_and_b32_e32 v149, 64, v173
	v_xor_b32_e32 v147, 16, v173
	v_add_u32_e32 v149, 64, v149
	v_cmp_lt_i32_e32 vcc, v147, v149
	v_xor_b32_e32 v153, 32, v173
	v_mov_b64_e32 v[190:191], s[12:13]
	v_cndmask_b32_e32 v147, v173, v147, vcc
	v_lshlrev_b32_e32 v147, 2, v147
	v_cmp_lt_i32_e32 vcc, v153, v149
	s_waitcnt vmcnt(0)
	v_mov_b32_e32 v212, v175
	v_mov_b32_e32 v213, v176
	v_mov_b32_e32 v175, v177
	v_pk_add_f32 v[174:175], v[212:213], v[174:175]
	v_cndmask_b32_e32 v149, v173, v153, vcc
	v_lshlrev_b32_e32 v149, 2, v149
	v_mov_b32_e32 v176, v179
	v_mov_b32_e32 v177, v180
	v_mov_b32_e32 v179, v181
	v_mov_b32_e32 v180, v183
	v_mov_b32_e32 v181, v184
	v_mov_b32_e32 v183, v185
	v_mov_b32_e32 v184, v187
	v_mov_b32_e32 v185, v188
	v_mov_b32_e32 v187, v189
	v_pk_add_f32 v[176:177], v[176:177], v[178:179]
	v_pk_add_f32 v[178:179], v[180:181], v[182:183]
	v_pk_add_f32 v[180:181], v[184:185], v[186:187]
	v_mov_b32_e32 v182, v176
	v_mov_b32_e32 v183, v174
	v_mov_b32_e32 v174, v177
	v_mov_b32_e32 v176, v180
	v_mov_b32_e32 v177, v178
	v_mov_b32_e32 v178, v181
	v_pk_add_f32 v[174:175], v[182:183], v[174:175]
	v_pk_add_f32 v[176:177], v[176:177], v[178:179]
	ds_bpermute_b32 v179, v147, v175
	ds_bpermute_b32 v178, v147, v174
	ds_bpermute_b32 v181, v147, v177
	ds_bpermute_b32 v180, v147, v176
	v_mov_b32_e32 v184, v201
	v_mov_b32_e32 v185, v202
	s_waitcnt lgkmcnt(0)
	v_pk_add_f32 v[174:175], v[174:175], v[178:179]
	ds_bpermute_b32 v179, v149, v175
	v_pk_add_f32 v[176:177], v[176:177], v[180:181]
	ds_bpermute_b32 v178, v149, v174
	ds_bpermute_b32 v181, v149, v177
	ds_bpermute_b32 v180, v149, v176
	v_mov_b32_e32 v201, v203
	v_mov_b32_e32 v182, v197
	s_waitcnt lgkmcnt(2)
	v_pk_add_f32 v[174:175], v[174:175], v[178:179]
	v_pk_add_f32 v[178:179], v[184:185], v[200:201]
	s_waitcnt lgkmcnt(0)
	v_pk_add_f32 v[176:177], v[176:177], v[180:181]
	v_pk_fma_f32 v[174:175], v[174:175], s[10:11], v[190:191] op_sel_hi:[1,0,0]
	v_mov_b32_e32 v180, v205
	v_mov_b32_e32 v181, v206
	v_mov_b32_e32 v205, v207
	v_mul_f32_e32 v151, 0x4b800000, v175
	v_cmp_gt_f32_e32 vcc, s65, v175
	v_pk_add_f32 v[180:181], v[180:181], v[204:205]
	v_mov_b32_e32 v185, v178
	v_cndmask_b32_e32 v151, v175, v151, vcc
	v_mov_b32_e32 v184, v180
	v_mov_b32_e32 v178, v181
	v_rsq_f32_e32 v151, v151
	v_pk_add_f32 v[178:179], v[184:185], v[178:179]
	ds_bpermute_b32 v181, v147, v179
	ds_bpermute_b32 v180, v147, v178
	v_pk_fma_f32 v[176:177], v[176:177], s[10:11], v[190:191] op_sel_hi:[1,0,0]
	v_mul_f32_e32 v153, 0x4b800000, v174
	v_cmp_gt_f32_e64 s[0:1], s65, v174
	v_mul_f32_e32 v157, 0x45800000, v151
	v_mul_f32_e32 v155, 0x4b800000, v177
	v_cndmask_b32_e64 v153, v174, v153, s[0:1]
	v_cmp_gt_f32_e64 s[6:7], s65, v177
	v_cndmask_b32_e32 v174, v151, v157, vcc
	v_mul_f32_e32 v151, 0x4b800000, v176
	v_cmp_gt_f32_e32 vcc, s65, v176
	v_cndmask_b32_e64 v155, v177, v155, s[6:7]
	v_rsq_f32_e32 v153, v153
	v_cndmask_b32_e32 v151, v176, v151, vcc
	s_waitcnt lgkmcnt(0)
	v_pk_add_f32 v[176:177], v[178:179], v[180:181]
	ds_bpermute_b32 v179, v149, v177
	ds_bpermute_b32 v178, v149, v176
	v_rsq_f32_e32 v155, v155
	v_mul_f32_e32 v159, 0x45800000, v153
	v_cndmask_b32_e64 v180, v153, v159, s[0:1]
	v_rsq_f32_e32 v151, v151
	s_waitcnt lgkmcnt(0)
	v_pk_add_f32 v[176:177], v[176:177], v[178:179]
	v_mul_f32_e32 v153, 0x45800000, v155
	v_pk_fma_f32 v[176:177], v[176:177], s[10:11], v[190:191] op_sel_hi:[1,0,0]
	v_cndmask_b32_e64 v170, v155, v153, s[6:7]
	v_mul_f32_e32 v155, 0x4b800000, v177
	v_cmp_gt_f32_e64 s[0:1], s65, v177
	v_mul_f32_e32 v157, 0x4b800000, v176
	v_cmp_gt_f32_e64 s[6:7], s65, v176
	v_cndmask_b32_e64 v155, v177, v155, s[0:1]
	v_rsq_f32_e32 v155, v155
	v_cndmask_b32_e64 v157, v176, v157, s[6:7]
	v_rsq_f32_e32 v157, v157
	v_mul_f32_e32 v153, 0x45800000, v151
	v_cndmask_b32_e32 v168, v151, v153, vcc
	v_mul_f32_e32 v151, 0x45800000, v155
	v_mov_b32_e32 v183, v198
	v_mov_b32_e32 v197, v199
	v_cndmask_b32_e64 v166, v155, v151, s[0:1]
	v_mul_f32_e32 v151, 0x45800000, v157
	v_mov_b32_e32 v176, v209
	v_mov_b32_e32 v177, v210
	v_mov_b32_e32 v209, v211
	v_pk_add_f32 v[182:183], v[182:183], v[196:197]
	v_cndmask_b32_e64 v162, v157, v151, s[6:7]
	v_pk_add_f32 v[176:177], v[176:177], v[208:209]
	v_mov_b32_e32 v178, v182
	v_mov_b32_e32 v179, v176
	v_mov_b32_e32 v176, v183
	v_pk_add_f32 v[176:177], v[178:179], v[176:177]
	ds_bpermute_b32 v178, v147, v176
	ds_bpermute_b32 v179, v147, v177
	v_lshl_or_b32 v182, s66, 8, v167
	v_pk_mul_f32 v[100:101], v[100:101], v[174:175] op_sel_hi:[1,0]
	v_pk_mul_f32 v[108:109], v[108:109], v[174:175] op_sel_hi:[1,0]
	v_ashrrev_i32_e32 v183, 31, v182
	s_waitcnt lgkmcnt(0)
	v_pk_add_f32 v[176:177], v[176:177], v[178:179]
	ds_bpermute_b32 v178, v149, v176
	ds_bpermute_b32 v179, v149, v177
	v_pk_mul_f32 v[96:97], v[96:97], v[174:175] op_sel_hi:[1,0]
	v_pk_mul_f32 v[102:103], v[102:103], v[174:175] op_sel_hi:[1,0]
	v_pk_mul_f32 v[110:111], v[110:111], v[174:175] op_sel_hi:[1,0]
	v_cvt_pk_bf16_f32 v108, v108, v109
	s_waitcnt lgkmcnt(0)
	v_pk_add_f32 v[176:177], v[176:177], v[178:179]
	v_pk_mul_f32 v[106:107], v[106:107], v[174:175] op_sel_hi:[1,0]
	v_pk_fma_f32 v[176:177], v[176:177], s[10:11], v[190:191] op_sel_hi:[1,0,0]
	v_pk_mul_f32 v[104:105], v[104:105], v[174:175] op_sel_hi:[1,0]
	v_mul_f32_e32 v147, 0x4b800000, v177
	v_cmp_gt_f32_e32 vcc, s65, v177
	v_mul_f32_e32 v149, 0x4b800000, v176
	v_cmp_gt_f32_e64 s[0:1], s65, v176
	v_cndmask_b32_e32 v147, v177, v147, vcc
	v_rsq_f32_e32 v147, v147
	v_cndmask_b32_e64 v149, v176, v149, s[0:1]
	v_rsq_f32_e32 v149, v149
	v_cvt_pk_bf16_f32 v100, v100, v101
	v_mul_f32_e32 v151, 0x45800000, v147
	v_cndmask_b32_e32 v160, v147, v151, vcc
	v_mul_f32_e32 v147, 0x45800000, v149
	v_cndmask_b32_e64 v176, v149, v147, s[0:1]
	v_pk_mul_f32 v[112:113], v[112:113], v[176:177] op_sel_hi:[1,0]
	v_pk_mul_f32 v[116:117], v[116:117], v[176:177] op_sel_hi:[1,0]
	v_pk_mul_f32 v[124:125], v[124:125], v[176:177] op_sel_hi:[1,0]
	v_pk_mul_f32 v[122:123], v[122:123], v[176:177] op_sel_hi:[1,0]
	v_pk_mul_f32 v[120:121], v[120:121], v[176:177] op_sel_hi:[1,0]
	v_pk_mul_f32 v[114:115], v[114:115], v[176:177] op_sel_hi:[1,0]
	v_pk_mul_f32 v[118:119], v[118:119], v[176:177] op_sel_hi:[1,0]
	v_pk_mul_f32 v[126:127], v[126:127], v[176:177] op_sel_hi:[1,0]
	v_cvt_pk_bf16_f32 v124, v124, v125
	v_cvt_pk_bf16_f32 v120, v120, v121
	v_cvt_pk_bf16_f32 v121, v122, v123
	v_cvt_pk_bf16_f32 v122, v116, v117
	v_cvt_pk_bf16_f32 v112, v112, v113
	v_cvt_pk_bf16_f32 v125, v126, v127
	v_cvt_pk_bf16_f32 v118, v118, v119
	v_cvt_pk_bf16_f32 v113, v114, v115
	v_cndmask_b32_e64 v114, v124, v122, s[2:3]
	v_mov_b32_e32 v123, 0
	v_cndmask_b32_e64 v115, v120, v112, s[2:3]
	v_mov_b32_e32 v126, 0
	v_mov_b32_dpp v123, v114 row_ror:8 row_mask:0xf bank_mask:0xf
	v_cndmask_b32_e64 v114, v125, v118, s[2:3]
	v_mov_b32_e32 v119, 0
	v_mov_b32_dpp v126, v115 row_ror:8 row_mask:0xf bank_mask:0xf
	v_mov_b32_e32 v127, 0
	v_mov_b32_dpp v119, v114 row_ror:8 row_mask:0xf bank_mask:0xf
	v_cndmask_b32_e64 v114, v121, v113, s[2:3]
	v_cndmask_b32_e64 v116, v126, v120, s[2:3]
	v_cndmask_b32_e64 v120, v112, v126, s[2:3]
	v_add_u32_e32 v112, -8, v146
	v_mov_b32_dpp v127, v114 row_ror:8 row_mask:0xf bank_mask:0xf
	v_cndmask_b32_e64 v112, v112, v146, s[2:3]
	v_cndmask_b32_e64 v117, v127, v121, s[2:3]
	v_cndmask_b32_e64 v121, v113, v127, s[2:3]
	v_ashrrev_i32_e32 v113, 31, v112
	v_lshlrev_b64 v[112:113], 10, v[112:113]
	v_cndmask_b32_e64 v115, v119, v125, s[2:3]
	v_cndmask_b32_e64 v114, v123, v124, s[2:3]
	v_cndmask_b32_e64 v119, v118, v119, s[2:3]
	v_cndmask_b32_e64 v118, v122, v123, s[2:3]
	v_lshl_add_u64 v[122:123], s[38:39], 0, v[112:113]
	v_lshlrev_b64 v[112:113], 1, v[182:183]
	v_pk_mul_f32 v[98:99], v[98:99], v[174:175] op_sel_hi:[1,0]
	v_cvt_pk_bf16_f32 v109, v110, v111
	v_cvt_pk_bf16_f32 v104, v104, v105
	v_cvt_pk_bf16_f32 v105, v106, v107
	v_cvt_pk_bf16_f32 v101, v102, v103
	v_cvt_pk_bf16_f32 v102, v96, v97
	v_cndmask_b32_e64 v96, v108, v100, s[2:3]
	v_mov_b32_e32 v106, 0
	v_lshl_add_u64 v[122:123], v[122:123], 0, v[112:113]
	v_cvt_pk_bf16_f32 v103, v98, v99
	v_mov_b32_dpp v106, v96 row_ror:8 row_mask:0xf bank_mask:0xf
	v_cndmask_b32_e64 v96, v109, v101, s[2:3]
	v_mov_b32_e32 v107, 0
	v_cndmask_b32_e64 v97, v104, v102, s[2:3]
	v_mov_b32_e32 v110, 0
	global_store_dwordx4 v[122:123], v[114:117], off
	v_mov_b32_dpp v107, v96 row_ror:8 row_mask:0xf bank_mask:0xf
	v_cndmask_b32_e64 v96, v105, v103, s[2:3]
	v_add_u32_e32 v116, 8, v146
	v_mov_b32_dpp v110, v97 row_ror:8 row_mask:0xf bank_mask:0xf
	v_mov_b32_e32 v111, 0
	v_cndmask_b32_e64 v114, v146, v116, s[2:3]
	v_cndmask_b32_e64 v98, v110, v104, s[2:3]
	v_mov_b32_dpp v111, v96 row_ror:8 row_mask:0xf bank_mask:0xf
	v_cndmask_b32_e64 v104, v116, v164, s[2:3]
	v_ashrrev_i32_e32 v115, 31, v114
	v_cndmask_b32_e64 v99, v111, v105, s[2:3]
	v_ashrrev_i32_e32 v105, 31, v104
	v_pk_mul_f32 v[84:85], v[84:85], v[180:181] op_sel_hi:[1,0]
	v_pk_mul_f32 v[92:93], v[92:93], v[180:181] op_sel_hi:[1,0]
	v_lshlrev_b64 v[114:115], 10, v[114:115]
	v_lshlrev_b64 v[104:105], 10, v[104:105]
	v_pk_mul_f32 v[80:81], v[80:81], v[180:181] op_sel_hi:[1,0]
	v_pk_mul_f32 v[86:87], v[86:87], v[180:181] op_sel_hi:[1,0]
	v_pk_mul_f32 v[94:95], v[94:95], v[180:181] op_sel_hi:[1,0]
	v_cvt_pk_bf16_f32 v92, v92, v93
	v_pk_mul_f32 v[90:91], v[90:91], v[180:181] op_sel_hi:[1,0]
	v_pk_mul_f32 v[88:89], v[88:89], v[180:181] op_sel_hi:[1,0]
	v_cvt_pk_bf16_f32 v84, v84, v85
	v_lshl_add_u64 v[114:115], s[38:39], 0, v[114:115]
	v_lshl_add_u64 v[104:105], s[38:39], 0, v[104:105]
	v_pk_mul_f32 v[82:83], v[82:83], v[180:181] op_sel_hi:[1,0]
	v_cvt_pk_bf16_f32 v93, v94, v95
	v_cvt_pk_bf16_f32 v88, v88, v89
	v_cvt_pk_bf16_f32 v89, v90, v91
	v_cvt_pk_bf16_f32 v85, v86, v87
	v_cvt_pk_bf16_f32 v86, v80, v81
	v_cndmask_b32_e64 v80, v92, v84, s[2:3]
	v_mov_b32_e32 v90, 0
	v_lshl_add_u64 v[114:115], v[114:115], 0, v[112:113]
	v_cndmask_b32_e64 v97, v107, v109, s[2:3]
	v_cndmask_b32_e64 v96, v106, v108, s[2:3]
	v_lshl_add_u64 v[104:105], v[104:105], 0, v[112:113]
	v_cvt_pk_bf16_f32 v87, v82, v83
	v_mov_b32_dpp v90, v80 row_ror:8 row_mask:0xf bank_mask:0xf
	v_cndmask_b32_e64 v80, v93, v85, s[2:3]
	v_mov_b32_e32 v91, 0
	v_cndmask_b32_e64 v81, v88, v86, s[2:3]
	v_mov_b32_e32 v94, 0
	global_store_dwordx4 v[114:115], v[118:121], off
	global_store_dwordx4 v[104:105], v[96:99], off
	v_mov_b32_dpp v91, v80 row_ror:8 row_mask:0xf bank_mask:0xf
	v_cndmask_b32_e64 v80, v89, v87, s[2:3]
	v_add_u32_e32 v98, 24, v146
	v_mov_b32_dpp v94, v81 row_ror:8 row_mask:0xf bank_mask:0xf
	v_mov_b32_e32 v95, 0
	v_cndmask_b32_e64 v96, v164, v98, s[2:3]
	v_cndmask_b32_e64 v82, v94, v88, s[2:3]
	v_mov_b32_dpp v95, v80 row_ror:8 row_mask:0xf bank_mask:0xf
	v_cndmask_b32_e64 v88, v98, v158, s[2:3]
	v_ashrrev_i32_e32 v97, 31, v96
	v_cndmask_b32_e64 v83, v95, v89, s[2:3]
	v_ashrrev_i32_e32 v89, 31, v88
	v_pk_mul_f32 v[68:69], v[68:69], v[170:171] op_sel_hi:[1,0]
	v_pk_mul_f32 v[76:77], v[76:77], v[170:171] op_sel_hi:[1,0]
	v_lshlrev_b64 v[96:97], 10, v[96:97]
	v_lshlrev_b64 v[88:89], 10, v[88:89]
	v_pk_mul_f32 v[64:65], v[64:65], v[170:171] op_sel_hi:[1,0]
	v_pk_mul_f32 v[70:71], v[70:71], v[170:171] op_sel_hi:[1,0]
	v_pk_mul_f32 v[78:79], v[78:79], v[170:171] op_sel_hi:[1,0]
	v_cvt_pk_bf16_f32 v76, v76, v77
	v_pk_mul_f32 v[74:75], v[74:75], v[170:171] op_sel_hi:[1,0]
	v_pk_mul_f32 v[72:73], v[72:73], v[170:171] op_sel_hi:[1,0]
	v_cvt_pk_bf16_f32 v68, v68, v69
	v_lshl_add_u64 v[96:97], s[38:39], 0, v[96:97]
	v_lshl_add_u64 v[88:89], s[38:39], 0, v[88:89]
	v_pk_mul_f32 v[66:67], v[66:67], v[170:171] op_sel_hi:[1,0]
	v_cvt_pk_bf16_f32 v77, v78, v79
	v_cvt_pk_bf16_f32 v72, v72, v73
	v_cvt_pk_bf16_f32 v73, v74, v75
	v_cvt_pk_bf16_f32 v69, v70, v71
	v_cvt_pk_bf16_f32 v70, v64, v65
	v_cndmask_b32_e64 v64, v76, v68, s[2:3]
	v_mov_b32_e32 v74, 0
	v_cndmask_b32_e64 v103, v103, v111, s[2:3]
	v_cndmask_b32_e64 v102, v102, v110, s[2:3]
	v_cndmask_b32_e64 v101, v101, v107, s[2:3]
	v_cndmask_b32_e64 v100, v100, v106, s[2:3]
	v_lshl_add_u64 v[96:97], v[96:97], 0, v[112:113]
	v_cndmask_b32_e64 v81, v91, v93, s[2:3]
	v_cndmask_b32_e64 v80, v90, v92, s[2:3]
	v_lshl_add_u64 v[88:89], v[88:89], 0, v[112:113]
	v_cvt_pk_bf16_f32 v71, v66, v67
	v_mov_b32_dpp v74, v64 row_ror:8 row_mask:0xf bank_mask:0xf
	v_cndmask_b32_e64 v64, v77, v69, s[2:3]
	v_mov_b32_e32 v75, 0
	v_cndmask_b32_e64 v65, v72, v70, s[2:3]
	v_mov_b32_e32 v78, 0
	global_store_dwordx4 v[96:97], v[100:103], off
	global_store_dwordx4 v[88:89], v[80:83], off
	v_mov_b32_dpp v75, v64 row_ror:8 row_mask:0xf bank_mask:0xf
	v_cndmask_b32_e64 v64, v73, v71, s[2:3]
	v_add_u32_e32 v82, 40, v146
	v_mov_b32_dpp v78, v65 row_ror:8 row_mask:0xf bank_mask:0xf
	v_mov_b32_e32 v79, 0
	v_cndmask_b32_e64 v80, v158, v82, s[2:3]
	v_cndmask_b32_e64 v66, v78, v72, s[2:3]
	v_mov_b32_dpp v79, v64 row_ror:8 row_mask:0xf bank_mask:0xf
	v_cndmask_b32_e64 v72, v82, v156, s[2:3]
	v_ashrrev_i32_e32 v81, 31, v80
	v_cndmask_b32_e64 v67, v79, v73, s[2:3]
	v_ashrrev_i32_e32 v73, 31, v72
	v_pk_mul_f32 v[48:49], v[48:49], v[168:169] op_sel_hi:[1,0]
	v_pk_mul_f32 v[54:55], v[54:55], v[168:169] op_sel_hi:[1,0]
	v_pk_mul_f32 v[52:53], v[52:53], v[168:169] op_sel_hi:[1,0]
	v_pk_mul_f32 v[60:61], v[60:61], v[168:169] op_sel_hi:[1,0]
	v_pk_mul_f32 v[56:57], v[56:57], v[168:169] op_sel_hi:[1,0]
	v_lshlrev_b64 v[80:81], 10, v[80:81]
	v_lshlrev_b64 v[72:73], 10, v[72:73]
	v_pk_mul_f32 v[62:63], v[62:63], v[168:169] op_sel_hi:[1,0]
	v_cvt_pk_bf16_f32 v60, v60, v61
	v_pk_mul_f32 v[58:59], v[58:59], v[168:169] op_sel_hi:[1,0]
	v_cvt_pk_bf16_f32 v56, v56, v57
	v_cvt_pk_bf16_f32 v52, v52, v53
	v_cvt_pk_bf16_f32 v53, v54, v55
	v_cvt_pk_bf16_f32 v54, v48, v49
	v_lshl_add_u64 v[80:81], s[38:39], 0, v[80:81]
	v_lshl_add_u64 v[72:73], s[38:39], 0, v[72:73]
	v_pk_mul_f32 v[50:51], v[50:51], v[168:169] op_sel_hi:[1,0]
	v_cvt_pk_bf16_f32 v61, v62, v63
	v_cvt_pk_bf16_f32 v57, v58, v59
	v_cndmask_b32_e64 v48, v60, v52, s[2:3]
	v_mov_b32_e32 v58, 0
	v_cndmask_b32_e64 v49, v56, v54, s[2:3]
	v_mov_b32_e32 v62, 0
	v_cndmask_b32_e64 v87, v87, v95, s[2:3]
	v_cndmask_b32_e64 v86, v86, v94, s[2:3]
	v_cndmask_b32_e64 v85, v85, v91, s[2:3]
	v_cndmask_b32_e64 v84, v84, v90, s[2:3]
	v_lshl_add_u64 v[80:81], v[80:81], 0, v[112:113]
	v_cndmask_b32_e64 v65, v75, v77, s[2:3]
	v_cndmask_b32_e64 v64, v74, v76, s[2:3]
	v_lshl_add_u64 v[72:73], v[72:73], 0, v[112:113]
	v_cvt_pk_bf16_f32 v55, v50, v51
	v_mov_b32_dpp v58, v48 row_ror:8 row_mask:0xf bank_mask:0xf
	v_cndmask_b32_e64 v48, v61, v53, s[2:3]
	v_mov_b32_e32 v59, 0
	v_mov_b32_dpp v62, v49 row_ror:8 row_mask:0xf bank_mask:0xf
	global_store_dwordx4 v[80:81], v[84:87], off
	global_store_dwordx4 v[72:73], v[64:67], off
	v_mov_b32_dpp v59, v48 row_ror:8 row_mask:0xf bank_mask:0xf
	v_cndmask_b32_e64 v48, v57, v55, s[2:3]
	v_add_u32_e32 v64, 56, v146
	v_mov_b32_e32 v63, 0
	v_cndmask_b32_e64 v50, v62, v56, s[2:3]
	v_add_u32_e32 v56, 0x78, v146
	v_cndmask_b32_e64 v64, v156, v64, s[2:3]
	v_mov_b32_dpp v63, v48 row_ror:8 row_mask:0xf bank_mask:0xf
	v_cndmask_b32_e64 v56, v56, v154, s[2:3]
	v_ashrrev_i32_e32 v65, 31, v64
	v_cndmask_b32_e64 v51, v63, v57, s[2:3]
	v_ashrrev_i32_e32 v57, 31, v56
	v_pk_mul_f32 v[36:37], v[36:37], v[166:167] op_sel_hi:[1,0]
	v_pk_mul_f32 v[44:45], v[44:45], v[166:167] op_sel_hi:[1,0]
	v_lshlrev_b64 v[64:65], 10, v[64:65]
	v_lshlrev_b64 v[56:57], 10, v[56:57]
	v_pk_mul_f32 v[32:33], v[32:33], v[166:167] op_sel_hi:[1,0]
	v_pk_mul_f32 v[38:39], v[38:39], v[166:167] op_sel_hi:[1,0]
	v_pk_mul_f32 v[46:47], v[46:47], v[166:167] op_sel_hi:[1,0]
	v_cvt_pk_bf16_f32 v44, v44, v45
	v_pk_mul_f32 v[42:43], v[42:43], v[166:167] op_sel_hi:[1,0]
	v_pk_mul_f32 v[40:41], v[40:41], v[166:167] op_sel_hi:[1,0]
	v_cvt_pk_bf16_f32 v36, v36, v37
	v_lshl_add_u64 v[64:65], s[38:39], 0, v[64:65]
	v_lshl_add_u64 v[56:57], s[38:39], 0, v[56:57]
	v_pk_mul_f32 v[34:35], v[34:35], v[166:167] op_sel_hi:[1,0]
	v_cvt_pk_bf16_f32 v45, v46, v47
	v_cvt_pk_bf16_f32 v40, v40, v41
	v_cvt_pk_bf16_f32 v41, v42, v43
	v_cvt_pk_bf16_f32 v37, v38, v39
	v_cvt_pk_bf16_f32 v38, v32, v33
	v_cndmask_b32_e64 v32, v44, v36, s[2:3]
	v_mov_b32_e32 v42, 0
	v_cndmask_b32_e64 v71, v71, v79, s[2:3]
	v_cndmask_b32_e64 v70, v70, v78, s[2:3]
	v_cndmask_b32_e64 v69, v69, v75, s[2:3]
	v_cndmask_b32_e64 v68, v68, v74, s[2:3]
	v_lshl_add_u64 v[64:65], v[64:65], 0, v[112:113]
	v_cndmask_b32_e64 v49, v59, v61, s[2:3]
	v_cndmask_b32_e64 v48, v58, v60, s[2:3]
	v_lshl_add_u64 v[56:57], v[56:57], 0, v[112:113]
	v_cvt_pk_bf16_f32 v39, v34, v35
	v_mov_b32_dpp v42, v32 row_ror:8 row_mask:0xf bank_mask:0xf
	v_cndmask_b32_e64 v32, v45, v37, s[2:3]
	v_mov_b32_e32 v43, 0
	v_cndmask_b32_e64 v33, v40, v38, s[2:3]
	v_mov_b32_e32 v46, 0
	global_store_dwordx4 v[64:65], v[68:71], off
	global_store_dwordx4 v[56:57], v[48:51], off
	v_mov_b32_dpp v43, v32 row_ror:8 row_mask:0xf bank_mask:0xf
	v_cndmask_b32_e64 v32, v41, v39, s[2:3]
	v_add_u32_e32 v50, 0x88, v146
	v_mov_b32_dpp v46, v33 row_ror:8 row_mask:0xf bank_mask:0xf
	v_mov_b32_e32 v47, 0
	v_cndmask_b32_e64 v34, v46, v40, s[2:3]
	v_cndmask_b32_e64 v40, v50, v152, s[2:3]
	v_mov_b32_dpp v47, v32 row_ror:8 row_mask:0xf bank_mask:0xf
	v_cndmask_b32_e64 v35, v47, v41, s[2:3]
	v_ashrrev_i32_e32 v41, 31, v40
	v_pk_mul_f32 v[20:21], v[20:21], v[162:163] op_sel_hi:[1,0]
	v_pk_mul_f32 v[28:29], v[28:29], v[162:163] op_sel_hi:[1,0]
	v_lshlrev_b64 v[40:41], 10, v[40:41]
	v_pk_mul_f32 v[16:17], v[16:17], v[162:163] op_sel_hi:[1,0]
	v_pk_mul_f32 v[22:23], v[22:23], v[162:163] op_sel_hi:[1,0]
	v_pk_mul_f32 v[30:31], v[30:31], v[162:163] op_sel_hi:[1,0]
	v_cvt_pk_bf16_f32 v28, v28, v29
	v_pk_mul_f32 v[26:27], v[26:27], v[162:163] op_sel_hi:[1,0]
	v_pk_mul_f32 v[24:25], v[24:25], v[162:163] op_sel_hi:[1,0]
	v_cvt_pk_bf16_f32 v20, v20, v21
	v_lshl_add_u64 v[40:41], s[38:39], 0, v[40:41]
	v_pk_mul_f32 v[18:19], v[18:19], v[162:163] op_sel_hi:[1,0]
	v_cvt_pk_bf16_f32 v29, v30, v31
	v_cvt_pk_bf16_f32 v24, v24, v25
	v_cvt_pk_bf16_f32 v25, v26, v27
	v_cvt_pk_bf16_f32 v21, v22, v23
	v_cvt_pk_bf16_f32 v22, v16, v17
	v_cndmask_b32_e64 v16, v28, v20, s[2:3]
	v_mov_b32_e32 v26, 0
	v_cndmask_b32_e64 v33, v43, v45, s[2:3]
	v_cndmask_b32_e64 v32, v42, v44, s[2:3]
	v_lshl_add_u64 v[40:41], v[40:41], 0, v[112:113]
	v_cvt_pk_bf16_f32 v23, v18, v19
	v_mov_b32_dpp v26, v16 row_ror:8 row_mask:0xf bank_mask:0xf
	v_cndmask_b32_e64 v16, v29, v21, s[2:3]
	v_mov_b32_e32 v27, 0
	v_cndmask_b32_e64 v17, v24, v22, s[2:3]
	v_mov_b32_e32 v30, 0
	global_store_dwordx4 v[40:41], v[32:35], off
	v_mov_b32_dpp v27, v16 row_ror:8 row_mask:0xf bank_mask:0xf
	v_cndmask_b32_e64 v16, v25, v23, s[2:3]
	v_add_u32_e32 v34, 0x98, v146
	v_mov_b32_dpp v30, v17 row_ror:8 row_mask:0xf bank_mask:0xf
	v_mov_b32_e32 v31, 0
	v_cndmask_b32_e64 v18, v30, v24, s[2:3]
	v_cndmask_b32_e64 v24, v34, v148, s[2:3]
	v_mov_b32_dpp v31, v16 row_ror:8 row_mask:0xf bank_mask:0xf
	v_cndmask_b32_e64 v19, v31, v25, s[2:3]
	v_ashrrev_i32_e32 v25, 31, v24
	v_lshlrev_b64 v[24:25], 10, v[24:25]
	v_lshl_add_u64 v[24:25], s[38:39], 0, v[24:25]
	v_cndmask_b32_e64 v17, v27, v29, s[2:3]
	v_cndmask_b32_e64 v16, v26, v28, s[2:3]
	v_lshl_add_u64 v[24:25], v[24:25], 0, v[112:113]
	global_store_dwordx4 v[24:25], v[16:19], off
	v_pk_mul_f32 v[4:5], v[4:5], v[160:161] op_sel_hi:[1,0]
	v_pk_mul_f32 v[12:13], v[12:13], v[160:161] op_sel_hi:[1,0]
	v_add_u32_e32 v18, 0xa8, v146
	v_cndmask_b32_e64 v16, v148, v18, s[2:3]
	v_ashrrev_i32_e32 v17, 31, v16
	v_pk_mul_f32 v[10:11], v[10:11], v[160:161] op_sel_hi:[1,0]
	v_pk_mul_f32 v[8:9], v[8:9], v[160:161] op_sel_hi:[1,0]
	v_lshlrev_b64 v[16:17], 10, v[16:17]
	v_pk_mul_f32 v[0:1], v[0:1], v[160:161] op_sel_hi:[1,0]
	v_pk_mul_f32 v[6:7], v[6:7], v[160:161] op_sel_hi:[1,0]
	v_pk_mul_f32 v[14:15], v[14:15], v[160:161] op_sel_hi:[1,0]
	v_cvt_pk_bf16_f32 v12, v12, v13
	v_cvt_pk_bf16_f32 v8, v8, v9
	v_cvt_pk_bf16_f32 v9, v10, v11
	v_cvt_pk_bf16_f32 v10, v4, v5
	v_lshl_add_u64 v[16:17], s[38:39], 0, v[16:17]
	v_pk_mul_f32 v[2:3], v[2:3], v[160:161] op_sel_hi:[1,0]
	v_cvt_pk_bf16_f32 v13, v14, v15
	v_cvt_pk_bf16_f32 v6, v6, v7
	v_cvt_pk_bf16_f32 v7, v0, v1
	v_cndmask_b32_e64 v0, v12, v10, s[2:3]
	v_mov_b32_e32 v14, 0
	v_cndmask_b32_e64 v4, v18, v150, s[2:3]
	v_cndmask_b32_e64 v23, v23, v31, s[2:3]
	v_cndmask_b32_e64 v22, v22, v30, s[2:3]
	v_cndmask_b32_e64 v21, v21, v27, s[2:3]
	v_cndmask_b32_e64 v20, v20, v26, s[2:3]
	v_lshl_add_u64 v[16:17], v[16:17], 0, v[112:113]
	v_cvt_pk_bf16_f32 v11, v2, v3
	v_mov_b32_dpp v14, v0 row_ror:8 row_mask:0xf bank_mask:0xf
	v_cndmask_b32_e64 v0, v13, v6, s[2:3]
	v_mov_b32_e32 v15, 0
	v_ashrrev_i32_e32 v5, 31, v4
	global_store_dwordx4 v[16:17], v[20:23], off
	v_mov_b32_dpp v15, v0 row_ror:8 row_mask:0xf bank_mask:0xf
	v_cndmask_b32_e64 v0, v9, v11, s[2:3]
	v_cndmask_b32_e64 v1, v8, v7, s[2:3]
	v_mov_b32_e32 v16, 0
	v_mov_b32_e32 v17, 0
	v_lshlrev_b64 v[4:5], 10, v[4:5]
	v_mov_b32_dpp v16, v1 row_ror:8 row_mask:0xf bank_mask:0xf
	v_mov_b32_dpp v17, v0 row_ror:8 row_mask:0xf bank_mask:0xf
	v_lshl_add_u64 v[4:5], s[38:39], 0, v[4:5]
	v_cndmask_b32_e64 v3, v17, v9, s[2:3]
	v_cndmask_b32_e64 v2, v16, v8, s[2:3]
	v_cndmask_b32_e64 v1, v15, v13, s[2:3]
	v_cndmask_b32_e64 v0, v14, v12, s[2:3]
	v_lshl_add_u64 v[4:5], v[4:5], 0, v[112:113]
	global_store_dwordx4 v[4:5], v[0:3], off
	v_cndmask_b32_e64 v48, v154, v50, s[2:3]
	v_cndmask_b32_e64 v32, v152, v34, s[2:3]
	v_add_u32_e32 v0, 0xb8, v146
	v_cndmask_b32_e64 v0, v150, v0, s[2:3]
	v_ashrrev_i32_e32 v49, 31, v48
	v_ashrrev_i32_e32 v33, 31, v32
	v_ashrrev_i32_e32 v1, 31, v0
	v_lshlrev_b64 v[48:49], 10, v[48:49]
	v_lshlrev_b64 v[32:33], 10, v[32:33]
	v_lshlrev_b64 v[0:1], 10, v[0:1]
	v_lshl_add_u64 v[48:49], s[38:39], 0, v[48:49]
	v_lshl_add_u64 v[32:33], s[38:39], 0, v[32:33]
	v_lshl_add_u64 v[0:1], s[38:39], 0, v[0:1]
	v_cndmask_b32_e64 v55, v55, v63, s[2:3]
	v_cndmask_b32_e64 v54, v54, v62, s[2:3]
	v_cndmask_b32_e64 v53, v53, v59, s[2:3]
	v_cndmask_b32_e64 v52, v52, v58, s[2:3]
	v_lshl_add_u64 v[48:49], v[48:49], 0, v[112:113]
	v_cndmask_b32_e64 v39, v39, v47, s[2:3]
	v_cndmask_b32_e64 v38, v38, v46, s[2:3]
	v_cndmask_b32_e64 v37, v37, v43, s[2:3]
	v_cndmask_b32_e64 v36, v36, v42, s[2:3]
	v_lshl_add_u64 v[32:33], v[32:33], 0, v[112:113]
	v_lshl_add_u64 v[4:5], v[0:1], 0, v[112:113]
	v_cndmask_b32_e64 v3, v11, v17, s[2:3]
	v_cndmask_b32_e64 v2, v7, v16, s[2:3]
	v_cndmask_b32_e64 v1, v6, v15, s[2:3]
	v_cndmask_b32_e64 v0, v10, v14, s[2:3]
	s_and_b64 vcc, exec, s[4:5]
	s_mov_b32 s66, s36
	s_mov_b32 s6, s44
	s_mov_b64 s[50:51], s[48:49]
	s_mov_b64 s[52:53], s[46:47]
	global_store_dwordx4 v[48:49], v[52:55], off
	global_store_dwordx4 v[32:33], v[36:39], off
	global_store_dwordx4 v[4:5], v[0:3], off
	s_cbranch_vccz .LBB0_897
	s_waitcnt vmcnt(0)
	s_cmpk_gt_u32 s11, 0xff
	s_cbranch_scc1 .LBB0_908
	s_barrier

.LBB0_996:
	s_ashr_i32 s41, s40, 31
	v_cmp_lt_i64_e32 vcc, s[44:45], v[148:149]
	s_lshl_b64 s[44:45], s[40:41], 18
	s_add_u32 s44, s74, s44
	s_addc_u32 s45, s75, s45
	s_and_b64 s[46:47], vcc, exec
	s_cselect_b32 s9, s45, s49
	s_cselect_b32 s41, s44, s48
	s_ashr_i32 s39, s38, 31
	s_lshl_b64 s[46:47], s[38:39], 18
	s_add_u32 s46, s72, s46
	s_addc_u32 s47, s73, s47
	s_and_b64 s[52:53], vcc, exec
	s_cselect_b32 s39, s47, s51
	s_cselect_b32 s76, s46, s50
	s_add_u32 s48, s48, 0x20080
	s_addc_u32 s49, s49, 0
	s_add_u32 s77, s50, 0x100
	v_mov_b32_e32 v0, 0
	s_addc_u32 s78, s51, 0
	s_mov_b32 s79, -2
	s_waitcnt lgkmcnt(0)
	v_mov_b64_e32 v[0:1], 0
	v_mov_b64_e32 v[2:3], 0
	v_mov_b64_e32 v[4:5], 0
	v_mov_b64_e32 v[6:7], 0
	v_mov_b64_e32 v[8:9], 0
	v_mov_b64_e32 v[10:11], 0
	v_mov_b64_e32 v[12:13], 0
	v_mov_b64_e32 v[14:15], 0
	v_mov_b64_e32 v[16:17], 0
	v_mov_b64_e32 v[18:19], 0
	v_mov_b64_e32 v[20:21], 0
	v_mov_b64_e32 v[22:23], 0
	v_mov_b64_e32 v[24:25], 0
	v_mov_b64_e32 v[26:27], 0
	v_mov_b64_e32 v[28:29], 0
	v_mov_b64_e32 v[30:31], 0
	v_mov_b64_e32 v[32:33], 0
	v_mov_b64_e32 v[34:35], 0
	v_mov_b64_e32 v[36:37], 0
	v_mov_b64_e32 v[38:39], 0
	v_mov_b64_e32 v[40:41], 0
	v_mov_b64_e32 v[42:43], 0
	v_mov_b64_e32 v[44:45], 0
	v_mov_b64_e32 v[46:47], 0
	v_mov_b64_e32 v[48:49], 0
	v_mov_b64_e32 v[50:51], 0
	v_mov_b64_e32 v[52:53], 0
	v_mov_b64_e32 v[54:55], 0
	v_mov_b64_e32 v[56:57], 0
	v_mov_b64_e32 v[58:59], 0
	v_mov_b64_e32 v[60:61], 0
	v_mov_b64_e32 v[62:63], 0
	v_mov_b64_e32 v[64:65], 0
	v_mov_b64_e32 v[66:67], 0
	v_mov_b64_e32 v[68:69], 0
	v_mov_b64_e32 v[70:71], 0
	v_mov_b64_e32 v[72:73], 0
	v_mov_b64_e32 v[74:75], 0
	v_mov_b64_e32 v[76:77], 0
	v_mov_b64_e32 v[78:79], 0
	v_mov_b64_e32 v[80:81], 0
	v_mov_b64_e32 v[82:83], 0
	v_mov_b64_e32 v[84:85], 0
	v_mov_b64_e32 v[86:87], 0
	v_mov_b64_e32 v[88:89], 0
	v_mov_b64_e32 v[90:91], 0
	v_mov_b64_e32 v[92:93], 0
	v_mov_b64_e32 v[94:95], 0
	v_mov_b64_e32 v[96:97], 0
	v_mov_b64_e32 v[98:99], 0
	v_mov_b64_e32 v[100:101], 0
	v_mov_b64_e32 v[102:103], 0
	v_mov_b64_e32 v[104:105], 0
	v_mov_b64_e32 v[106:107], 0
	v_mov_b64_e32 v[108:109], 0
	v_mov_b64_e32 v[110:111], 0
	v_mov_b64_e32 v[112:113], 0
	v_mov_b64_e32 v[114:115], 0
	v_mov_b64_e32 v[116:117], 0
	v_mov_b64_e32 v[118:119], 0
	v_mov_b64_e32 v[120:121], 0
	v_mov_b64_e32 v[122:123], 0
	v_mov_b64_e32 v[124:125], 0
	v_mov_b64_e32 v[126:127], 0
	s_branch .LBB0_997

.LBB0_997:
	ds_read_b128 v[128:131], v164
	ds_read_b128 v[132:135], v164 offset:1024
	ds_read_b128 v[152:155], v164 offset:2048
	ds_read_b128 v[156:159], v164 offset:3072
	s_add_u32 s28, s48, 0xfffe0080
	s_addc_u32 s29, s49, -1
	s_cmp_eq_u32 s79, 4
	s_cselect_b32 s53, s9, s29
	s_cselect_b32 s52, s41, s28
	s_cselect_b32 s51, s39, s78
	s_cselect_b32 s50, s76, s77
	v_lshl_add_u64 v[204:205], s[48:49], 0, v[144:145]
	s_add_i32 m0, s55, 0xc000
	ds_read_b128 v[168:171], v165
	ds_read_b128 v[172:175], v165 offset:1024
	ds_read_b128 v[176:179], v165 offset:2048
	ds_read_b128 v[180:183], v165 offset:3072
	ds_read_b128 v[184:187], v165 offset:4096
	ds_read_b128 v[188:191], v165 offset:5120
	ds_read_b128 v[196:199], v165 offset:6144
	ds_read_b128 v[200:203], v165 offset:7168
	global_load_lds_dwordx4 v[204:205], off
	v_lshl_add_u64 v[204:205], s[48:49], 0, v[146:147]
	s_add_i32 m0, s55, 0xe000
	s_nop 0
	global_load_lds_dwordx4 v[204:205], off
	s_waitcnt lgkmcnt(8)
	s_barrier
	s_waitcnt lgkmcnt(0)
	s_waitcnt lgkmcnt(0)
	v_mfma_f32_16x16x32_bf16 v[124:127], v[128:131], v[168:171], v[124:127]
	v_mfma_f32_16x16x32_bf16 v[120:123], v[152:155], v[168:171], v[120:123]
	v_mfma_f32_16x16x32_bf16 v[108:111], v[128:131], v[176:179], v[108:111]
	v_mfma_f32_16x16x32_bf16 v[104:107], v[152:155], v[176:179], v[104:107]
	v_mfma_f32_16x16x32_bf16 v[92:95], v[128:131], v[184:187], v[92:95]
	v_mfma_f32_16x16x32_bf16 v[88:91], v[152:155], v[184:187], v[88:91]
	v_mfma_f32_16x16x32_bf16 v[76:79], v[128:131], v[196:199], v[76:79]
	v_mfma_f32_16x16x32_bf16 v[72:75], v[152:155], v[196:199], v[72:75]
	v_mfma_f32_16x16x32_bf16 v[124:127], v[132:135], v[172:175], v[124:127]
	v_mfma_f32_16x16x32_bf16 v[120:123], v[156:159], v[172:175], v[120:123]
	v_mfma_f32_16x16x32_bf16 v[108:111], v[132:135], v[180:183], v[108:111]
	v_mfma_f32_16x16x32_bf16 v[104:107], v[156:159], v[180:183], v[104:107]
	v_mfma_f32_16x16x32_bf16 v[92:95], v[132:135], v[188:191], v[92:95]
	v_mfma_f32_16x16x32_bf16 v[88:91], v[156:159], v[188:191], v[88:91]
	v_mfma_f32_16x16x32_bf16 v[76:79], v[132:135], v[200:203], v[76:79]
	v_mfma_f32_16x16x32_bf16 v[72:75], v[156:159], v[200:203], v[72:75]
	s_barrier
	s_add_i32 s28, s65, s54
	v_lshl_add_u64 v[220:221], s[50:51], 0, v[138:139]
	s_mov_b32 m0, s28
	ds_read_b128 v[204:207], v166
	ds_read_b128 v[208:211], v166 offset:1024
	ds_read_b128 v[212:215], v166 offset:2048
	ds_read_b128 v[216:219], v166 offset:3072
	global_load_lds_dwordx4 v[220:221], off
	v_lshl_add_u64 v[222:223], s[50:51], 0, v[142:143]
	s_add_i32 m0, s28, 0x2000
	s_nop 0
	global_load_lds_dwordx4 v[222:223], off
	s_barrier
	s_waitcnt lgkmcnt(0)
	s_waitcnt lgkmcnt(0)
	v_mfma_f32_16x16x32_bf16 v[116:119], v[204:207], v[168:171], v[116:119]
	v_mfma_f32_16x16x32_bf16 v[112:115], v[212:215], v[168:171], v[112:115]
	v_mfma_f32_16x16x32_bf16 v[100:103], v[204:207], v[176:179], v[100:103]
	v_mfma_f32_16x16x32_bf16 v[96:99], v[212:215], v[176:179], v[96:99]
	v_mfma_f32_16x16x32_bf16 v[84:87], v[204:207], v[184:187], v[84:87]
	v_mfma_f32_16x16x32_bf16 v[80:83], v[212:215], v[184:187], v[80:83]
	v_mfma_f32_16x16x32_bf16 v[68:71], v[204:207], v[196:199], v[68:71]
	v_mfma_f32_16x16x32_bf16 v[64:67], v[212:215], v[196:199], v[64:67]
	v_mfma_f32_16x16x32_bf16 v[116:119], v[208:211], v[172:175], v[116:119]
	v_mfma_f32_16x16x32_bf16 v[112:115], v[216:219], v[172:175], v[112:115]
	v_mfma_f32_16x16x32_bf16 v[100:103], v[208:211], v[180:183], v[100:103]
	v_mfma_f32_16x16x32_bf16 v[96:99], v[216:219], v[180:183], v[96:99]
	v_mfma_f32_16x16x32_bf16 v[84:87], v[208:211], v[188:191], v[84:87]
	v_mfma_f32_16x16x32_bf16 v[80:83], v[216:219], v[188:191], v[80:83]
	v_mfma_f32_16x16x32_bf16 v[68:71], v[208:211], v[200:203], v[68:71]
	v_mfma_f32_16x16x32_bf16 v[64:67], v[216:219], v[200:203], v[64:67]
	s_mov_b32 m0, s55
	v_lshl_add_u64 v[224:225], s[52:53], 0, v[136:137]
	s_barrier
	ds_read_b128 v[168:171], v165 offset:16384
	ds_read_b128 v[172:175], v165 offset:17408
	ds_read_b128 v[176:179], v165 offset:18432
	ds_read_b128 v[180:183], v165 offset:19456
	ds_read_b128 v[184:187], v165 offset:20480
	ds_read_b128 v[188:191], v165 offset:21504
	ds_read_b128 v[196:199], v165 offset:22528
	ds_read_b128 v[200:203], v165 offset:23552
	global_load_lds_dwordx4 v[224:225], off
	v_lshl_add_u64 v[226:227], s[52:53], 0, v[140:141]
	s_mov_b32 m0, s56
	s_nop 0
	global_load_lds_dwordx4 v[226:227], off
	s_barrier
	s_waitcnt lgkmcnt(0)
	s_waitcnt lgkmcnt(0)
	v_mfma_f32_16x16x32_bf16 v[60:63], v[128:131], v[168:171], v[60:63]
	v_mfma_f32_16x16x32_bf16 v[56:59], v[152:155], v[168:171], v[56:59]
	v_mfma_f32_16x16x32_bf16 v[44:47], v[128:131], v[176:179], v[44:47]
	v_mfma_f32_16x16x32_bf16 v[40:43], v[152:155], v[176:179], v[40:43]
	v_mfma_f32_16x16x32_bf16 v[28:31], v[128:131], v[184:187], v[28:31]
	v_mfma_f32_16x16x32_bf16 v[24:27], v[152:155], v[184:187], v[24:27]
	v_mfma_f32_16x16x32_bf16 v[12:15], v[128:131], v[196:199], v[12:15]
	v_mfma_f32_16x16x32_bf16 v[8:11], v[152:155], v[196:199], v[8:11]
	v_mfma_f32_16x16x32_bf16 v[60:63], v[132:135], v[172:175], v[60:63]
	v_mfma_f32_16x16x32_bf16 v[56:59], v[156:159], v[172:175], v[56:59]
	v_mfma_f32_16x16x32_bf16 v[44:47], v[132:135], v[180:183], v[44:47]
	v_mfma_f32_16x16x32_bf16 v[40:43], v[156:159], v[180:183], v[40:43]
	v_mfma_f32_16x16x32_bf16 v[28:31], v[132:135], v[188:191], v[28:31]
	v_mfma_f32_16x16x32_bf16 v[24:27], v[156:159], v[188:191], v[24:27]
	v_mfma_f32_16x16x32_bf16 v[12:15], v[132:135], v[200:203], v[12:15]
	v_mfma_f32_16x16x32_bf16 v[8:11], v[156:159], v[200:203], v[8:11]
	s_barrier
	s_add_u32 s80, s50, 0x8000
	s_addc_u32 s81, s51, 0
	s_add_i32 s28, s66, s54
	v_lshl_add_u64 v[128:129], s[80:81], 0, v[138:139]
	s_mov_b32 m0, s28
	s_nop 0
	global_load_lds_dwordx4 v[128:129], off
	v_lshl_add_u64 v[128:129], s[80:81], 0, v[142:143]
	s_add_i32 m0, s28, 0x2000
	s_nop 0
	global_load_lds_dwordx4 v[128:129], off
	s_waitcnt vmcnt(6)
	s_barrier
	v_mfma_f32_16x16x32_bf16 v[52:55], v[204:207], v[168:171], v[52:55]
	v_mfma_f32_16x16x32_bf16 v[48:51], v[212:215], v[168:171], v[48:51]
	v_mfma_f32_16x16x32_bf16 v[36:39], v[204:207], v[176:179], v[36:39]
	v_mfma_f32_16x16x32_bf16 v[32:35], v[212:215], v[176:179], v[32:35]
	v_mfma_f32_16x16x32_bf16 v[20:23], v[204:207], v[184:187], v[20:23]
	v_mfma_f32_16x16x32_bf16 v[16:19], v[212:215], v[184:187], v[16:19]
	v_mfma_f32_16x16x32_bf16 v[4:7], v[204:207], v[196:199], v[4:7]
	v_mfma_f32_16x16x32_bf16 v[0:3], v[212:215], v[196:199], v[0:3]
	v_mfma_f32_16x16x32_bf16 v[52:55], v[208:211], v[172:175], v[52:55]
	v_mfma_f32_16x16x32_bf16 v[48:51], v[216:219], v[172:175], v[48:51]
	v_mfma_f32_16x16x32_bf16 v[36:39], v[208:211], v[180:183], v[36:39]
	v_mfma_f32_16x16x32_bf16 v[32:35], v[216:219], v[180:183], v[32:35]
	v_mfma_f32_16x16x32_bf16 v[20:23], v[208:211], v[188:191], v[20:23]
	v_mfma_f32_16x16x32_bf16 v[16:19], v[216:219], v[188:191], v[16:19]
	v_mfma_f32_16x16x32_bf16 v[4:7], v[208:211], v[200:203], v[4:7]
	v_mfma_f32_16x16x32_bf16 v[0:3], v[216:219], v[200:203], v[0:3]
	s_add_i32 s28, 0, 0x18000
	v_add_u32_e32 v156, s28, v161
	s_barrier
	ds_read_b128 v[128:131], v156
	ds_read_b128 v[132:135], v156 offset:1024
	ds_read_b128 v[152:155], v156 offset:2048
	ds_read_b128 v[156:159], v156 offset:3072
	s_add_u32 s52, s52, 0x20000
	s_addc_u32 s53, s53, 0
	s_mov_b32 m0, s57
	v_lshl_add_u64 v[204:205], s[52:53], 0, v[136:137]
	ds_read_b128 v[168:171], v165 offset:32768
	ds_read_b128 v[172:175], v165 offset:33792
	ds_read_b128 v[176:179], v165 offset:34816
	ds_read_b128 v[180:183], v165 offset:35840
	ds_read_b128 v[184:187], v165 offset:36864
	ds_read_b128 v[188:191], v165 offset:37888
	ds_read_b128 v[196:199], v165 offset:38912
	ds_read_b128 v[200:203], v165 offset:39936
	global_load_lds_dwordx4 v[204:205], off
	v_lshl_add_u64 v[204:205], s[52:53], 0, v[140:141]
	s_mov_b32 m0, s58
	s_nop 0
	global_load_lds_dwordx4 v[204:205], off
	s_waitcnt lgkmcnt(8)
	s_barrier
	s_waitcnt lgkmcnt(0)
	s_waitcnt lgkmcnt(0)
	v_mfma_f32_16x16x32_bf16 v[124:127], v[128:131], v[168:171], v[124:127]
	v_mfma_f32_16x16x32_bf16 v[120:123], v[152:155], v[168:171], v[120:123]
	v_mfma_f32_16x16x32_bf16 v[108:111], v[128:131], v[176:179], v[108:111]
	v_mfma_f32_16x16x32_bf16 v[104:107], v[152:155], v[176:179], v[104:107]
	v_mfma_f32_16x16x32_bf16 v[92:95], v[128:131], v[184:187], v[92:95]
	v_mfma_f32_16x16x32_bf16 v[88:91], v[152:155], v[184:187], v[88:91]
	v_mfma_f32_16x16x32_bf16 v[76:79], v[128:131], v[196:199], v[76:79]
	v_mfma_f32_16x16x32_bf16 v[72:75], v[152:155], v[196:199], v[72:75]
	v_mfma_f32_16x16x32_bf16 v[124:127], v[132:135], v[172:175], v[124:127]
	v_mfma_f32_16x16x32_bf16 v[120:123], v[156:159], v[172:175], v[120:123]
	v_mfma_f32_16x16x32_bf16 v[108:111], v[132:135], v[180:183], v[108:111]
	v_mfma_f32_16x16x32_bf16 v[104:107], v[156:159], v[180:183], v[104:107]
	v_mfma_f32_16x16x32_bf16 v[92:95], v[132:135], v[188:191], v[92:95]
	v_mfma_f32_16x16x32_bf16 v[88:91], v[156:159], v[188:191], v[88:91]
	v_mfma_f32_16x16x32_bf16 v[76:79], v[132:135], v[200:203], v[76:79]
	v_mfma_f32_16x16x32_bf16 v[72:75], v[156:159], v[200:203], v[72:75]
	s_barrier
	s_add_i32 s29, 0, 0x1c000
	s_add_i32 s28, s28, s54
	v_add_u32_e32 v195, s29, v161
	v_lshl_add_u64 v[220:221], v[220:221], 0, s[36:37]
	s_mov_b32 m0, s28
	ds_read_b128 v[204:207], v195
	ds_read_b128 v[208:211], v195 offset:1024
	ds_read_b128 v[212:215], v195 offset:2048
	ds_read_b128 v[216:219], v195 offset:3072
	global_load_lds_dwordx4 v[220:221], off
	v_lshl_add_u64 v[220:221], v[222:223], 0, s[36:37]
	s_add_i32 m0, s28, 0x2000
	s_nop 0
	global_load_lds_dwordx4 v[220:221], off
	s_barrier
	s_waitcnt lgkmcnt(0)
	s_waitcnt lgkmcnt(0)
	v_mfma_f32_16x16x32_bf16 v[116:119], v[204:207], v[168:171], v[116:119]
	v_mfma_f32_16x16x32_bf16 v[112:115], v[212:215], v[168:171], v[112:115]
	v_mfma_f32_16x16x32_bf16 v[100:103], v[204:207], v[176:179], v[100:103]
	v_mfma_f32_16x16x32_bf16 v[96:99], v[212:215], v[176:179], v[96:99]
	v_mfma_f32_16x16x32_bf16 v[84:87], v[204:207], v[184:187], v[84:87]
	v_mfma_f32_16x16x32_bf16 v[80:83], v[212:215], v[184:187], v[80:83]
	v_mfma_f32_16x16x32_bf16 v[68:71], v[204:207], v[196:199], v[68:71]
	v_mfma_f32_16x16x32_bf16 v[64:67], v[212:215], v[196:199], v[64:67]
	v_mfma_f32_16x16x32_bf16 v[116:119], v[208:211], v[172:175], v[116:119]
	v_mfma_f32_16x16x32_bf16 v[112:115], v[216:219], v[172:175], v[112:115]
	v_mfma_f32_16x16x32_bf16 v[100:103], v[208:211], v[180:183], v[100:103]
	v_mfma_f32_16x16x32_bf16 v[96:99], v[216:219], v[180:183], v[96:99]
	v_mfma_f32_16x16x32_bf16 v[84:87], v[208:211], v[188:191], v[84:87]
	v_mfma_f32_16x16x32_bf16 v[80:83], v[216:219], v[188:191], v[80:83]
	v_mfma_f32_16x16x32_bf16 v[68:71], v[208:211], v[200:203], v[68:71]
	v_mfma_f32_16x16x32_bf16 v[64:67], v[216:219], v[200:203], v[64:67]
	s_mov_b32 m0, s62
	v_lshl_add_u64 v[220:221], v[224:225], 0, s[36:37]
	s_barrier
	ds_read_b128 v[168:171], v165 offset:49152
	ds_read_b128 v[172:175], v165 offset:50176
	ds_read_b128 v[176:179], v165 offset:51200
	ds_read_b128 v[180:183], v165 offset:52224
	ds_read_b128 v[184:187], v165 offset:53248
	ds_read_b128 v[188:191], v165 offset:54272
	ds_read_b128 v[196:199], v165 offset:55296
	ds_read_b128 v[200:203], v165 offset:56320
	global_load_lds_dwordx4 v[220:221], off
	v_lshl_add_u64 v[220:221], v[226:227], 0, s[36:37]
	s_mov_b32 m0, s63
	s_nop 0
	global_load_lds_dwordx4 v[220:221], off
	s_barrier
	s_waitcnt lgkmcnt(0)
	s_waitcnt lgkmcnt(0)
	v_mfma_f32_16x16x32_bf16 v[60:63], v[128:131], v[168:171], v[60:63]
	v_mfma_f32_16x16x32_bf16 v[56:59], v[152:155], v[168:171], v[56:59]
	v_mfma_f32_16x16x32_bf16 v[44:47], v[128:131], v[176:179], v[44:47]
	v_mfma_f32_16x16x32_bf16 v[40:43], v[152:155], v[176:179], v[40:43]
	v_mfma_f32_16x16x32_bf16 v[28:31], v[128:131], v[184:187], v[28:31]
	v_mfma_f32_16x16x32_bf16 v[24:27], v[152:155], v[184:187], v[24:27]
	v_mfma_f32_16x16x32_bf16 v[12:15], v[128:131], v[196:199], v[12:15]
	v_mfma_f32_16x16x32_bf16 v[8:11], v[152:155], v[196:199], v[8:11]
	v_mfma_f32_16x16x32_bf16 v[60:63], v[132:135], v[172:175], v[60:63]
	v_mfma_f32_16x16x32_bf16 v[56:59], v[156:159], v[172:175], v[56:59]
	v_mfma_f32_16x16x32_bf16 v[44:47], v[132:135], v[180:183], v[44:47]
	v_mfma_f32_16x16x32_bf16 v[40:43], v[156:159], v[180:183], v[40:43]
	v_mfma_f32_16x16x32_bf16 v[28:31], v[132:135], v[188:191], v[28:31]
	v_mfma_f32_16x16x32_bf16 v[24:27], v[156:159], v[188:191], v[24:27]
	v_mfma_f32_16x16x32_bf16 v[12:15], v[132:135], v[200:203], v[12:15]
	v_mfma_f32_16x16x32_bf16 v[8:11], v[156:159], v[200:203], v[8:11]
	s_barrier
	s_add_u32 s50, s50, 0x8080
	s_addc_u32 s51, s51, 0
	s_add_i32 s28, s29, s54
	v_lshl_add_u64 v[128:129], s[50:51], 0, v[138:139]
	s_mov_b32 m0, s28
	s_nop 0
	global_load_lds_dwordx4 v[128:129], off
	v_lshl_add_u64 v[128:129], s[50:51], 0, v[142:143]
	s_add_i32 m0, s28, 0x2000
	s_nop 0
	global_load_lds_dwordx4 v[128:129], off
	s_waitcnt vmcnt(6)
	s_barrier
	v_mfma_f32_16x16x32_bf16 v[52:55], v[204:207], v[168:171], v[52:55]
	v_mfma_f32_16x16x32_bf16 v[48:51], v[212:215], v[168:171], v[48:51]
	v_mfma_f32_16x16x32_bf16 v[36:39], v[204:207], v[176:179], v[36:39]
	v_mfma_f32_16x16x32_bf16 v[32:35], v[212:215], v[176:179], v[32:35]
	v_mfma_f32_16x16x32_bf16 v[20:23], v[204:207], v[184:187], v[20:23]
	v_mfma_f32_16x16x32_bf16 v[16:19], v[212:215], v[184:187], v[16:19]
	v_mfma_f32_16x16x32_bf16 v[4:7], v[204:207], v[196:199], v[4:7]
	v_mfma_f32_16x16x32_bf16 v[0:3], v[212:215], v[196:199], v[0:3]
	v_mfma_f32_16x16x32_bf16 v[52:55], v[208:211], v[172:175], v[52:55]
	v_mfma_f32_16x16x32_bf16 v[48:51], v[216:219], v[172:175], v[48:51]
	v_mfma_f32_16x16x32_bf16 v[36:39], v[208:211], v[180:183], v[36:39]
	v_mfma_f32_16x16x32_bf16 v[32:35], v[216:219], v[180:183], v[32:35]
	v_mfma_f32_16x16x32_bf16 v[20:23], v[208:211], v[188:191], v[20:23]
	v_mfma_f32_16x16x32_bf16 v[16:19], v[216:219], v[188:191], v[16:19]
	v_mfma_f32_16x16x32_bf16 v[4:7], v[208:211], v[200:203], v[4:7]
	v_mfma_f32_16x16x32_bf16 v[0:3], v[216:219], v[200:203], v[0:3]
	s_add_i32 s79, s79, 2
	s_add_u32 s48, s48, 0x100
	s_addc_u32 s49, s49, 0
	s_add_u32 s77, s77, 0x100
	s_addc_u32 s78, s78, 0
	s_cmp_gt_u32 s79, 5
	s_cbranch_scc0 .Lrot_997
	s_barrier
	v_lshl_add_u32 v152, s8, 8, v160
	v_lshl_or_b32 v156, s10, 8, v162
	v_ashrrev_i32_e32 v153, 31, v152
	v_lshlrev_b64 v[128:129], 11, v[152:153]
	v_ashrrev_i32_e32 v157, 31, v156
	v_lshl_add_u64 v[128:129], s[42:43], 0, v[128:129]
	v_lshlrev_b64 v[130:131], 1, v[156:157]
	v_or_b32_e32 v158, 16, v152
	v_lshl_add_u64 v[128:129], v[128:129], 0, v[130:131]
	v_ashrrev_i32_e32 v159, 31, v158
	global_load_dwordx4 v[168:171], v[128:129], off
	global_load_dwordx4 v[172:175], v[128:129], off offset:64
	v_lshlrev_b64 v[128:129], 11, v[158:159]
	v_lshl_add_u64 v[128:129], s[42:43], 0, v[128:129]
	v_lshl_add_u64 v[128:129], v[128:129], 0, v[130:131]
	global_load_dwordx4 v[132:135], v[128:129], off
	s_nop 0
	global_load_dwordx4 v[128:131], v[128:129], off offset:64
	v_cndmask_b32_e64 v155, 0, 1, s[12:13]
	v_or_b32_e32 v154, v156, v163
	v_cmp_ne_u32_e64 s[8:9], 1, v155
	v_ashrrev_i32_e32 v155, 31, v154
	s_andn2_b64 vcc, exec, s[12:13]
	v_lshlrev_b64 v[154:155], 1, v[154:155]
	s_waitcnt vmcnt(0)
	v_lshlrev_b32_e32 v176, 16, v168
	v_and_b32_e32 v177, 0xffff0000, v168
	v_lshlrev_b32_e32 v168, 16, v169
	v_and_b32_e32 v169, 0xffff0000, v169
	v_lshlrev_b32_e32 v178, 16, v170
	v_and_b32_e32 v179, 0xffff0000, v170
	v_lshlrev_b32_e32 v170, 16, v171
	v_and_b32_e32 v171, 0xffff0000, v171
	v_lshlrev_b32_e32 v180, 16, v172
	v_and_b32_e32 v181, 0xffff0000, v172
	v_lshlrev_b32_e32 v172, 16, v173
	v_and_b32_e32 v173, 0xffff0000, v173
	v_lshlrev_b32_e32 v182, 16, v174
	v_and_b32_e32 v183, 0xffff0000, v174
	v_lshlrev_b32_e32 v174, 16, v175
	v_and_b32_e32 v175, 0xffff0000, v175
	v_pk_add_f32 v[126:127], v[126:127], v[168:169]
	v_pk_add_f32 v[124:125], v[124:125], v[176:177]
	v_pk_add_f32 v[122:123], v[122:123], v[170:171]
	v_pk_add_f32 v[120:121], v[120:121], v[178:179]
	v_pk_add_f32 v[118:119], v[118:119], v[172:173]
	v_pk_add_f32 v[116:117], v[116:117], v[180:181]
	v_pk_add_f32 v[114:115], v[114:115], v[174:175]
	v_pk_add_f32 v[112:113], v[112:113], v[182:183]
	v_add_u32_e32 v169, 8, v152
	s_cbranch_vccnz .LBB0_1000
	v_cvt_pk_bf16_f32 v168, v124, v125
	v_cvt_pk_bf16_f32 v174, v116, v117
	v_cvt_pk_bf16_f32 v170, v126, v127
	v_cvt_pk_bf16_f32 v171, v120, v121
	v_cvt_pk_bf16_f32 v175, v118, v119
	v_cvt_pk_bf16_f32 v176, v112, v113
	v_cndmask_b32_e64 v173, v168, v174, s[4:5]
	v_mov_b32_e32 v178, 0
	v_cvt_pk_bf16_f32 v172, v122, v123
	v_cvt_pk_bf16_f32 v177, v114, v115
	v_mov_b32_dpp v178, v173 row_ror:8 row_mask:0xf bank_mask:0xf
	v_cndmask_b32_e64 v173, v170, v175, s[4:5]
	v_mov_b32_e32 v179, 0
	v_cndmask_b32_e64 v180, v171, v176, s[4:5]
	v_mov_b32_e32 v181, 0
	v_mov_b32_dpp v179, v173 row_ror:8 row_mask:0xf bank_mask:0xf
	v_cndmask_b32_e64 v173, v172, v177, s[4:5]
	v_mov_b32_dpp v181, v180 row_ror:8 row_mask:0xf bank_mask:0xf
	v_mov_b32_e32 v180, 0
	v_cndmask_b32_e64 v174, v174, v178, s[4:5]
	v_cndmask_b32_e64 v175, v175, v179, s[4:5]
	v_mov_b32_dpp v180, v173 row_ror:8 row_mask:0xf bank_mask:0xf
	v_cndmask_b32_e64 v173, v180, v172, s[4:5]
	v_cndmask_b32_e64 v172, v181, v171, s[4:5]
	v_cndmask_b32_e64 v171, v179, v170, s[4:5]
	v_cndmask_b32_e64 v170, v178, v168, s[4:5]
	v_add_u32_e32 v168, -8, v152
	v_cndmask_b32_e64 v178, v168, v152, s[4:5]
	v_ashrrev_i32_e32 v179, 31, v178
	v_lshlrev_b64 v[178:179], 11, v[178:179]
	v_lshl_add_u64 v[178:179], s[68:69], 0, v[178:179]
	v_lshl_add_u64 v[178:179], v[178:179], 0, v[154:155]
	global_store_dwordx4 v[178:179], v[170:173], off
	v_cndmask_b32_e64 v177, v177, v180, s[4:5]
	v_cndmask_b32_e64 v176, v176, v181, s[4:5]
	v_cndmask_b32_e64 v170, v152, v169, s[4:5]
	v_ashrrev_i32_e32 v171, 31, v170
	v_lshlrev_b64 v[170:171], 11, v[170:171]
	v_lshl_add_u64 v[170:171], s[68:69], 0, v[170:171]
	v_lshl_add_u64 v[170:171], v[170:171], 0, v[154:155]
	global_store_dwordx4 v[170:171], v[174:177], off

.LBB0_1092:
	s_ashr_i32 s37, s36, 31
	v_cmp_lt_i64_e32 vcc, s[0:1], v[142:143]
	s_lshl_b64 s[0:1], s[36:37], 19
	s_add_u32 s38, s68, s0
	s_addc_u32 s39, s69, s1
	s_and_b64 s[0:1], vcc, exec
	s_cselect_b32 s37, s39, s45
	s_cselect_b32 s60, s38, s44
	s_ashr_i32 s13, s12, 31
	s_lshl_b64 s[0:1], s[12:13], 19
	s_add_u32 s40, s70, s0
	s_addc_u32 s41, s71, s1
	s_and_b64 s[0:1], vcc, exec
	s_cselect_b32 s13, s41, s43
	s_cselect_b32 s61, s40, s42
	s_add_u32 s0, s44, 0x40080
	s_addc_u32 s1, s45, 0
	s_add_u32 s62, s42, 0x100
	s_addc_u32 s63, s43, 0
	s_mov_b32 s64, -2
	s_branch .LBB0_1093
.Lrot_1093:
	s_barrier
.LBB0_1093:
	ds_read_b128 v[146:149], v167
	ds_read_b128 v[150:153], v167 offset:1024
	ds_read_b128 v[178:181], v167 offset:2048
	ds_read_b128 v[182:185], v167 offset:3072
	s_add_u32 s28, s0, 0xfffc0080
	s_addc_u32 s29, s1, -1
	s_cmp_eq_u32 s64, 12
	s_cselect_b32 s45, s37, s29
	s_cselect_b32 s44, s60, s28
	s_cselect_b32 s43, s13, s63
	s_cselect_b32 s42, s61, s62
	v_lshl_add_u64 v[156:157], s[0:1], 0, v[138:139]
	s_add_i32 m0, s47, 0xc000
	ds_read_b128 v[186:189], v171
	ds_read_b128 v[196:199], v171 offset:1024
	ds_read_b128 v[200:203], v171 offset:2048
	ds_read_b128 v[204:207], v171 offset:3072
	ds_read_b128 v[208:211], v171 offset:4096
	ds_read_b128 v[212:215], v171 offset:5120
	ds_read_b128 v[216:219], v171 offset:6144
	ds_read_b128 v[220:223], v171 offset:7168
	global_load_lds_dwordx4 v[156:157], off
	v_lshl_add_u64 v[156:157], s[0:1], 0, v[140:141]
	s_add_i32 m0, s47, 0xe000
	s_nop 0
	global_load_lds_dwordx4 v[156:157], off
	s_waitcnt lgkmcnt(8)
	s_barrier
	s_waitcnt lgkmcnt(0)
	s_waitcnt lgkmcnt(0)
	s_cmp_eq_u32 s64, -2
	s_cbranch_scc1 .Lz10_0_first
	v_mfma_f32_16x16x32_bf16 v[124:127], v[146:149], v[186:189], v[124:127]
	v_mfma_f32_16x16x32_bf16 v[120:123], v[178:181], v[186:189], v[120:123]
	v_mfma_f32_16x16x32_bf16 v[108:111], v[146:149], v[200:203], v[108:111]
	v_mfma_f32_16x16x32_bf16 v[104:107], v[178:181], v[200:203], v[104:107]
	v_mfma_f32_16x16x32_bf16 v[92:95], v[146:149], v[208:211], v[92:95]
	v_mfma_f32_16x16x32_bf16 v[88:91], v[178:181], v[208:211], v[88:91]
	v_mfma_f32_16x16x32_bf16 v[76:79], v[146:149], v[216:219], v[76:79]
	v_mfma_f32_16x16x32_bf16 v[72:75], v[178:181], v[216:219], v[72:75]
	v_mfma_f32_16x16x32_bf16 v[124:127], v[150:153], v[196:199], v[124:127]
	v_mfma_f32_16x16x32_bf16 v[120:123], v[182:185], v[196:199], v[120:123]
	v_mfma_f32_16x16x32_bf16 v[108:111], v[150:153], v[204:207], v[108:111]
	v_mfma_f32_16x16x32_bf16 v[104:107], v[182:185], v[204:207], v[104:107]
	v_mfma_f32_16x16x32_bf16 v[92:95], v[150:153], v[212:215], v[92:95]
	v_mfma_f32_16x16x32_bf16 v[88:91], v[182:185], v[212:215], v[88:91]
	v_mfma_f32_16x16x32_bf16 v[76:79], v[150:153], v[220:223], v[76:79]
	v_mfma_f32_16x16x32_bf16 v[72:75], v[182:185], v[220:223], v[72:75]

.Lz10_3_join:
	s_add_i32 s28, 0, 0x18000
	v_add_u32_e32 v154, s28, v159
	s_barrier
	ds_read_b128 v[146:149], v154
	ds_read_b128 v[150:153], v154 offset:1024
	ds_read_b128 v[178:181], v154 offset:2048
	ds_read_b128 v[182:185], v154 offset:3072
	s_add_u32 s44, s44, 0x40000
	s_addc_u32 s45, s45, 0
	s_mov_b32 m0, s49
	v_lshl_add_u64 v[172:173], s[44:45], 0, v[134:135]
	ds_read_b128 v[186:189], v171 offset:32768
	ds_read_b128 v[196:199], v171 offset:33792
	ds_read_b128 v[200:203], v171 offset:34816
	ds_read_b128 v[204:207], v171 offset:35840
	ds_read_b128 v[208:211], v171 offset:36864
	ds_read_b128 v[212:215], v171 offset:37888
	ds_read_b128 v[216:219], v171 offset:38912
	ds_read_b128 v[220:223], v171 offset:39936
	global_load_lds_dwordx4 v[172:173], off
	v_lshl_add_u64 v[172:173], s[44:45], 0, v[130:131]
	s_mov_b32 m0, s50
	s_nop 0
	global_load_lds_dwordx4 v[172:173], off
	s_waitcnt lgkmcnt(8)
	s_barrier
	s_waitcnt lgkmcnt(0)
	s_waitcnt lgkmcnt(0)
	v_mfma_f32_16x16x32_bf16 v[124:127], v[146:149], v[186:189], v[124:127]
	v_mfma_f32_16x16x32_bf16 v[120:123], v[178:181], v[186:189], v[120:123]
	v_mfma_f32_16x16x32_bf16 v[108:111], v[146:149], v[200:203], v[108:111]
	v_mfma_f32_16x16x32_bf16 v[104:107], v[178:181], v[200:203], v[104:107]
	v_mfma_f32_16x16x32_bf16 v[92:95], v[146:149], v[208:211], v[92:95]
	v_mfma_f32_16x16x32_bf16 v[88:91], v[178:181], v[208:211], v[88:91]
	v_mfma_f32_16x16x32_bf16 v[76:79], v[146:149], v[216:219], v[76:79]
	v_mfma_f32_16x16x32_bf16 v[72:75], v[178:181], v[216:219], v[72:75]
	v_mfma_f32_16x16x32_bf16 v[124:127], v[150:153], v[196:199], v[124:127]
	v_mfma_f32_16x16x32_bf16 v[120:123], v[182:185], v[196:199], v[120:123]
	v_mfma_f32_16x16x32_bf16 v[108:111], v[150:153], v[204:207], v[108:111]
	v_mfma_f32_16x16x32_bf16 v[104:107], v[182:185], v[204:207], v[104:107]
	v_mfma_f32_16x16x32_bf16 v[92:95], v[150:153], v[212:215], v[92:95]
	v_mfma_f32_16x16x32_bf16 v[88:91], v[182:185], v[212:215], v[88:91]
	v_mfma_f32_16x16x32_bf16 v[76:79], v[150:153], v[220:223], v[76:79]
	v_mfma_f32_16x16x32_bf16 v[72:75], v[182:185], v[220:223], v[72:75]
	s_barrier
	s_add_i32 s29, 0, 0x1c000
	s_add_i32 s28, s28, s11
	v_add_u32_e32 v154, s29, v159
	v_lshl_add_u64 v[156:157], v[156:157], 0, s[6:7]
	s_mov_b32 m0, s28
	ds_read_b128 v[224:227], v154
	ds_read_b128 v[228:231], v154 offset:1024
	ds_read_b128 v[232:235], v154 offset:2048
	ds_read_b128 v[236:239], v154 offset:3072
	global_load_lds_dwordx4 v[156:157], off
	v_lshl_add_u64 v[156:157], v[160:161], 0, s[6:7]
	s_add_i32 m0, s28, 0x2000
	s_nop 0
	global_load_lds_dwordx4 v[156:157], off
	s_barrier
	s_waitcnt lgkmcnt(0)
	s_waitcnt lgkmcnt(0)
	v_mfma_f32_16x16x32_bf16 v[116:119], v[224:227], v[186:189], v[116:119]
	v_mfma_f32_16x16x32_bf16 v[112:115], v[232:235], v[186:189], v[112:115]
	v_mfma_f32_16x16x32_bf16 v[100:103], v[224:227], v[200:203], v[100:103]
	v_mfma_f32_16x16x32_bf16 v[96:99], v[232:235], v[200:203], v[96:99]
	v_mfma_f32_16x16x32_bf16 v[84:87], v[224:227], v[208:211], v[84:87]
	v_mfma_f32_16x16x32_bf16 v[80:83], v[232:235], v[208:211], v[80:83]
	v_mfma_f32_16x16x32_bf16 v[68:71], v[224:227], v[216:219], v[68:71]
	v_mfma_f32_16x16x32_bf16 v[64:67], v[232:235], v[216:219], v[64:67]
	v_mfma_f32_16x16x32_bf16 v[116:119], v[228:231], v[196:199], v[116:119]
	v_mfma_f32_16x16x32_bf16 v[112:115], v[236:239], v[196:199], v[112:115]
	v_mfma_f32_16x16x32_bf16 v[100:103], v[228:231], v[204:207], v[100:103]
	v_mfma_f32_16x16x32_bf16 v[96:99], v[236:239], v[204:207], v[96:99]
	v_mfma_f32_16x16x32_bf16 v[84:87], v[228:231], v[212:215], v[84:87]
	v_mfma_f32_16x16x32_bf16 v[80:83], v[236:239], v[212:215], v[80:83]
	v_mfma_f32_16x16x32_bf16 v[68:71], v[228:231], v[220:223], v[68:71]
	v_mfma_f32_16x16x32_bf16 v[64:67], v[236:239], v[220:223], v[64:67]
	s_mov_b32 m0, s53
	v_lshl_add_u64 v[156:157], v[164:165], 0, s[6:7]
	s_barrier
	ds_read_b128 v[186:189], v171 offset:49152
	ds_read_b128 v[196:199], v171 offset:50176
	ds_read_b128 v[200:203], v171 offset:51200
	ds_read_b128 v[204:207], v171 offset:52224
	ds_read_b128 v[208:211], v171 offset:53248
	ds_read_b128 v[212:215], v171 offset:54272
	ds_read_b128 v[216:219], v171 offset:55296
	ds_read_b128 v[220:223], v171 offset:56320
	global_load_lds_dwordx4 v[156:157], off
	v_lshl_add_u64 v[156:157], v[168:169], 0, s[6:7]
	s_mov_b32 m0, s54
	s_nop 0
	global_load_lds_dwordx4 v[156:157], off
	s_barrier
	s_waitcnt lgkmcnt(0)
	s_waitcnt lgkmcnt(0)
	v_mfma_f32_16x16x32_bf16 v[60:63], v[146:149], v[186:189], v[60:63]
	v_mfma_f32_16x16x32_bf16 v[56:59], v[178:181], v[186:189], v[56:59]
	v_mfma_f32_16x16x32_bf16 v[44:47], v[146:149], v[200:203], v[44:47]
	v_mfma_f32_16x16x32_bf16 v[40:43], v[178:181], v[200:203], v[40:43]
	v_mfma_f32_16x16x32_bf16 v[28:31], v[146:149], v[208:211], v[28:31]
	v_mfma_f32_16x16x32_bf16 v[24:27], v[178:181], v[208:211], v[24:27]
	v_mfma_f32_16x16x32_bf16 v[12:15], v[146:149], v[216:219], v[12:15]
	v_mfma_f32_16x16x32_bf16 v[8:11], v[178:181], v[216:219], v[8:11]
	v_mfma_f32_16x16x32_bf16 v[60:63], v[150:153], v[196:199], v[60:63]
	v_mfma_f32_16x16x32_bf16 v[56:59], v[182:185], v[196:199], v[56:59]
	v_mfma_f32_16x16x32_bf16 v[44:47], v[150:153], v[204:207], v[44:47]
	v_mfma_f32_16x16x32_bf16 v[40:43], v[182:185], v[204:207], v[40:43]
	v_mfma_f32_16x16x32_bf16 v[28:31], v[150:153], v[212:215], v[28:31]
	v_mfma_f32_16x16x32_bf16 v[24:27], v[182:185], v[212:215], v[24:27]
	v_mfma_f32_16x16x32_bf16 v[12:15], v[150:153], v[220:223], v[12:15]
	v_mfma_f32_16x16x32_bf16 v[8:11], v[182:185], v[220:223], v[8:11]
	s_barrier
	s_add_u32 s42, s42, 0x40080
	s_addc_u32 s43, s43, 0
	s_add_i32 s28, s29, s11
	v_lshl_add_u64 v[146:147], s[42:43], 0, v[132:133]
	s_mov_b32 m0, s28
	s_nop 0
	global_load_lds_dwordx4 v[146:147], off
	v_lshl_add_u64 v[146:147], s[42:43], 0, v[128:129]
	s_add_i32 m0, s28, 0x2000
	s_nop 0
	global_load_lds_dwordx4 v[146:147], off
	s_waitcnt vmcnt(6)
	s_barrier
	v_mfma_f32_16x16x32_bf16 v[52:55], v[224:227], v[186:189], v[52:55]
	v_mfma_f32_16x16x32_bf16 v[48:51], v[232:235], v[186:189], v[48:51]
	v_mfma_f32_16x16x32_bf16 v[36:39], v[224:227], v[200:203], v[36:39]
	v_mfma_f32_16x16x32_bf16 v[32:35], v[232:235], v[200:203], v[32:35]
	v_mfma_f32_16x16x32_bf16 v[20:23], v[224:227], v[208:211], v[20:23]
	v_mfma_f32_16x16x32_bf16 v[16:19], v[232:235], v[208:211], v[16:19]
	v_mfma_f32_16x16x32_bf16 v[4:7], v[224:227], v[216:219], v[4:7]
	v_mfma_f32_16x16x32_bf16 v[0:3], v[232:235], v[216:219], v[0:3]
	v_mfma_f32_16x16x32_bf16 v[52:55], v[228:231], v[196:199], v[52:55]
	v_mfma_f32_16x16x32_bf16 v[48:51], v[236:239], v[196:199], v[48:51]
	v_mfma_f32_16x16x32_bf16 v[36:39], v[228:231], v[204:207], v[36:39]
	v_mfma_f32_16x16x32_bf16 v[32:35], v[236:239], v[204:207], v[32:35]
	v_mfma_f32_16x16x32_bf16 v[20:23], v[228:231], v[212:215], v[20:23]
	v_mfma_f32_16x16x32_bf16 v[16:19], v[236:239], v[212:215], v[16:19]
	v_mfma_f32_16x16x32_bf16 v[4:7], v[228:231], v[220:223], v[4:7]
	v_mfma_f32_16x16x32_bf16 v[0:3], v[236:239], v[220:223], v[0:3]
	s_add_i32 s64, s64, 2
	s_add_u32 s0, s0, 0x100
	s_addc_u32 s1, s1, 0
	s_add_u32 s62, s62, 0x100
	s_addc_u32 s63, s63, 0
	s_cmp_gt_u32 s64, 13
	s_cbranch_scc0 .Lrot_1093
	s_barrier
	s_branch .Lz10_skip

.LBB0_1168:
	s_add_u32 s63, s42, 0x100
	v_mov_b32_e32 v0, 0
	s_addc_u32 s64, s43, 0
	s_mov_b32 s65, -2
	s_waitcnt lgkmcnt(0)
	v_mov_b64_e32 v[0:1], 0
	v_mov_b64_e32 v[2:3], 0
	v_mov_b64_e32 v[4:5], 0
	v_mov_b64_e32 v[6:7], 0
	v_mov_b64_e32 v[8:9], 0
	v_mov_b64_e32 v[10:11], 0
	v_mov_b64_e32 v[12:13], 0
	v_mov_b64_e32 v[14:15], 0
	v_mov_b64_e32 v[16:17], 0
	v_mov_b64_e32 v[18:19], 0
	v_mov_b64_e32 v[20:21], 0
	v_mov_b64_e32 v[22:23], 0
	v_mov_b64_e32 v[24:25], 0
	v_mov_b64_e32 v[26:27], 0
	v_mov_b64_e32 v[28:29], 0
	v_mov_b64_e32 v[30:31], 0
	v_mov_b64_e32 v[32:33], 0
	v_mov_b64_e32 v[34:35], 0
	v_mov_b64_e32 v[36:37], 0
	v_mov_b64_e32 v[38:39], 0
	v_mov_b64_e32 v[40:41], 0
	v_mov_b64_e32 v[42:43], 0
	v_mov_b64_e32 v[44:45], 0
	v_mov_b64_e32 v[46:47], 0
	v_mov_b64_e32 v[48:49], 0
	v_mov_b64_e32 v[50:51], 0
	v_mov_b64_e32 v[52:53], 0
	v_mov_b64_e32 v[54:55], 0
	v_mov_b64_e32 v[56:57], 0
	v_mov_b64_e32 v[58:59], 0
	v_mov_b64_e32 v[60:61], 0
	v_mov_b64_e32 v[62:63], 0
	v_mov_b64_e32 v[64:65], 0
	v_mov_b64_e32 v[66:67], 0
	v_mov_b64_e32 v[68:69], 0
	v_mov_b64_e32 v[70:71], 0
	v_mov_b64_e32 v[72:73], 0
	v_mov_b64_e32 v[74:75], 0
	v_mov_b64_e32 v[76:77], 0
	v_mov_b64_e32 v[78:79], 0
	v_mov_b64_e32 v[80:81], 0
	v_mov_b64_e32 v[82:83], 0
	v_mov_b64_e32 v[84:85], 0
	v_mov_b64_e32 v[86:87], 0
	v_mov_b64_e32 v[88:89], 0
	v_mov_b64_e32 v[90:91], 0
	v_mov_b64_e32 v[92:93], 0
	v_mov_b64_e32 v[94:95], 0
	v_mov_b64_e32 v[96:97], 0
	v_mov_b64_e32 v[98:99], 0
	v_mov_b64_e32 v[100:101], 0
	v_mov_b64_e32 v[102:103], 0
	v_mov_b64_e32 v[104:105], 0
	v_mov_b64_e32 v[106:107], 0
	v_mov_b64_e32 v[108:109], 0
	v_mov_b64_e32 v[110:111], 0
	v_mov_b64_e32 v[112:113], 0
	v_mov_b64_e32 v[114:115], 0
	v_mov_b64_e32 v[116:117], 0
	v_mov_b64_e32 v[118:119], 0
	v_mov_b64_e32 v[120:121], 0
	v_mov_b64_e32 v[122:123], 0
	v_mov_b64_e32 v[124:125], 0
	v_mov_b64_e32 v[126:127], 0
	s_branch .LBB0_1169

.LBB0_1169:
	ds_read_b128 v[128:131], v167
	ds_read_b128 v[132:135], v167 offset:1024
	ds_read_b128 v[136:139], v167 offset:2048
	ds_read_b128 v[156:159], v167 offset:3072
	s_add_u32 s6, s40, 0x100
	s_addc_u32 s7, s41, 0
	s_cmp_eq_u32 s65, 40
	s_cselect_b32 s45, s1, s7
	s_cselect_b32 s44, s0, s6
	s_cselect_b32 s43, s39, s64
	s_cselect_b32 s42, s38, s63
	v_lshl_add_u64 v[202:203], s[40:41], 0, v[148:149]
	s_add_i32 m0, s47, 0xc000
	ds_read_b128 v[160:163], v168
	ds_read_b128 v[172:175], v168 offset:1024
	ds_read_b128 v[176:179], v168 offset:2048
	ds_read_b128 v[180:183], v168 offset:3072
	ds_read_b128 v[184:187], v168 offset:4096
	ds_read_b128 v[188:191], v168 offset:5120
	ds_read_b128 v[194:197], v168 offset:6144
	ds_read_b128 v[198:201], v168 offset:7168
	global_load_lds_dwordx4 v[202:203], off
	v_lshl_add_u64 v[202:203], s[40:41], 0, v[150:151]
	s_add_i32 m0, s47, 0xe000
	s_nop 0
	global_load_lds_dwordx4 v[202:203], off
	s_waitcnt lgkmcnt(8)
	s_barrier
	s_waitcnt lgkmcnt(0)
	s_waitcnt lgkmcnt(0)
	v_mfma_f32_16x16x32_bf16 v[124:127], v[128:131], v[160:163], v[124:127]
	v_mfma_f32_16x16x32_bf16 v[120:123], v[136:139], v[160:163], v[120:123]
	v_mfma_f32_16x16x32_bf16 v[108:111], v[128:131], v[176:179], v[108:111]
	v_mfma_f32_16x16x32_bf16 v[104:107], v[136:139], v[176:179], v[104:107]
	v_mfma_f32_16x16x32_bf16 v[92:95], v[128:131], v[184:187], v[92:95]
	v_mfma_f32_16x16x32_bf16 v[88:91], v[136:139], v[184:187], v[88:91]
	v_mfma_f32_16x16x32_bf16 v[76:79], v[128:131], v[194:197], v[76:79]
	v_mfma_f32_16x16x32_bf16 v[72:75], v[136:139], v[194:197], v[72:75]
	v_mfma_f32_16x16x32_bf16 v[124:127], v[132:135], v[172:175], v[124:127]
	v_mfma_f32_16x16x32_bf16 v[120:123], v[156:159], v[172:175], v[120:123]
	v_mfma_f32_16x16x32_bf16 v[108:111], v[132:135], v[180:183], v[108:111]
	v_mfma_f32_16x16x32_bf16 v[104:107], v[156:159], v[180:183], v[104:107]
	v_mfma_f32_16x16x32_bf16 v[92:95], v[132:135], v[188:191], v[92:95]
	v_mfma_f32_16x16x32_bf16 v[88:91], v[156:159], v[188:191], v[88:91]
	v_mfma_f32_16x16x32_bf16 v[76:79], v[132:135], v[198:201], v[76:79]
	v_mfma_f32_16x16x32_bf16 v[72:75], v[156:159], v[198:201], v[72:75]
	s_barrier
	s_add_i32 s28, s57, s46
	v_lshl_add_u64 v[218:219], s[42:43], 0, v[142:143]
	s_mov_b32 m0, s28
	ds_read_b128 v[202:205], v169
	ds_read_b128 v[206:209], v169 offset:1024
	ds_read_b128 v[210:213], v169 offset:2048
	ds_read_b128 v[214:217], v169 offset:3072
	global_load_lds_dwordx4 v[218:219], off
	v_lshl_add_u64 v[220:221], s[42:43], 0, v[146:147]
	s_add_i32 m0, s28, 0x2000
	s_nop 0
	global_load_lds_dwordx4 v[220:221], off
	s_barrier
	s_waitcnt lgkmcnt(0)
	s_waitcnt lgkmcnt(0)
	v_mfma_f32_16x16x32_bf16 v[116:119], v[202:205], v[160:163], v[116:119]
	v_mfma_f32_16x16x32_bf16 v[112:115], v[210:213], v[160:163], v[112:115]
	v_mfma_f32_16x16x32_bf16 v[100:103], v[202:205], v[176:179], v[100:103]
	v_mfma_f32_16x16x32_bf16 v[96:99], v[210:213], v[176:179], v[96:99]
	v_mfma_f32_16x16x32_bf16 v[84:87], v[202:205], v[184:187], v[84:87]
	v_mfma_f32_16x16x32_bf16 v[80:83], v[210:213], v[184:187], v[80:83]
	v_mfma_f32_16x16x32_bf16 v[68:71], v[202:205], v[194:197], v[68:71]
	v_mfma_f32_16x16x32_bf16 v[64:67], v[210:213], v[194:197], v[64:67]
	v_mfma_f32_16x16x32_bf16 v[116:119], v[206:209], v[172:175], v[116:119]
	v_mfma_f32_16x16x32_bf16 v[112:115], v[214:217], v[172:175], v[112:115]
	v_mfma_f32_16x16x32_bf16 v[100:103], v[206:209], v[180:183], v[100:103]
	v_mfma_f32_16x16x32_bf16 v[96:99], v[214:217], v[180:183], v[96:99]
	v_mfma_f32_16x16x32_bf16 v[84:87], v[206:209], v[188:191], v[84:87]
	v_mfma_f32_16x16x32_bf16 v[80:83], v[214:217], v[188:191], v[80:83]
	v_mfma_f32_16x16x32_bf16 v[68:71], v[206:209], v[198:201], v[68:71]
	v_mfma_f32_16x16x32_bf16 v[64:67], v[214:217], v[198:201], v[64:67]
	s_mov_b32 m0, s47
	v_lshl_add_u64 v[222:223], s[44:45], 0, v[140:141]
	s_barrier
	ds_read_b128 v[160:163], v168 offset:16384
	ds_read_b128 v[172:175], v168 offset:17408
	ds_read_b128 v[176:179], v168 offset:18432
	ds_read_b128 v[180:183], v168 offset:19456
	ds_read_b128 v[184:187], v168 offset:20480
	ds_read_b128 v[188:191], v168 offset:21504
	ds_read_b128 v[194:197], v168 offset:22528
	ds_read_b128 v[198:201], v168 offset:23552
	global_load_lds_dwordx4 v[222:223], off
	v_lshl_add_u64 v[224:225], s[44:45], 0, v[144:145]
	s_mov_b32 m0, s48
	s_nop 0
	global_load_lds_dwordx4 v[224:225], off
	s_barrier
	s_waitcnt lgkmcnt(0)
	s_waitcnt lgkmcnt(0)
	v_mfma_f32_16x16x32_bf16 v[60:63], v[128:131], v[160:163], v[60:63]
	v_mfma_f32_16x16x32_bf16 v[56:59], v[136:139], v[160:163], v[56:59]
	v_mfma_f32_16x16x32_bf16 v[44:47], v[128:131], v[176:179], v[44:47]
	v_mfma_f32_16x16x32_bf16 v[40:43], v[136:139], v[176:179], v[40:43]
	v_mfma_f32_16x16x32_bf16 v[28:31], v[128:131], v[184:187], v[28:31]
	v_mfma_f32_16x16x32_bf16 v[24:27], v[136:139], v[184:187], v[24:27]
	v_mfma_f32_16x16x32_bf16 v[12:15], v[128:131], v[194:197], v[12:15]
	v_mfma_f32_16x16x32_bf16 v[8:11], v[136:139], v[194:197], v[8:11]
	v_mfma_f32_16x16x32_bf16 v[60:63], v[132:135], v[172:175], v[60:63]
	v_mfma_f32_16x16x32_bf16 v[56:59], v[156:159], v[172:175], v[56:59]
	v_mfma_f32_16x16x32_bf16 v[44:47], v[132:135], v[180:183], v[44:47]
	v_mfma_f32_16x16x32_bf16 v[40:43], v[156:159], v[180:183], v[40:43]
	v_mfma_f32_16x16x32_bf16 v[28:31], v[132:135], v[188:191], v[28:31]
	v_mfma_f32_16x16x32_bf16 v[24:27], v[156:159], v[188:191], v[24:27]
	v_mfma_f32_16x16x32_bf16 v[12:15], v[132:135], v[198:201], v[12:15]
	v_mfma_f32_16x16x32_bf16 v[8:11], v[156:159], v[198:201], v[8:11]
	s_barrier
	s_add_u32 s40, s42, 0x2c000
	s_addc_u32 s41, s43, 0
	s_add_i32 s28, s58, s46
	v_lshl_add_u64 v[128:129], s[40:41], 0, v[142:143]
	s_mov_b32 m0, s28
	s_nop 0
	global_load_lds_dwordx4 v[128:129], off
	v_lshl_add_u64 v[128:129], s[40:41], 0, v[146:147]
	s_add_i32 m0, s28, 0x2000
	s_nop 0
	global_load_lds_dwordx4 v[128:129], off
	s_waitcnt vmcnt(6)
	s_barrier
	v_mfma_f32_16x16x32_bf16 v[52:55], v[202:205], v[160:163], v[52:55]
	v_mfma_f32_16x16x32_bf16 v[48:51], v[210:213], v[160:163], v[48:51]
	v_mfma_f32_16x16x32_bf16 v[36:39], v[202:205], v[176:179], v[36:39]
	v_mfma_f32_16x16x32_bf16 v[32:35], v[210:213], v[176:179], v[32:35]
	v_mfma_f32_16x16x32_bf16 v[20:23], v[202:205], v[184:187], v[20:23]
	v_mfma_f32_16x16x32_bf16 v[16:19], v[210:213], v[184:187], v[16:19]
	v_mfma_f32_16x16x32_bf16 v[4:7], v[202:205], v[194:197], v[4:7]
	v_mfma_f32_16x16x32_bf16 v[0:3], v[210:213], v[194:197], v[0:3]
	v_mfma_f32_16x16x32_bf16 v[52:55], v[206:209], v[172:175], v[52:55]
	v_mfma_f32_16x16x32_bf16 v[48:51], v[214:217], v[172:175], v[48:51]
	v_mfma_f32_16x16x32_bf16 v[36:39], v[206:209], v[180:183], v[36:39]
	v_mfma_f32_16x16x32_bf16 v[32:35], v[214:217], v[180:183], v[32:35]
	v_mfma_f32_16x16x32_bf16 v[20:23], v[206:209], v[188:191], v[20:23]
	v_mfma_f32_16x16x32_bf16 v[16:19], v[214:217], v[188:191], v[16:19]
	v_mfma_f32_16x16x32_bf16 v[4:7], v[206:209], v[198:201], v[4:7]
	v_mfma_f32_16x16x32_bf16 v[0:3], v[214:217], v[198:201], v[0:3]
	s_add_i32 s28, 0, 0x18000
	v_add_u32_e32 v156, s28, v165
	s_barrier
	ds_read_b128 v[128:131], v156
	ds_read_b128 v[132:135], v156 offset:1024
	ds_read_b128 v[136:139], v156 offset:2048
	ds_read_b128 v[156:159], v156 offset:3072
	s_add_u32 s40, s44, 0xb0000
	s_addc_u32 s41, s45, 0
	s_mov_b32 m0, s49
	v_lshl_add_u64 v[202:203], s[40:41], 0, v[140:141]
	ds_read_b128 v[160:163], v168 offset:32768
	ds_read_b128 v[172:175], v168 offset:33792
	ds_read_b128 v[176:179], v168 offset:34816
	ds_read_b128 v[180:183], v168 offset:35840
	ds_read_b128 v[184:187], v168 offset:36864
	ds_read_b128 v[188:191], v168 offset:37888
	ds_read_b128 v[194:197], v168 offset:38912
	ds_read_b128 v[198:201], v168 offset:39936
	global_load_lds_dwordx4 v[202:203], off
	v_lshl_add_u64 v[202:203], s[40:41], 0, v[144:145]
	s_mov_b32 m0, s50
	s_nop 0
	global_load_lds_dwordx4 v[202:203], off
	s_waitcnt lgkmcnt(8)
	s_barrier
	s_waitcnt lgkmcnt(0)
	s_waitcnt lgkmcnt(0)
	v_mfma_f32_16x16x32_bf16 v[124:127], v[128:131], v[160:163], v[124:127]
	v_mfma_f32_16x16x32_bf16 v[120:123], v[136:139], v[160:163], v[120:123]
	v_mfma_f32_16x16x32_bf16 v[108:111], v[128:131], v[176:179], v[108:111]
	v_mfma_f32_16x16x32_bf16 v[104:107], v[136:139], v[176:179], v[104:107]
	v_mfma_f32_16x16x32_bf16 v[92:95], v[128:131], v[184:187], v[92:95]
	v_mfma_f32_16x16x32_bf16 v[88:91], v[136:139], v[184:187], v[88:91]
	v_mfma_f32_16x16x32_bf16 v[76:79], v[128:131], v[194:197], v[76:79]
	v_mfma_f32_16x16x32_bf16 v[72:75], v[136:139], v[194:197], v[72:75]
	v_mfma_f32_16x16x32_bf16 v[124:127], v[132:135], v[172:175], v[124:127]
	v_mfma_f32_16x16x32_bf16 v[120:123], v[156:159], v[172:175], v[120:123]
	v_mfma_f32_16x16x32_bf16 v[108:111], v[132:135], v[180:183], v[108:111]
	v_mfma_f32_16x16x32_bf16 v[104:107], v[156:159], v[180:183], v[104:107]
	v_mfma_f32_16x16x32_bf16 v[92:95], v[132:135], v[188:191], v[92:95]
	v_mfma_f32_16x16x32_bf16 v[88:91], v[156:159], v[188:191], v[88:91]
	v_mfma_f32_16x16x32_bf16 v[76:79], v[132:135], v[198:201], v[76:79]
	v_mfma_f32_16x16x32_bf16 v[72:75], v[156:159], v[198:201], v[72:75]
	s_barrier
	s_add_i32 s29, 0, 0x1c000
	s_add_i32 s28, s28, s46
	v_add_u32_e32 v171, s29, v165
	v_lshl_add_u64 v[218:219], v[218:219], 0, s[36:37]
	s_mov_b32 m0, s28
	ds_read_b128 v[202:205], v171
	ds_read_b128 v[206:209], v171 offset:1024
	ds_read_b128 v[210:213], v171 offset:2048
	ds_read_b128 v[214:217], v171 offset:3072
	global_load_lds_dwordx4 v[218:219], off
	v_lshl_add_u64 v[218:219], v[220:221], 0, s[36:37]
	s_add_i32 m0, s28, 0x2000
	s_nop 0
	global_load_lds_dwordx4 v[218:219], off
	s_barrier
	s_waitcnt lgkmcnt(0)
	s_waitcnt lgkmcnt(0)
	v_mfma_f32_16x16x32_bf16 v[116:119], v[202:205], v[160:163], v[116:119]
	v_mfma_f32_16x16x32_bf16 v[112:115], v[210:213], v[160:163], v[112:115]
	v_mfma_f32_16x16x32_bf16 v[100:103], v[202:205], v[176:179], v[100:103]
	v_mfma_f32_16x16x32_bf16 v[96:99], v[210:213], v[176:179], v[96:99]
	v_mfma_f32_16x16x32_bf16 v[84:87], v[202:205], v[184:187], v[84:87]
	v_mfma_f32_16x16x32_bf16 v[80:83], v[210:213], v[184:187], v[80:83]
	v_mfma_f32_16x16x32_bf16 v[68:71], v[202:205], v[194:197], v[68:71]
	v_mfma_f32_16x16x32_bf16 v[64:67], v[210:213], v[194:197], v[64:67]
	v_mfma_f32_16x16x32_bf16 v[116:119], v[206:209], v[172:175], v[116:119]
	v_mfma_f32_16x16x32_bf16 v[112:115], v[214:217], v[172:175], v[112:115]
	v_mfma_f32_16x16x32_bf16 v[100:103], v[206:209], v[180:183], v[100:103]
	v_mfma_f32_16x16x32_bf16 v[96:99], v[214:217], v[180:183], v[96:99]
	v_mfma_f32_16x16x32_bf16 v[84:87], v[206:209], v[188:191], v[84:87]
	v_mfma_f32_16x16x32_bf16 v[80:83], v[214:217], v[188:191], v[80:83]
	v_mfma_f32_16x16x32_bf16 v[68:71], v[206:209], v[198:201], v[68:71]
	v_mfma_f32_16x16x32_bf16 v[64:67], v[214:217], v[198:201], v[64:67]
	s_mov_b32 m0, s54
	v_lshl_add_u64 v[218:219], v[222:223], 0, s[36:37]
	s_barrier
	ds_read_b128 v[160:163], v168 offset:49152
	ds_read_b128 v[172:175], v168 offset:50176
	ds_read_b128 v[176:179], v168 offset:51200
	ds_read_b128 v[180:183], v168 offset:52224
	ds_read_b128 v[184:187], v168 offset:53248
	ds_read_b128 v[188:191], v168 offset:54272
	ds_read_b128 v[194:197], v168 offset:55296
	ds_read_b128 v[198:201], v168 offset:56320
	global_load_lds_dwordx4 v[218:219], off
	v_lshl_add_u64 v[218:219], v[224:225], 0, s[36:37]
	s_mov_b32 m0, s55
	s_nop 0
	global_load_lds_dwordx4 v[218:219], off
	s_barrier
	s_waitcnt lgkmcnt(0)
	s_waitcnt lgkmcnt(0)
	v_mfma_f32_16x16x32_bf16 v[60:63], v[128:131], v[160:163], v[60:63]
	v_mfma_f32_16x16x32_bf16 v[56:59], v[136:139], v[160:163], v[56:59]
	v_mfma_f32_16x16x32_bf16 v[44:47], v[128:131], v[176:179], v[44:47]
	v_mfma_f32_16x16x32_bf16 v[40:43], v[136:139], v[176:179], v[40:43]
	v_mfma_f32_16x16x32_bf16 v[28:31], v[128:131], v[184:187], v[28:31]
	v_mfma_f32_16x16x32_bf16 v[24:27], v[136:139], v[184:187], v[24:27]
	v_mfma_f32_16x16x32_bf16 v[12:15], v[128:131], v[194:197], v[12:15]
	v_mfma_f32_16x16x32_bf16 v[8:11], v[136:139], v[194:197], v[8:11]
	v_mfma_f32_16x16x32_bf16 v[60:63], v[132:135], v[172:175], v[60:63]
	v_mfma_f32_16x16x32_bf16 v[56:59], v[156:159], v[172:175], v[56:59]
	v_mfma_f32_16x16x32_bf16 v[44:47], v[132:135], v[180:183], v[44:47]
	v_mfma_f32_16x16x32_bf16 v[40:43], v[156:159], v[180:183], v[40:43]
	v_mfma_f32_16x16x32_bf16 v[28:31], v[132:135], v[188:191], v[28:31]
	v_mfma_f32_16x16x32_bf16 v[24:27], v[156:159], v[188:191], v[24:27]
	v_mfma_f32_16x16x32_bf16 v[12:15], v[132:135], v[198:201], v[12:15]
	v_mfma_f32_16x16x32_bf16 v[8:11], v[156:159], v[198:201], v[8:11]
	s_barrier
	s_add_u32 s40, s42, 0x2c080
	s_addc_u32 s41, s43, 0
	s_add_i32 s28, s29, s46
	v_lshl_add_u64 v[128:129], s[40:41], 0, v[142:143]
	s_mov_b32 m0, s28
	s_nop 0
	global_load_lds_dwordx4 v[128:129], off
	v_lshl_add_u64 v[128:129], s[40:41], 0, v[146:147]
	s_add_i32 m0, s28, 0x2000
	s_nop 0
	global_load_lds_dwordx4 v[128:129], off
	s_waitcnt vmcnt(6)
	s_barrier
	v_mfma_f32_16x16x32_bf16 v[52:55], v[202:205], v[160:163], v[52:55]
	v_mfma_f32_16x16x32_bf16 v[48:51], v[210:213], v[160:163], v[48:51]
	v_mfma_f32_16x16x32_bf16 v[36:39], v[202:205], v[176:179], v[36:39]
	v_mfma_f32_16x16x32_bf16 v[32:35], v[210:213], v[176:179], v[32:35]
	v_mfma_f32_16x16x32_bf16 v[20:23], v[202:205], v[184:187], v[20:23]
	v_mfma_f32_16x16x32_bf16 v[16:19], v[210:213], v[184:187], v[16:19]
	v_mfma_f32_16x16x32_bf16 v[4:7], v[202:205], v[194:197], v[4:7]
	v_mfma_f32_16x16x32_bf16 v[0:3], v[210:213], v[194:197], v[0:3]
	v_mfma_f32_16x16x32_bf16 v[52:55], v[206:209], v[172:175], v[52:55]
	v_mfma_f32_16x16x32_bf16 v[48:51], v[214:217], v[172:175], v[48:51]
	v_mfma_f32_16x16x32_bf16 v[36:39], v[206:209], v[180:183], v[36:39]
	v_mfma_f32_16x16x32_bf16 v[32:35], v[214:217], v[180:183], v[32:35]
	v_mfma_f32_16x16x32_bf16 v[20:23], v[206:209], v[188:191], v[20:23]
	v_mfma_f32_16x16x32_bf16 v[16:19], v[214:217], v[188:191], v[16:19]
	v_mfma_f32_16x16x32_bf16 v[4:7], v[206:209], v[198:201], v[4:7]
	v_mfma_f32_16x16x32_bf16 v[0:3], v[214:217], v[198:201], v[0:3]
	s_add_i32 s65, s65, 2
	s_add_u32 s63, s63, 0x100
	s_addc_u32 s64, s64, 0
	s_cmp_gt_u32 s65, 41
	s_mov_b64 s[40:41], s[6:7]
	s_cbranch_scc0 .Lrot_1169
	s_barrier
	v_lshl_add_u32 v171, s62, 8, v164
	v_lshl_or_b32 v188, s10, 8, v166
	s_mov_b32 s63, 0xffff0000
	v_lshlrev_b32_e32 v128, 11, v171
	v_lshl_add_u32 v128, v188, 1, v128
	v_lshlrev_b32_e32 v129, 12, v171
	v_lshl_add_u32 v129, v188, 2, v129
	v_lshlrev_b32_e32 v132, 2, v188
	s_mov_b64 s[70:71], s[68:69]
	global_load_dwordx4 v[194:197], v128, s[70:71]
	global_load_dwordx4 v[198:201], v128, s[70:71] offset:64
	s_add_u32 s70, s70, 0x8000
	s_addc_u32 s71, s71, 0
	global_load_dwordx4 v[202:205], v128, s[70:71]
	global_load_dwordx4 v[206:209], v128, s[70:71] offset:64
	s_add_u32 s70, s70, 0x8000
	s_addc_u32 s71, s71, 0
	global_load_dwordx4 v[210:213], v128, s[70:71]
	global_load_dwordx4 v[214:217], v128, s[70:71] offset:64
	s_add_u32 s70, s70, 0x8000
	s_addc_u32 s71, s71, 0
	global_load_dwordx4 v[218:221], v128, s[70:71]
	global_load_dwordx4 v[222:225], v128, s[70:71] offset:64
	s_add_u32 s70, s70, 0x28000
	s_addc_u32 s71, s71, 0
	global_load_dwordx4 v[226:229], v128, s[70:71]
	global_load_dwordx4 v[230:233], v128, s[70:71] offset:64
	s_add_u32 s70, s70, 0x8000
	s_addc_u32 s71, s71, 0
	global_load_dwordx4 v[234:237], v128, s[70:71]
	global_load_dwordx4 v[238:241], v128, s[70:71] offset:64
	s_add_u32 s70, s70, 0x8000
	s_addc_u32 s71, s71, 0
	global_load_dwordx4 v[172:175], v128, s[70:71]
	global_load_dwordx4 v[176:179], v128, s[70:71] offset:64
	s_add_u32 s70, s70, 0x8000
	s_addc_u32 s71, s71, 0
	global_load_dwordx4 v[180:183], v128, s[70:71]
	global_load_dwordx4 v[184:187], v128, s[70:71] offset:64
	s_bfe_u32 s42, s17, 0x20006
	s_lshl_b32 s43, s10, 4
	s_lshl_b32 s42, s42, 2
	s_add_i32 s43, s43, s42
	v_lshl_add_u32 v130, v171, 6, s43
	v_and_b32_e32 v131, 48, v170
	v_lshl_add_u32 v131, v171, 6, v131
	v_xor_b32_e32 v134, 16, v170
	v_xor_b32_e32 v135, 32, v170
	v_lshlrev_b32_e32 v134, 2, v134
	v_lshlrev_b32_e32 v135, 2, v135
	v_cmp_gt_u32_e64 s[64:65], 16, v170
	s_add_u32 s74, s8, 0x2000
	s_addc_u32 s75, s9, 0
	s_lshl_b32 s42, s62, 7
	s_add_u32 s78, s26, 0x3c08000
	s_addc_u32 s79, s27, 0
	s_add_u32 s78, s78, s42
	s_addc_u32 s79, s79, 0
	s_waitcnt vmcnt(14)
	v_lshlrev_b32_e32 v136, 16, v194
	v_and_b32_e32 v137, s63, v194
	v_pk_add_f32 v[124:125], v[124:125], v[136:137]
	v_lshlrev_b32_e32 v138, 16, v195
	v_and_b32_e32 v139, s63, v195
	v_pk_add_f32 v[126:127], v[126:127], v[138:139]
	v_lshlrev_b32_e32 v190, 16, v196
	v_and_b32_e32 v191, s63, v196
	v_pk_add_f32 v[120:121], v[120:121], v[190:191]
	v_lshlrev_b32_e32 v136, 16, v197
	v_and_b32_e32 v137, s63, v197
	v_pk_add_f32 v[122:123], v[122:123], v[136:137]
	v_lshlrev_b32_e32 v138, 16, v198
	v_and_b32_e32 v139, s63, v198
	v_pk_add_f32 v[116:117], v[116:117], v[138:139]
	v_lshlrev_b32_e32 v190, 16, v199
	v_and_b32_e32 v191, s63, v199
	v_pk_add_f32 v[118:119], v[118:119], v[190:191]
	v_lshlrev_b32_e32 v136, 16, v200
	v_and_b32_e32 v137, s63, v200
	v_pk_add_f32 v[112:113], v[112:113], v[136:137]
	v_lshlrev_b32_e32 v138, 16, v201
	v_and_b32_e32 v139, s63, v201
	v_pk_add_f32 v[114:115], v[114:115], v[138:139]
	v_mul_f32_e32 v156, v120, v120
	v_mul_f32_e32 v189, v112, v112
	v_fmac_f32_e32 v156, v121, v121
	v_fmac_f32_e32 v189, v113, v113
	v_fmac_f32_e32 v156, v122, v122
	v_fmac_f32_e32 v189, v114, v114
	v_fmac_f32_e32 v156, v123, v123
	v_fmac_f32_e32 v189, v115, v115
	v_fmac_f32_e32 v156, v124, v124
	v_fmac_f32_e32 v189, v116, v116
	v_fmac_f32_e32 v156, v125, v125
	v_fmac_f32_e32 v189, v117, v117
	v_fmac_f32_e32 v156, v126, v126
	v_fmac_f32_e32 v189, v118, v118
	v_fmac_f32_e32 v156, v127, v127
	v_fmac_f32_e32 v189, v119, v119
	v_add_f32_e32 v156, v156, v189
	s_waitcnt vmcnt(12)
	v_lshlrev_b32_e32 v190, 16, v202
	v_and_b32_e32 v191, s63, v202
	v_pk_add_f32 v[108:109], v[108:109], v[190:191]
	v_lshlrev_b32_e32 v136, 16, v203
	v_and_b32_e32 v137, s63, v203
	v_pk_add_f32 v[110:111], v[110:111], v[136:137]
	v_lshlrev_b32_e32 v138, 16, v204
	v_and_b32_e32 v139, s63, v204
	v_pk_add_f32 v[104:105], v[104:105], v[138:139]
	v_lshlrev_b32_e32 v190, 16, v205
	v_and_b32_e32 v191, s63, v205
	v_pk_add_f32 v[106:107], v[106:107], v[190:191]
	v_lshlrev_b32_e32 v136, 16, v206
	v_and_b32_e32 v137, s63, v206
	v_pk_add_f32 v[100:101], v[100:101], v[136:137]
	v_lshlrev_b32_e32 v138, 16, v207
	v_and_b32_e32 v139, s63, v207
	v_pk_add_f32 v[102:103], v[102:103], v[138:139]
	v_lshlrev_b32_e32 v190, 16, v208
	v_and_b32_e32 v191, s63, v208
	v_pk_add_f32 v[96:97], v[96:97], v[190:191]
	v_lshlrev_b32_e32 v136, 16, v209
	v_and_b32_e32 v137, s63, v209
	v_pk_add_f32 v[98:99], v[98:99], v[136:137]
	v_mul_f32_e32 v157, v104, v104
	v_mul_f32_e32 v189, v96, v96
	v_fmac_f32_e32 v157, v105, v105
	v_fmac_f32_e32 v189, v97, v97
	v_fmac_f32_e32 v157, v106, v106
	v_fmac_f32_e32 v189, v98, v98
	v_fmac_f32_e32 v157, v107, v107
	v_fmac_f32_e32 v189, v99, v99
	v_fmac_f32_e32 v157, v108, v108
	v_fmac_f32_e32 v189, v100, v100
	v_fmac_f32_e32 v157, v109, v109
	v_fmac_f32_e32 v189, v101, v101
	v_fmac_f32_e32 v157, v110, v110
	v_fmac_f32_e32 v189, v102, v102
	v_fmac_f32_e32 v157, v111, v111
	v_fmac_f32_e32 v189, v103, v103
	v_add_f32_e32 v157, v157, v189
	s_waitcnt vmcnt(10)
	v_lshlrev_b32_e32 v138, 16, v210
	v_and_b32_e32 v139, s63, v210
	v_pk_add_f32 v[92:93], v[92:93], v[138:139]
	v_lshlrev_b32_e32 v190, 16, v211
	v_and_b32_e32 v191, s63, v211
	v_pk_add_f32 v[94:95], v[94:95], v[190:191]
	v_lshlrev_b32_e32 v136, 16, v212
	v_and_b32_e32 v137, s63, v212
	v_pk_add_f32 v[88:89], v[88:89], v[136:137]
	v_lshlrev_b32_e32 v138, 16, v213
	v_and_b32_e32 v139, s63, v213
	v_pk_add_f32 v[90:91], v[90:91], v[138:139]
	v_lshlrev_b32_e32 v190, 16, v214
	v_and_b32_e32 v191, s63, v214
	v_pk_add_f32 v[84:85], v[84:85], v[190:191]
	v_lshlrev_b32_e32 v136, 16, v215
	v_and_b32_e32 v137, s63, v215
	v_pk_add_f32 v[86:87], v[86:87], v[136:137]
	v_lshlrev_b32_e32 v138, 16, v216
	v_and_b32_e32 v139, s63, v216
	v_pk_add_f32 v[80:81], v[80:81], v[138:139]
	v_lshlrev_b32_e32 v190, 16, v217
	v_and_b32_e32 v191, s63, v217
	v_pk_add_f32 v[82:83], v[82:83], v[190:191]
	v_mul_f32_e32 v158, v88, v88
	v_mul_f32_e32 v189, v80, v80
	v_fmac_f32_e32 v158, v89, v89
	v_fmac_f32_e32 v189, v81, v81
	v_fmac_f32_e32 v158, v90, v90
	v_fmac_f32_e32 v189, v82, v82
	v_fmac_f32_e32 v158, v91, v91
	v_fmac_f32_e32 v189, v83, v83
	v_fmac_f32_e32 v158, v92, v92
	v_fmac_f32_e32 v189, v84, v84
	v_fmac_f32_e32 v158, v93, v93
	v_fmac_f32_e32 v189, v85, v85
	v_fmac_f32_e32 v158, v94, v94
	v_fmac_f32_e32 v189, v86, v86
	v_fmac_f32_e32 v158, v95, v95
	v_fmac_f32_e32 v189, v87, v87
	v_add_f32_e32 v158, v158, v189
	s_waitcnt vmcnt(8)
	v_lshlrev_b32_e32 v136, 16, v218
	v_and_b32_e32 v137, s63, v218
	v_pk_add_f32 v[76:77], v[76:77], v[136:137]
	v_lshlrev_b32_e32 v138, 16, v219
	v_and_b32_e32 v139, s63, v219
	v_pk_add_f32 v[78:79], v[78:79], v[138:139]
	v_lshlrev_b32_e32 v190, 16, v220
	v_and_b32_e32 v191, s63, v220
	v_pk_add_f32 v[72:73], v[72:73], v[190:191]
	v_lshlrev_b32_e32 v136, 16, v221
	v_and_b32_e32 v137, s63, v221
	v_pk_add_f32 v[74:75], v[74:75], v[136:137]
	v_lshlrev_b32_e32 v138, 16, v222
	v_and_b32_e32 v139, s63, v222
	v_pk_add_f32 v[68:69], v[68:69], v[138:139]
	v_lshlrev_b32_e32 v190, 16, v223
	v_and_b32_e32 v191, s63, v223
	v_pk_add_f32 v[70:71], v[70:71], v[190:191]
	v_lshlrev_b32_e32 v136, 16, v224
	v_and_b32_e32 v137, s63, v224
	v_pk_add_f32 v[64:65], v[64:65], v[136:137]
	v_lshlrev_b32_e32 v138, 16, v225
	v_and_b32_e32 v139, s63, v225
	v_pk_add_f32 v[66:67], v[66:67], v[138:139]
	v_mul_f32_e32 v159, v72, v72
	v_mul_f32_e32 v189, v64, v64
	v_fmac_f32_e32 v159, v73, v73
	v_fmac_f32_e32 v189, v65, v65
	v_fmac_f32_e32 v159, v74, v74
	v_fmac_f32_e32 v189, v66, v66
	v_fmac_f32_e32 v159, v75, v75
	v_fmac_f32_e32 v189, v67, v67
	v_fmac_f32_e32 v159, v76, v76
	v_fmac_f32_e32 v189, v68, v68
	v_fmac_f32_e32 v159, v77, v77
	v_fmac_f32_e32 v189, v69, v69
	v_fmac_f32_e32 v159, v78, v78
	v_fmac_f32_e32 v189, v70, v70
	v_fmac_f32_e32 v159, v79, v79
	v_fmac_f32_e32 v189, v71, v71
	v_add_f32_e32 v159, v159, v189
	s_waitcnt vmcnt(6)
	v_lshlrev_b32_e32 v190, 16, v226
	v_and_b32_e32 v191, s63, v226
	v_pk_add_f32 v[60:61], v[60:61], v[190:191]
	v_lshlrev_b32_e32 v136, 16, v227
	v_and_b32_e32 v137, s63, v227
	v_pk_add_f32 v[62:63], v[62:63], v[136:137]
	v_lshlrev_b32_e32 v138, 16, v228
	v_and_b32_e32 v139, s63, v228
	v_pk_add_f32 v[56:57], v[56:57], v[138:139]
	v_lshlrev_b32_e32 v190, 16, v229
	v_and_b32_e32 v191, s63, v229
	v_pk_add_f32 v[58:59], v[58:59], v[190:191]
	v_lshlrev_b32_e32 v136, 16, v230
	v_and_b32_e32 v137, s63, v230
	v_pk_add_f32 v[52:53], v[52:53], v[136:137]
	v_lshlrev_b32_e32 v138, 16, v231
	v_and_b32_e32 v139, s63, v231
	v_pk_add_f32 v[54:55], v[54:55], v[138:139]
	v_lshlrev_b32_e32 v190, 16, v232
	v_and_b32_e32 v191, s63, v232
	v_pk_add_f32 v[48:49], v[48:49], v[190:191]
	v_lshlrev_b32_e32 v136, 16, v233
	v_and_b32_e32 v137, s63, v233
	v_pk_add_f32 v[50:51], v[50:51], v[136:137]
	v_mul_f32_e32 v160, v56, v56
	v_mul_f32_e32 v189, v48, v48
	v_fmac_f32_e32 v160, v57, v57
	v_fmac_f32_e32 v189, v49, v49
	v_fmac_f32_e32 v160, v58, v58
	v_fmac_f32_e32 v189, v50, v50
	v_fmac_f32_e32 v160, v59, v59
	v_fmac_f32_e32 v189, v51, v51
	v_fmac_f32_e32 v160, v60, v60
	v_fmac_f32_e32 v189, v52, v52
	v_fmac_f32_e32 v160, v61, v61
	v_fmac_f32_e32 v189, v53, v53
	v_fmac_f32_e32 v160, v62, v62
	v_fmac_f32_e32 v189, v54, v54
	v_fmac_f32_e32 v160, v63, v63
	v_fmac_f32_e32 v189, v55, v55
	v_add_f32_e32 v160, v160, v189
	s_waitcnt vmcnt(4)
	v_lshlrev_b32_e32 v138, 16, v234
	v_and_b32_e32 v139, s63, v234
	v_pk_add_f32 v[44:45], v[44:45], v[138:139]
	v_lshlrev_b32_e32 v190, 16, v235
	v_and_b32_e32 v191, s63, v235
	v_pk_add_f32 v[46:47], v[46:47], v[190:191]
	v_lshlrev_b32_e32 v136, 16, v236
	v_and_b32_e32 v137, s63, v236
	v_pk_add_f32 v[40:41], v[40:41], v[136:137]
	v_lshlrev_b32_e32 v138, 16, v237
	v_and_b32_e32 v139, s63, v237
	v_pk_add_f32 v[42:43], v[42:43], v[138:139]
	v_lshlrev_b32_e32 v190, 16, v238
	v_and_b32_e32 v191, s63, v238
	v_pk_add_f32 v[36:37], v[36:37], v[190:191]
	v_lshlrev_b32_e32 v136, 16, v239
	v_and_b32_e32 v137, s63, v239
	v_pk_add_f32 v[38:39], v[38:39], v[136:137]
	v_lshlrev_b32_e32 v138, 16, v240
	v_and_b32_e32 v139, s63, v240
	v_pk_add_f32 v[32:33], v[32:33], v[138:139]
	v_lshlrev_b32_e32 v190, 16, v241
	v_and_b32_e32 v191, s63, v241
	v_pk_add_f32 v[34:35], v[34:35], v[190:191]
	v_mul_f32_e32 v161, v40, v40
	v_mul_f32_e32 v189, v32, v32
	v_fmac_f32_e32 v161, v41, v41
	v_fmac_f32_e32 v189, v33, v33
	v_fmac_f32_e32 v161, v42, v42
	v_fmac_f32_e32 v189, v34, v34
	v_fmac_f32_e32 v161, v43, v43
	v_fmac_f32_e32 v189, v35, v35
	v_fmac_f32_e32 v161, v44, v44
	v_fmac_f32_e32 v189, v36, v36
	v_fmac_f32_e32 v161, v45, v45
	v_fmac_f32_e32 v189, v37, v37
	v_fmac_f32_e32 v161, v46, v46
	v_fmac_f32_e32 v189, v38, v38
	v_fmac_f32_e32 v161, v47, v47
	v_fmac_f32_e32 v189, v39, v39
	v_add_f32_e32 v161, v161, v189
	s_waitcnt vmcnt(2)
	v_lshlrev_b32_e32 v136, 16, v172
	v_and_b32_e32 v137, s63, v172
	v_pk_add_f32 v[28:29], v[28:29], v[136:137]
	v_lshlrev_b32_e32 v138, 16, v173
	v_and_b32_e32 v139, s63, v173
	v_pk_add_f32 v[30:31], v[30:31], v[138:139]
	v_lshlrev_b32_e32 v190, 16, v174
	v_and_b32_e32 v191, s63, v174
	v_pk_add_f32 v[24:25], v[24:25], v[190:191]
	v_lshlrev_b32_e32 v136, 16, v175
	v_and_b32_e32 v137, s63, v175
	v_pk_add_f32 v[26:27], v[26:27], v[136:137]
	v_lshlrev_b32_e32 v138, 16, v176
	v_and_b32_e32 v139, s63, v176
	v_pk_add_f32 v[20:21], v[20:21], v[138:139]
	v_lshlrev_b32_e32 v190, 16, v177
	v_and_b32_e32 v191, s63, v177
	v_pk_add_f32 v[22:23], v[22:23], v[190:191]
	v_lshlrev_b32_e32 v136, 16, v178
	v_and_b32_e32 v137, s63, v178
	v_pk_add_f32 v[16:17], v[16:17], v[136:137]
	v_lshlrev_b32_e32 v138, 16, v179
	v_and_b32_e32 v139, s63, v179
	v_pk_add_f32 v[18:19], v[18:19], v[138:139]
	v_mul_f32_e32 v162, v24, v24
	v_mul_f32_e32 v189, v16, v16
	v_fmac_f32_e32 v162, v25, v25
	v_fmac_f32_e32 v189, v17, v17
	v_fmac_f32_e32 v162, v26, v26
	v_fmac_f32_e32 v189, v18, v18
	v_fmac_f32_e32 v162, v27, v27
	v_fmac_f32_e32 v189, v19, v19
	v_fmac_f32_e32 v162, v28, v28
	v_fmac_f32_e32 v189, v20, v20
	v_fmac_f32_e32 v162, v29, v29
	v_fmac_f32_e32 v189, v21, v21
	v_fmac_f32_e32 v162, v30, v30
	v_fmac_f32_e32 v189, v22, v22
	v_fmac_f32_e32 v162, v31, v31
	v_fmac_f32_e32 v189, v23, v23
	v_add_f32_e32 v162, v162, v189
	s_waitcnt vmcnt(0)
	v_lshlrev_b32_e32 v190, 16, v180
	v_and_b32_e32 v191, s63, v180
	v_pk_add_f32 v[12:13], v[12:13], v[190:191]
	v_lshlrev_b32_e32 v136, 16, v181
	v_and_b32_e32 v137, s63, v181
	v_pk_add_f32 v[14:15], v[14:15], v[136:137]
	v_lshlrev_b32_e32 v138, 16, v182
	v_and_b32_e32 v139, s63, v182
	v_pk_add_f32 v[8:9], v[8:9], v[138:139]
	v_lshlrev_b32_e32 v190, 16, v183
	v_and_b32_e32 v191, s63, v183
	v_pk_add_f32 v[10:11], v[10:11], v[190:191]
	v_lshlrev_b32_e32 v136, 16, v184
	v_and_b32_e32 v137, s63, v184
	v_pk_add_f32 v[4:5], v[4:5], v[136:137]
	v_lshlrev_b32_e32 v138, 16, v185
	v_and_b32_e32 v139, s63, v185
	v_pk_add_f32 v[6:7], v[6:7], v[138:139]
	v_lshlrev_b32_e32 v190, 16, v186
	v_and_b32_e32 v191, s63, v186
	v_pk_add_f32 v[0:1], v[0:1], v[190:191]
	v_lshlrev_b32_e32 v136, 16, v187
	v_and_b32_e32 v137, s63, v187
	v_pk_add_f32 v[2:3], v[2:3], v[136:137]
	v_mul_f32_e32 v163, v8, v8
	v_mul_f32_e32 v189, v0, v0
	v_fmac_f32_e32 v163, v9, v9
	v_fmac_f32_e32 v189, v1, v1
	v_fmac_f32_e32 v163, v10, v10
	v_fmac_f32_e32 v189, v2, v2
	v_fmac_f32_e32 v163, v11, v11
	v_fmac_f32_e32 v189, v3, v3
	v_fmac_f32_e32 v163, v12, v12
	v_fmac_f32_e32 v189, v4, v4
	v_fmac_f32_e32 v163, v13, v13
	v_fmac_f32_e32 v189, v5, v5
	v_fmac_f32_e32 v163, v14, v14
	v_fmac_f32_e32 v189, v6, v6
	v_fmac_f32_e32 v163, v15, v15
	v_fmac_f32_e32 v189, v7, v7
	v_add_f32_e32 v163, v163, v189
	ds_bpermute_b32 v136, v134, v156
	ds_bpermute_b32 v137, v134, v157
	ds_bpermute_b32 v138, v134, v158
	ds_bpermute_b32 v139, v134, v159
	ds_bpermute_b32 v188, v134, v160
	ds_bpermute_b32 v189, v134, v161
	ds_bpermute_b32 v190, v134, v162
	ds_bpermute_b32 v191, v134, v163
	s_waitcnt lgkmcnt(0)
	v_add_f32_e32 v156, v156, v136
	v_add_f32_e32 v157, v157, v137
	v_add_f32_e32 v158, v158, v138
	v_add_f32_e32 v159, v159, v139
	v_add_f32_e32 v160, v160, v188
	v_add_f32_e32 v161, v161, v189
	v_add_f32_e32 v162, v162, v190
	v_add_f32_e32 v163, v163, v191
	ds_bpermute_b32 v136, v135, v156
	ds_bpermute_b32 v137, v135, v157
	ds_bpermute_b32 v138, v135, v158
	ds_bpermute_b32 v139, v135, v159
	ds_bpermute_b32 v188, v135, v160
	ds_bpermute_b32 v189, v135, v161
	ds_bpermute_b32 v190, v135, v162
	ds_bpermute_b32 v191, v135, v163
	s_waitcnt lgkmcnt(0)
	v_add_f32_e32 v156, v156, v136
	v_add_f32_e32 v157, v157, v137
	v_add_f32_e32 v158, v158, v138
	v_add_f32_e32 v159, v159, v139
	v_add_f32_e32 v160, v160, v188
	v_add_f32_e32 v161, v161, v189
	v_add_f32_e32 v162, v162, v190
	v_add_f32_e32 v163, v163, v191
	s_and_saveexec_b64 s[66:67], s[64:65]
	global_store_dword v130, v156, s[8:9] sc1
	global_store_dword v130, v157, s[8:9] offset:1024 sc1
	global_store_dword v130, v158, s[8:9] offset:2048 sc1
	global_store_dword v130, v159, s[8:9] offset:3072 sc1
	global_store_dword v130, v160, s[74:75] sc1
	global_store_dword v130, v161, s[74:75] offset:1024 sc1
	global_store_dword v130, v162, s[74:75] offset:2048 sc1
	global_store_dword v130, v163, s[74:75] offset:3072 sc1
	s_or_b64 exec, exec, s[66:67]
	global_load_dwordx4 v[210:213], v132, s[22:23]
	global_load_dwordx4 v[214:217], v132, s[22:23] offset:16
	global_load_dwordx4 v[218:221], v132, s[22:23] offset:128
	global_load_dwordx4 v[222:225], v132, s[22:23] offset:144
	s_waitcnt vmcnt(0)
	s_barrier
	s_barrier
	s_cmpk_gt_u32 s17, 0xff
	s_cbranch_scc1 .Lf11_w1_a
	s_and_saveexec_b64 s[40:41], s[14:15]
	s_cbranch_execz .Lf11_t0_done
	v_mov_b32_e32 v133, 0
	v_mov_b32_e32 v189, 1
	global_atomic_add v133, v189, s[78:79]
	s_mov_b32 s80, 0
